# instruction selection: bf16 packing of the xn stores in the generated EpiResid epilogues done with v_cvt_pk_bf16_f32 (RNE) instead of add 0x8000 + v_perm (on top of v22)
# speedup vs baseline: 1.0120x; 1.0120x over previous
;     __device__ __forceinline__ void operator()(const f32x4 (&acc)[2][2][4][2], const Unit& u, int wr, int wc, int fr, int fq) const {
;         const int row0 = u.pm * BM + wr * 64 + fr, col0 = u.pn * BM + wc * 32 + 4 * fq;
;         const float* rbase = (u.pm * BM < SEQ_P) ? resA : (resB - (size_t)SEQ_P * ldc);
;         f32x4 wv[2][2];
;         if (xn) {
; #pragma unroll
;             for (int bj = 0; bj < 2; ++bj)
; #pragma unroll
;                 for (int n = 0; n < 2; ++n) wv[bj][n] = *(const f32x4*)(wn + col0 + bj * HALF + n * 16);
;         }
; #pragma unroll
;         for (int ai = 0; ai < 2; ++ai)
; #pragma unroll
;             for (int m = 0; m < 4; ++m) {
;                 const int row = row0 + ai * HALF + m * 16;
;                 const size_t off = (size_t)row * ldc + col0;
;                 float q = 0.f;
; #pragma unroll
;                 for (int bj = 0; bj < 2; ++bj)
; #pragma unroll
;                     for (int n = 0; n < 2; ++n) {
;                         const f32x4 rv = *(const f32x4*)(rbase + off + bj * HALF + n * 16);
;                         const f32x4 v = rv + acc[ai][bj][m][n] * scale;
;                         if (out) *(f32x4*)(out + off + bj * HALF + n * 16) = v;
;                         if (xn) { q += (v.x * v.x + v.y * v.y) + (v.z * v.z + v.w * v.w); const f32x4 o = v * wv[bj][n];
;                             u32x2 p; p.x = pk2(o.x, o.y); p.y = pk2(o.z, o.w); *(u32x2*)(xn + off + bj * HALF + n * 16) = p; }
.LBB0_312:
	v_lshl_add_u32 v212, s62, 8, v168
	v_lshl_or_b32 v214, s61, 8, v170
	v_and_b32_e32 v243, 8, v174
	v_mov_b32_e32 v213, 0
	v_cmp_eq_u32_e64 s[34:35], 0, v243
	v_lshlrev_b32_e32 v175, 1, v243
	v_add_u32_e32 v216, v214, v175
	v_sub_u32_e32 v234, 16, v175
	v_add_u32_e32 v234, v214, v234
	v_mov_b32_e32 v214, v216
	v_mov_b32_e32 v216, v234
	v_mov_b32_e32 v215, 0
	v_mov_b32_e32 v217, 0
	v_sub_u32_e32 v210, v212, v243
	v_mov_b32_e32 v211, 0
	v_lshlrev_b64 v[208:209], 11, v[210:211]
	v_add_u32_e32 v210, 8, v210
	v_lshlrev_b64 v[210:211], 11, v[210:211]
	s_cmp_lt_i32 s62, 32
	s_cselect_b32 s31, s2, s54
	s_cselect_b32 s30, s33, s53
	v_lshl_add_u64 v[208:209], v[208:209], 0, v[214:215]
	v_lshl_add_u64 v[210:211], v[210:211], 0, v[216:217]
	v_lshl_add_u64 v[164:165], v[208:209], 2, s[30:31]
	v_lshl_add_u64 v[200:201], v[210:211], 2, s[30:31]
	v_lshl_add_u64 v[202:203], v[214:215], 2, s[10:11]
	v_lshl_add_u64 v[204:205], v[216:217], 2, s[10:11]
	global_load_dwordx4 v[64:67], v[202:203], off
	global_load_dwordx4 v[72:75], v[202:203], off offset:512
	global_load_dwordx4 v[80:83], v[204:205], off
	global_load_dwordx4 v[84:87], v[204:205], off offset:512
	global_load_dwordx4 v[156:159], v[164:165], off
	global_load_dwordx4 v[160:163], v[164:165], off offset:512
	global_load_dwordx4 v[176:179], v[200:201], off
	global_load_dwordx4 v[180:183], v[200:201], off offset:512
	s_mov_b64 vcc, 0x20000
	v_lshl_add_u64 v[164:165], v[164:165], 0, vcc
	v_lshl_add_u64 v[200:201], v[200:201], 0, vcc
	global_load_dwordx4 v[184:187], v[164:165], off
	global_load_dwordx4 v[188:191], v[164:165], off offset:512
	global_load_dwordx4 v[192:195], v[200:201], off
	global_load_dwordx4 v[196:199], v[200:201], off offset:512
	s_mov_b64 vcc, 0x20000
	v_lshl_add_u64 v[164:165], v[164:165], 0, vcc
	v_lshl_add_u64 v[200:201], v[200:201], 0, vcc
	v_lshl_add_u64 v[218:219], v[208:209], 2, s[8:9]
	v_lshl_add_u64 v[220:221], v[210:211], 2, s[8:9]
	v_lshl_add_u64 v[202:203], v[208:209], 1, s[14:15]
	v_lshl_add_u64 v[204:205], v[210:211], 1, s[14:15]
	v_lshl_add_u64 v[206:207], v[212:213], 2, s[18:19]
	v_xor_b32_e32 v235, 16, v174
	v_xor_b32_e32 v240, 32, v174
	v_lshlrev_b32_e32 v235, 2, v235
	v_lshlrev_b32_e32 v240, 2, v240
	v_mov_b32_dpp v236, v136 row_ror:8 row_mask:0xf bank_mask:0xf
	v_mov_b32_dpp v237, v137 row_ror:8 row_mask:0xf bank_mask:0xf
	v_mov_b32_dpp v238, v138 row_ror:8 row_mask:0xf bank_mask:0xf
	v_mov_b32_dpp v239, v139 row_ror:8 row_mask:0xf bank_mask:0xf
	v_cndmask_b32_e64 v136, v236, v140, s[34:35]
	v_cndmask_b32_e64 v137, v237, v141, s[34:35]
	v_cndmask_b32_e64 v138, v238, v142, s[34:35]
	v_cndmask_b32_e64 v139, v239, v143, s[34:35]
	v_cndmask_b32_e64 v140, v140, v236, s[34:35]
	v_cndmask_b32_e64 v141, v141, v237, s[34:35]
	v_cndmask_b32_e64 v142, v142, v238, s[34:35]
	v_cndmask_b32_e64 v143, v143, v239, s[34:35]
	v_mov_b32_dpp v236, v128 row_ror:8 row_mask:0xf bank_mask:0xf
	v_mov_b32_dpp v237, v129 row_ror:8 row_mask:0xf bank_mask:0xf
	v_mov_b32_dpp v238, v130 row_ror:8 row_mask:0xf bank_mask:0xf
	v_mov_b32_dpp v239, v131 row_ror:8 row_mask:0xf bank_mask:0xf
	v_cndmask_b32_e64 v128, v236, v132, s[34:35]
	v_cndmask_b32_e64 v129, v237, v133, s[34:35]
	v_cndmask_b32_e64 v130, v238, v134, s[34:35]
	v_cndmask_b32_e64 v131, v239, v135, s[34:35]
	v_cndmask_b32_e64 v132, v132, v236, s[34:35]
	v_cndmask_b32_e64 v133, v133, v237, s[34:35]
	v_cndmask_b32_e64 v134, v134, v238, s[34:35]
	v_cndmask_b32_e64 v135, v135, v239, s[34:35]
	s_waitcnt vmcnt(4)
	v_pk_fma_f32 v[138:139], v[138:139], 0.5, v[158:159] op_sel_hi:[1,0,1]
	v_pk_fma_f32 v[136:137], v[136:137], 0.5, v[156:157] op_sel_hi:[1,0,1]
	global_store_dwordx4 v[218:219], v[136:139], off
	v_pk_mul_f32 v[224:225], v[64:65], v[136:137]
	v_pk_mul_f32 v[226:227], v[66:67], v[138:139]
	v_mul_f32_e32 v175, v136, v136
	v_fmac_f32_e32 v175, v137, v137
	v_fmac_f32_e32 v175, v138, v138
	v_fmac_f32_e32 v175, v139, v139
	v_cvt_pk_bf16_f32 v222, v224, v225
	v_cvt_pk_bf16_f32 v223, v226, v227
	global_store_dwordx2 v[202:203], v[222:223], off
	v_pk_fma_f32 v[130:131], v[130:131], 0.5, v[162:163] op_sel_hi:[1,0,1]
	v_pk_fma_f32 v[128:129], v[128:129], 0.5, v[160:161] op_sel_hi:[1,0,1]
	global_store_dwordx4 v[218:219], v[128:131], off offset:512
	v_pk_mul_f32 v[228:229], v[72:73], v[128:129]
	v_pk_mul_f32 v[230:231], v[74:75], v[130:131]
	v_fmac_f32_e32 v175, v128, v128
	v_fmac_f32_e32 v175, v129, v129
	v_fmac_f32_e32 v175, v130, v130
	v_fmac_f32_e32 v175, v131, v131
	v_cvt_pk_bf16_f32 v232, v228, v229
	v_cvt_pk_bf16_f32 v233, v230, v231
	global_store_dwordx2 v[202:203], v[232:233], off offset:256
	v_pk_fma_f32 v[142:143], v[142:143], 0.5, v[178:179] op_sel_hi:[1,0,1]
	v_pk_fma_f32 v[140:141], v[140:141], 0.5, v[176:177] op_sel_hi:[1,0,1]
	global_store_dwordx4 v[220:221], v[140:143], off
	v_pk_mul_f32 v[224:225], v[80:81], v[140:141]
	v_pk_mul_f32 v[226:227], v[82:83], v[142:143]
	v_mul_f32_e32 v234, v140, v140
	v_fmac_f32_e32 v234, v141, v141
	v_fmac_f32_e32 v234, v142, v142
	v_fmac_f32_e32 v234, v143, v143
	v_cvt_pk_bf16_f32 v222, v224, v225
	v_cvt_pk_bf16_f32 v223, v226, v227
	global_store_dwordx2 v[204:205], v[222:223], off
	v_pk_fma_f32 v[134:135], v[134:135], 0.5, v[182:183] op_sel_hi:[1,0,1]
	v_pk_fma_f32 v[132:133], v[132:133], 0.5, v[180:181] op_sel_hi:[1,0,1]
	global_store_dwordx4 v[220:221], v[132:135], off offset:512
	v_pk_mul_f32 v[228:229], v[84:85], v[132:133]
	v_pk_mul_f32 v[230:231], v[86:87], v[134:135]
	v_fmac_f32_e32 v234, v132, v132
	v_fmac_f32_e32 v234, v133, v133
	v_fmac_f32_e32 v234, v134, v134
	v_fmac_f32_e32 v234, v135, v135
	v_cvt_pk_bf16_f32 v232, v228, v229
	v_cvt_pk_bf16_f32 v233, v230, v231
	global_store_dwordx2 v[204:205], v[232:233], off offset:256
	s_nop 1
	v_mov_b32_dpp v241, v175 row_ror:8 row_mask:0xf bank_mask:0xf
	v_mov_b32_dpp v242, v234 row_ror:8 row_mask:0xf bank_mask:0xf
	v_add_f32_e32 v175, v175, v241
	v_add_f32_e32 v234, v234, v242
	v_cndmask_b32_e64 v175, v234, v175, s[34:35]
	s_nop 0
	ds_bpermute_b32 v241, v235, v175
	global_load_dwordx4 v[156:159], v[164:165], off
	global_load_dwordx4 v[160:163], v[164:165], off offset:512
	global_load_dwordx4 v[176:179], v[200:201], off
	global_load_dwordx4 v[180:183], v[200:201], off offset:512
	s_mov_b64 vcc, 0x20000
	v_lshl_add_u64 v[164:165], v[164:165], 0, vcc
	v_lshl_add_u64 v[200:201], v[200:201], 0, vcc
	s_mov_b64 vcc, 0x20000
	v_lshl_add_u64 v[218:219], v[218:219], 0, vcc
	v_lshl_add_u64 v[220:221], v[220:221], 0, vcc
	s_mov_b64 vcc, 0x10000
	v_lshl_add_u64 v[202:203], v[202:203], 0, vcc
	v_lshl_add_u64 v[204:205], v[204:205], 0, vcc
	s_waitcnt lgkmcnt(0)
;     __device__ __forceinline__ void operator()(const f32x4 (&acc)[2][2][4][2], const Unit& u, int wr, int wc, int fr, int fq) const {
;     ...
;                 for (int bj = 0; bj < 2; ++bj)
; #pragma unroll
;                     for (int n = 0; n < 2; ++n) {
;                         const f32x4 rv = *(const f32x4*)(rbase + off + bj * HALF + n * 16);
;                         const f32x4 v = rv + acc[ai][bj][m][n] * scale;
;                         if (out) *(f32x4*)(out + off + bj * HALF + n * 16) = v;
;                         if (xn) { q += (v.x * v.x + v.y * v.y) + (v.z * v.z + v.w * v.w); const f32x4 o = v * wv[bj][n];
;                             u32x2 p; p.x = pk2(o.x, o.y); p.y = pk2(o.z, o.w); *(u32x2*)(xn + off + bj * HALF + n * 16) = p; }
;                     }
;                 if (xn) { q += __shfl_xor(q, 16); q += __shfl_xor(q, 32); if (fq == 0) (void)__hip_atomic_fetch_add(ss + row, q, __ATOMIC_RELAXED, __HIP_MEMORY_SCOPE_AGENT); }
	v_add_f32_e32 v175, v175, v241
	s_nop 0
	ds_bpermute_b32 v242, v240, v175
	s_waitcnt lgkmcnt(0)
	v_add_f32_e32 v175, v175, v242
	s_mov_b64 exec, s[0:1]
	global_atomic_add_f32 v[206:207], v175, off
	s_mov_b64 exec, -1
	s_mov_b64 vcc, 64
	v_lshl_add_u64 v[206:207], v[206:207], 0, vcc
	v_mov_b32_dpp v236, v120 row_ror:8 row_mask:0xf bank_mask:0xf
	v_mov_b32_dpp v237, v121 row_ror:8 row_mask:0xf bank_mask:0xf
	v_mov_b32_dpp v238, v122 row_ror:8 row_mask:0xf bank_mask:0xf
	v_mov_b32_dpp v239, v123 row_ror:8 row_mask:0xf bank_mask:0xf
	v_cndmask_b32_e64 v120, v236, v124, s[34:35]
	v_cndmask_b32_e64 v121, v237, v125, s[34:35]
	v_cndmask_b32_e64 v122, v238, v126, s[34:35]
	v_cndmask_b32_e64 v123, v239, v127, s[34:35]
	v_cndmask_b32_e64 v124, v124, v236, s[34:35]
	v_cndmask_b32_e64 v125, v125, v237, s[34:35]
	v_cndmask_b32_e64 v126, v126, v238, s[34:35]
	v_cndmask_b32_e64 v127, v127, v239, s[34:35]
	v_mov_b32_dpp v236, v112 row_ror:8 row_mask:0xf bank_mask:0xf
	v_mov_b32_dpp v237, v113 row_ror:8 row_mask:0xf bank_mask:0xf
	v_mov_b32_dpp v238, v114 row_ror:8 row_mask:0xf bank_mask:0xf
	v_mov_b32_dpp v239, v115 row_ror:8 row_mask:0xf bank_mask:0xf
	v_cndmask_b32_e64 v112, v236, v116, s[34:35]
	v_cndmask_b32_e64 v113, v237, v117, s[34:35]
	v_cndmask_b32_e64 v114, v238, v118, s[34:35]
	v_cndmask_b32_e64 v115, v239, v119, s[34:35]
	v_cndmask_b32_e64 v116, v116, v236, s[34:35]
	v_cndmask_b32_e64 v117, v117, v237, s[34:35]
	v_cndmask_b32_e64 v118, v118, v238, s[34:35]
	v_cndmask_b32_e64 v119, v119, v239, s[34:35]
	s_waitcnt vmcnt(13)
	v_pk_fma_f32 v[122:123], v[122:123], 0.5, v[186:187] op_sel_hi:[1,0,1]
	v_pk_fma_f32 v[120:121], v[120:121], 0.5, v[184:185] op_sel_hi:[1,0,1]
	global_store_dwordx4 v[218:219], v[120:123], off
	v_pk_mul_f32 v[224:225], v[64:65], v[120:121]
	v_pk_mul_f32 v[226:227], v[66:67], v[122:123]
	v_mul_f32_e32 v175, v120, v120
	v_fmac_f32_e32 v175, v121, v121
	v_fmac_f32_e32 v175, v122, v122
	v_fmac_f32_e32 v175, v123, v123
	v_cvt_pk_bf16_f32 v222, v224, v225
	v_cvt_pk_bf16_f32 v223, v226, v227
	global_store_dwordx2 v[202:203], v[222:223], off
	v_pk_fma_f32 v[114:115], v[114:115], 0.5, v[190:191] op_sel_hi:[1,0,1]
	v_pk_fma_f32 v[112:113], v[112:113], 0.5, v[188:189] op_sel_hi:[1,0,1]
	global_store_dwordx4 v[218:219], v[112:115], off offset:512
	v_pk_mul_f32 v[228:229], v[72:73], v[112:113]
	v_pk_mul_f32 v[230:231], v[74:75], v[114:115]
	v_fmac_f32_e32 v175, v112, v112
	v_fmac_f32_e32 v175, v113, v113
	v_fmac_f32_e32 v175, v114, v114
	v_fmac_f32_e32 v175, v115, v115
	v_cvt_pk_bf16_f32 v232, v228, v229
	v_cvt_pk_bf16_f32 v233, v230, v231
	global_store_dwordx2 v[202:203], v[232:233], off offset:256
	v_pk_fma_f32 v[126:127], v[126:127], 0.5, v[194:195] op_sel_hi:[1,0,1]
	v_pk_fma_f32 v[124:125], v[124:125], 0.5, v[192:193] op_sel_hi:[1,0,1]
	global_store_dwordx4 v[220:221], v[124:127], off
	v_pk_mul_f32 v[224:225], v[80:81], v[124:125]
	v_pk_mul_f32 v[226:227], v[82:83], v[126:127]
	v_mul_f32_e32 v234, v124, v124
	v_fmac_f32_e32 v234, v125, v125
	v_fmac_f32_e32 v234, v126, v126
	v_fmac_f32_e32 v234, v127, v127
	v_cvt_pk_bf16_f32 v222, v224, v225
	v_cvt_pk_bf16_f32 v223, v226, v227
	global_store_dwordx2 v[204:205], v[222:223], off
	v_pk_fma_f32 v[118:119], v[118:119], 0.5, v[198:199] op_sel_hi:[1,0,1]
	v_pk_fma_f32 v[116:117], v[116:117], 0.5, v[196:197] op_sel_hi:[1,0,1]
	global_store_dwordx4 v[220:221], v[116:119], off offset:512
	v_pk_mul_f32 v[228:229], v[84:85], v[116:117]
	v_pk_mul_f32 v[230:231], v[86:87], v[118:119]
	v_fmac_f32_e32 v234, v116, v116
	v_fmac_f32_e32 v234, v117, v117
	v_fmac_f32_e32 v234, v118, v118
	v_fmac_f32_e32 v234, v119, v119
	v_cvt_pk_bf16_f32 v232, v228, v229
	v_cvt_pk_bf16_f32 v233, v230, v231
	global_store_dwordx2 v[204:205], v[232:233], off offset:256
	s_nop 1
	v_mov_b32_dpp v241, v175 row_ror:8 row_mask:0xf bank_mask:0xf
	v_mov_b32_dpp v242, v234 row_ror:8 row_mask:0xf bank_mask:0xf
	v_add_f32_e32 v175, v175, v241
	v_add_f32_e32 v234, v234, v242
	v_cndmask_b32_e64 v175, v234, v175, s[34:35]
	s_nop 0
	ds_bpermute_b32 v241, v235, v175
	global_load_dwordx4 v[184:187], v[164:165], off
	global_load_dwordx4 v[188:191], v[164:165], off offset:512
	global_load_dwordx4 v[192:195], v[200:201], off
	global_load_dwordx4 v[196:199], v[200:201], off offset:512
	s_mov_b64 vcc, 0xa0000
	v_lshl_add_u64 v[164:165], v[164:165], 0, vcc
	v_lshl_add_u64 v[200:201], v[200:201], 0, vcc
	s_mov_b64 vcc, 0x20000
	v_lshl_add_u64 v[218:219], v[218:219], 0, vcc
	v_lshl_add_u64 v[220:221], v[220:221], 0, vcc
	s_mov_b64 vcc, 0x10000
	v_lshl_add_u64 v[202:203], v[202:203], 0, vcc
	v_lshl_add_u64 v[204:205], v[204:205], 0, vcc
	s_waitcnt lgkmcnt(0)
	v_add_f32_e32 v175, v175, v241
	s_nop 0
	ds_bpermute_b32 v242, v240, v175
	s_waitcnt lgkmcnt(0)
	v_add_f32_e32 v175, v175, v242
	s_mov_b64 exec, s[0:1]
	global_atomic_add_f32 v[206:207], v175, off
	s_mov_b64 exec, -1
	s_mov_b64 vcc, 64
	v_lshl_add_u64 v[206:207], v[206:207], 0, vcc
	v_mov_b32_dpp v236, v104 row_ror:8 row_mask:0xf bank_mask:0xf
	v_mov_b32_dpp v237, v105 row_ror:8 row_mask:0xf bank_mask:0xf
	v_mov_b32_dpp v238, v106 row_ror:8 row_mask:0xf bank_mask:0xf
	v_mov_b32_dpp v239, v107 row_ror:8 row_mask:0xf bank_mask:0xf
	v_cndmask_b32_e64 v104, v236, v108, s[34:35]
	v_cndmask_b32_e64 v105, v237, v109, s[34:35]
	v_cndmask_b32_e64 v106, v238, v110, s[34:35]
	v_cndmask_b32_e64 v107, v239, v111, s[34:35]
	v_cndmask_b32_e64 v108, v108, v236, s[34:35]
	v_cndmask_b32_e64 v109, v109, v237, s[34:35]
	v_cndmask_b32_e64 v110, v110, v238, s[34:35]
	v_cndmask_b32_e64 v111, v111, v239, s[34:35]
	v_mov_b32_dpp v236, v96 row_ror:8 row_mask:0xf bank_mask:0xf
	v_mov_b32_dpp v237, v97 row_ror:8 row_mask:0xf bank_mask:0xf
	v_mov_b32_dpp v238, v98 row_ror:8 row_mask:0xf bank_mask:0xf
	v_mov_b32_dpp v239, v99 row_ror:8 row_mask:0xf bank_mask:0xf
	v_cndmask_b32_e64 v96, v236, v100, s[34:35]
	v_cndmask_b32_e64 v97, v237, v101, s[34:35]
	v_cndmask_b32_e64 v98, v238, v102, s[34:35]
	v_cndmask_b32_e64 v99, v239, v103, s[34:35]
	v_cndmask_b32_e64 v100, v100, v236, s[34:35]
	v_cndmask_b32_e64 v101, v101, v237, s[34:35]
	v_cndmask_b32_e64 v102, v102, v238, s[34:35]
	v_cndmask_b32_e64 v103, v103, v239, s[34:35]
	s_waitcnt vmcnt(14)
;     __device__ __forceinline__ void operator()(const f32x4 (&acc)[2][2][4][2], const Unit& u, int wr, int wc, int fr, int fq) const {
;     ...
; #pragma unroll
;         for (int ai = 0; ai < 2; ++ai)
; #pragma unroll
;             for (int m = 0; m < 4; ++m) {
;                 const int row = row0 + ai * HALF + m * 16;
;                 const size_t off = (size_t)row * ldc + col0;
;                 float q = 0.f;
; #pragma unroll
;                 for (int bj = 0; bj < 2; ++bj)
; #pragma unroll
;                     for (int n = 0; n < 2; ++n) {
;                         const f32x4 rv = *(const f32x4*)(rbase + off + bj * HALF + n * 16);
;                         const f32x4 v = rv + acc[ai][bj][m][n] * scale;
;                         if (out) *(f32x4*)(out + off + bj * HALF + n * 16) = v;
;                         if (xn) { q += (v.x * v.x + v.y * v.y) + (v.z * v.z + v.w * v.w); const f32x4 o = v * wv[bj][n];
;                             u32x2 p; p.x = pk2(o.x, o.y); p.y = pk2(o.z, o.w); *(u32x2*)(xn + off + bj * HALF + n * 16) = p; }
;                     }
;                 if (xn) { q += __shfl_xor(q, 16); q += __shfl_xor(q, 32); if (fq == 0) (void)__hip_atomic_fetch_add(ss + row, q, __ATOMIC_RELAXED, __HIP_MEMORY_SCOPE_AGENT); }
	v_pk_fma_f32 v[106:107], v[106:107], 0.5, v[158:159] op_sel_hi:[1,0,1]
	v_pk_fma_f32 v[104:105], v[104:105], 0.5, v[156:157] op_sel_hi:[1,0,1]
	global_store_dwordx4 v[218:219], v[104:107], off
	v_pk_mul_f32 v[224:225], v[64:65], v[104:105]
	v_pk_mul_f32 v[226:227], v[66:67], v[106:107]
	v_mul_f32_e32 v175, v104, v104
	v_fmac_f32_e32 v175, v105, v105
	v_fmac_f32_e32 v175, v106, v106
	v_fmac_f32_e32 v175, v107, v107
	v_cvt_pk_bf16_f32 v222, v224, v225
	v_cvt_pk_bf16_f32 v223, v226, v227
	global_store_dwordx2 v[202:203], v[222:223], off
	v_pk_fma_f32 v[98:99], v[98:99], 0.5, v[162:163] op_sel_hi:[1,0,1]
	v_pk_fma_f32 v[96:97], v[96:97], 0.5, v[160:161] op_sel_hi:[1,0,1]
	global_store_dwordx4 v[218:219], v[96:99], off offset:512
	v_pk_mul_f32 v[228:229], v[72:73], v[96:97]
	v_pk_mul_f32 v[230:231], v[74:75], v[98:99]
	v_fmac_f32_e32 v175, v96, v96
	v_fmac_f32_e32 v175, v97, v97
	v_fmac_f32_e32 v175, v98, v98
	v_fmac_f32_e32 v175, v99, v99
	v_cvt_pk_bf16_f32 v232, v228, v229
	v_cvt_pk_bf16_f32 v233, v230, v231
	global_store_dwordx2 v[202:203], v[232:233], off offset:256
	v_pk_fma_f32 v[110:111], v[110:111], 0.5, v[178:179] op_sel_hi:[1,0,1]
	v_pk_fma_f32 v[108:109], v[108:109], 0.5, v[176:177] op_sel_hi:[1,0,1]
	global_store_dwordx4 v[220:221], v[108:111], off
	v_pk_mul_f32 v[224:225], v[80:81], v[108:109]
	v_pk_mul_f32 v[226:227], v[82:83], v[110:111]
	v_mul_f32_e32 v234, v108, v108
	v_fmac_f32_e32 v234, v109, v109
	v_fmac_f32_e32 v234, v110, v110
	v_fmac_f32_e32 v234, v111, v111
	v_cvt_pk_bf16_f32 v222, v224, v225
	v_cvt_pk_bf16_f32 v223, v226, v227
	global_store_dwordx2 v[204:205], v[222:223], off
	v_pk_fma_f32 v[102:103], v[102:103], 0.5, v[182:183] op_sel_hi:[1,0,1]
	v_pk_fma_f32 v[100:101], v[100:101], 0.5, v[180:181] op_sel_hi:[1,0,1]
	global_store_dwordx4 v[220:221], v[100:103], off offset:512
	v_pk_mul_f32 v[228:229], v[84:85], v[100:101]
	v_pk_mul_f32 v[230:231], v[86:87], v[102:103]
	v_fmac_f32_e32 v234, v100, v100
	v_fmac_f32_e32 v234, v101, v101
	v_fmac_f32_e32 v234, v102, v102
	v_fmac_f32_e32 v234, v103, v103
	v_cvt_pk_bf16_f32 v232, v228, v229
	v_cvt_pk_bf16_f32 v233, v230, v231
	global_store_dwordx2 v[204:205], v[232:233], off offset:256
	s_nop 1
	v_mov_b32_dpp v241, v175 row_ror:8 row_mask:0xf bank_mask:0xf
	v_mov_b32_dpp v242, v234 row_ror:8 row_mask:0xf bank_mask:0xf
	v_add_f32_e32 v175, v175, v241
	v_add_f32_e32 v234, v234, v242
	v_cndmask_b32_e64 v175, v234, v175, s[34:35]
	s_nop 0
	ds_bpermute_b32 v241, v235, v175
	global_load_dwordx4 v[156:159], v[164:165], off
	global_load_dwordx4 v[160:163], v[164:165], off offset:512
	global_load_dwordx4 v[176:179], v[200:201], off
	global_load_dwordx4 v[180:183], v[200:201], off offset:512
	s_mov_b64 vcc, 0x20000
	v_lshl_add_u64 v[164:165], v[164:165], 0, vcc
	v_lshl_add_u64 v[200:201], v[200:201], 0, vcc
	s_mov_b64 vcc, 0x20000
	v_lshl_add_u64 v[218:219], v[218:219], 0, vcc
	v_lshl_add_u64 v[220:221], v[220:221], 0, vcc
	s_mov_b64 vcc, 0x10000
	v_lshl_add_u64 v[202:203], v[202:203], 0, vcc
	v_lshl_add_u64 v[204:205], v[204:205], 0, vcc
	s_waitcnt lgkmcnt(0)
	v_add_f32_e32 v175, v175, v241
	s_nop 0
	ds_bpermute_b32 v242, v240, v175
	s_waitcnt lgkmcnt(0)
	v_add_f32_e32 v175, v175, v242
	s_mov_b64 exec, s[0:1]
	global_atomic_add_f32 v[206:207], v175, off
	s_mov_b64 exec, -1
	s_mov_b64 vcc, 64
	v_lshl_add_u64 v[206:207], v[206:207], 0, vcc
	v_mov_b32_dpp v236, v88 row_ror:8 row_mask:0xf bank_mask:0xf
	v_mov_b32_dpp v237, v89 row_ror:8 row_mask:0xf bank_mask:0xf
	v_mov_b32_dpp v238, v90 row_ror:8 row_mask:0xf bank_mask:0xf
	v_mov_b32_dpp v239, v91 row_ror:8 row_mask:0xf bank_mask:0xf
	v_cndmask_b32_e64 v88, v236, v92, s[34:35]
	v_cndmask_b32_e64 v89, v237, v93, s[34:35]
	v_cndmask_b32_e64 v90, v238, v94, s[34:35]
	v_cndmask_b32_e64 v91, v239, v95, s[34:35]
	v_cndmask_b32_e64 v92, v92, v236, s[34:35]
	v_cndmask_b32_e64 v93, v93, v237, s[34:35]
	v_cndmask_b32_e64 v94, v94, v238, s[34:35]
	v_cndmask_b32_e64 v95, v95, v239, s[34:35]
	v_mov_b32_dpp v236, v68 row_ror:8 row_mask:0xf bank_mask:0xf
	v_mov_b32_dpp v237, v69 row_ror:8 row_mask:0xf bank_mask:0xf
	v_mov_b32_dpp v238, v70 row_ror:8 row_mask:0xf bank_mask:0xf
	v_mov_b32_dpp v239, v71 row_ror:8 row_mask:0xf bank_mask:0xf
	v_cndmask_b32_e64 v68, v236, v76, s[34:35]
	v_cndmask_b32_e64 v69, v237, v77, s[34:35]
	v_cndmask_b32_e64 v70, v238, v78, s[34:35]
	v_cndmask_b32_e64 v71, v239, v79, s[34:35]
	v_cndmask_b32_e64 v76, v76, v236, s[34:35]
	v_cndmask_b32_e64 v77, v77, v237, s[34:35]
	v_cndmask_b32_e64 v78, v78, v238, s[34:35]
	v_cndmask_b32_e64 v79, v79, v239, s[34:35]
	s_waitcnt vmcnt(14)
;     __device__ __forceinline__ void operator()(const f32x4 (&acc)[2][2][4][2], const Unit& u, int wr, int wc, int fr, int fq) const {
;     ...
; #pragma unroll
;         for (int ai = 0; ai < 2; ++ai)
; #pragma unroll
;             for (int m = 0; m < 4; ++m) {
;                 const int row = row0 + ai * HALF + m * 16;
;                 const size_t off = (size_t)row * ldc + col0;
;                 float q = 0.f;
; #pragma unroll
;                 for (int bj = 0; bj < 2; ++bj)
; #pragma unroll
;                     for (int n = 0; n < 2; ++n) {
;                         const f32x4 rv = *(const f32x4*)(rbase + off + bj * HALF + n * 16);
;                         const f32x4 v = rv + acc[ai][bj][m][n] * scale;
;                         if (out) *(f32x4*)(out + off + bj * HALF + n * 16) = v;
;                         if (xn) { q += (v.x * v.x + v.y * v.y) + (v.z * v.z + v.w * v.w); const f32x4 o = v * wv[bj][n];
;                             u32x2 p; p.x = pk2(o.x, o.y); p.y = pk2(o.z, o.w); *(u32x2*)(xn + off + bj * HALF + n * 16) = p; }
;                     }
;                 if (xn) { q += __shfl_xor(q, 16); q += __shfl_xor(q, 32); if (fq == 0) (void)__hip_atomic_fetch_add(ss + row, q, __ATOMIC_RELAXED, __HIP_MEMORY_SCOPE_AGENT); }
	v_pk_fma_f32 v[90:91], v[90:91], 0.5, v[186:187] op_sel_hi:[1,0,1]
	v_pk_fma_f32 v[88:89], v[88:89], 0.5, v[184:185] op_sel_hi:[1,0,1]
	global_store_dwordx4 v[218:219], v[88:91], off
	v_pk_mul_f32 v[224:225], v[64:65], v[88:89]
	v_pk_mul_f32 v[226:227], v[66:67], v[90:91]
	v_mul_f32_e32 v175, v88, v88
	v_fmac_f32_e32 v175, v89, v89
	v_fmac_f32_e32 v175, v90, v90
	v_fmac_f32_e32 v175, v91, v91
	v_cvt_pk_bf16_f32 v222, v224, v225
	v_cvt_pk_bf16_f32 v223, v226, v227
	global_store_dwordx2 v[202:203], v[222:223], off
	v_pk_fma_f32 v[70:71], v[70:71], 0.5, v[190:191] op_sel_hi:[1,0,1]
	v_pk_fma_f32 v[68:69], v[68:69], 0.5, v[188:189] op_sel_hi:[1,0,1]
	global_store_dwordx4 v[218:219], v[68:71], off offset:512
	v_pk_mul_f32 v[228:229], v[72:73], v[68:69]
	v_pk_mul_f32 v[230:231], v[74:75], v[70:71]
	v_fmac_f32_e32 v175, v68, v68
	v_fmac_f32_e32 v175, v69, v69
	v_fmac_f32_e32 v175, v70, v70
	v_fmac_f32_e32 v175, v71, v71
	v_cvt_pk_bf16_f32 v232, v228, v229
	v_cvt_pk_bf16_f32 v233, v230, v231
	global_store_dwordx2 v[202:203], v[232:233], off offset:256
	v_pk_fma_f32 v[94:95], v[94:95], 0.5, v[194:195] op_sel_hi:[1,0,1]
	v_pk_fma_f32 v[92:93], v[92:93], 0.5, v[192:193] op_sel_hi:[1,0,1]
	global_store_dwordx4 v[220:221], v[92:95], off
	v_pk_mul_f32 v[224:225], v[80:81], v[92:93]
	v_pk_mul_f32 v[226:227], v[82:83], v[94:95]
	v_mul_f32_e32 v234, v92, v92
	v_fmac_f32_e32 v234, v93, v93
	v_fmac_f32_e32 v234, v94, v94
	v_fmac_f32_e32 v234, v95, v95
	v_cvt_pk_bf16_f32 v222, v224, v225
	v_cvt_pk_bf16_f32 v223, v226, v227
	global_store_dwordx2 v[204:205], v[222:223], off
	v_pk_fma_f32 v[78:79], v[78:79], 0.5, v[198:199] op_sel_hi:[1,0,1]
	v_pk_fma_f32 v[76:77], v[76:77], 0.5, v[196:197] op_sel_hi:[1,0,1]
	global_store_dwordx4 v[220:221], v[76:79], off offset:512
	v_pk_mul_f32 v[228:229], v[84:85], v[76:77]
	v_pk_mul_f32 v[230:231], v[86:87], v[78:79]
	v_fmac_f32_e32 v234, v76, v76
	v_fmac_f32_e32 v234, v77, v77
	v_fmac_f32_e32 v234, v78, v78
	v_fmac_f32_e32 v234, v79, v79
	v_cvt_pk_bf16_f32 v232, v228, v229
	v_cvt_pk_bf16_f32 v233, v230, v231
	global_store_dwordx2 v[204:205], v[232:233], off offset:256
	s_nop 1
	v_mov_b32_dpp v241, v175 row_ror:8 row_mask:0xf bank_mask:0xf
	v_mov_b32_dpp v242, v234 row_ror:8 row_mask:0xf bank_mask:0xf
	v_add_f32_e32 v175, v175, v241
	v_add_f32_e32 v234, v234, v242
	v_cndmask_b32_e64 v175, v234, v175, s[34:35]
	s_nop 0
	ds_bpermute_b32 v241, v235, v175
	global_load_dwordx4 v[184:187], v[164:165], off
	global_load_dwordx4 v[188:191], v[164:165], off offset:512
	global_load_dwordx4 v[192:195], v[200:201], off
	global_load_dwordx4 v[196:199], v[200:201], off offset:512
	s_mov_b64 vcc, 0x20000
	v_lshl_add_u64 v[164:165], v[164:165], 0, vcc
	v_lshl_add_u64 v[200:201], v[200:201], 0, vcc
	s_mov_b64 vcc, 0xa0000
	v_lshl_add_u64 v[218:219], v[218:219], 0, vcc
	v_lshl_add_u64 v[220:221], v[220:221], 0, vcc
	s_mov_b64 vcc, 0x50000
	v_lshl_add_u64 v[202:203], v[202:203], 0, vcc
	v_lshl_add_u64 v[204:205], v[204:205], 0, vcc
	s_waitcnt lgkmcnt(0)
	v_add_f32_e32 v175, v175, v241
	s_nop 0
	ds_bpermute_b32 v242, v240, v175
	s_waitcnt lgkmcnt(0)
	v_add_f32_e32 v175, v175, v242
	s_mov_b64 exec, s[0:1]
	global_atomic_add_f32 v[206:207], v175, off
	s_mov_b64 exec, -1
	s_mov_b64 vcc, 320
	v_lshl_add_u64 v[206:207], v[206:207], 0, vcc
	v_mov_b32_dpp v236, v56 row_ror:8 row_mask:0xf bank_mask:0xf
	v_mov_b32_dpp v237, v57 row_ror:8 row_mask:0xf bank_mask:0xf
	v_mov_b32_dpp v238, v58 row_ror:8 row_mask:0xf bank_mask:0xf
	v_mov_b32_dpp v239, v59 row_ror:8 row_mask:0xf bank_mask:0xf
	v_cndmask_b32_e64 v56, v236, v60, s[34:35]
	v_cndmask_b32_e64 v57, v237, v61, s[34:35]
	v_cndmask_b32_e64 v58, v238, v62, s[34:35]
	v_cndmask_b32_e64 v59, v239, v63, s[34:35]
	v_cndmask_b32_e64 v60, v60, v236, s[34:35]
	v_cndmask_b32_e64 v61, v61, v237, s[34:35]
	v_cndmask_b32_e64 v62, v62, v238, s[34:35]
	v_cndmask_b32_e64 v63, v63, v239, s[34:35]
	v_mov_b32_dpp v236, v48 row_ror:8 row_mask:0xf bank_mask:0xf
	v_mov_b32_dpp v237, v49 row_ror:8 row_mask:0xf bank_mask:0xf
	v_mov_b32_dpp v238, v50 row_ror:8 row_mask:0xf bank_mask:0xf
	v_mov_b32_dpp v239, v51 row_ror:8 row_mask:0xf bank_mask:0xf
	v_cndmask_b32_e64 v48, v236, v52, s[34:35]
	v_cndmask_b32_e64 v49, v237, v53, s[34:35]
	v_cndmask_b32_e64 v50, v238, v54, s[34:35]
	v_cndmask_b32_e64 v51, v239, v55, s[34:35]
	v_cndmask_b32_e64 v52, v52, v236, s[34:35]
	v_cndmask_b32_e64 v53, v53, v237, s[34:35]
	v_cndmask_b32_e64 v54, v54, v238, s[34:35]
	v_cndmask_b32_e64 v55, v55, v239, s[34:35]
	s_waitcnt vmcnt(14)
;     __device__ __forceinline__ void operator()(const f32x4 (&acc)[2][2][4][2], const Unit& u, int wr, int wc, int fr, int fq) const {
;     ...
; #pragma unroll
;         for (int ai = 0; ai < 2; ++ai)
; #pragma unroll
;             for (int m = 0; m < 4; ++m) {
;                 const int row = row0 + ai * HALF + m * 16;
;                 const size_t off = (size_t)row * ldc + col0;
;                 float q = 0.f;
; #pragma unroll
;                 for (int bj = 0; bj < 2; ++bj)
; #pragma unroll
;                     for (int n = 0; n < 2; ++n) {
;                         const f32x4 rv = *(const f32x4*)(rbase + off + bj * HALF + n * 16);
;                         const f32x4 v = rv + acc[ai][bj][m][n] * scale;
;                         if (out) *(f32x4*)(out + off + bj * HALF + n * 16) = v;
;                         if (xn) { q += (v.x * v.x + v.y * v.y) + (v.z * v.z + v.w * v.w); const f32x4 o = v * wv[bj][n];
;                             u32x2 p; p.x = pk2(o.x, o.y); p.y = pk2(o.z, o.w); *(u32x2*)(xn + off + bj * HALF + n * 16) = p; }
;                     }
;                 if (xn) { q += __shfl_xor(q, 16); q += __shfl_xor(q, 32); if (fq == 0) (void)__hip_atomic_fetch_add(ss + row, q, __ATOMIC_RELAXED, __HIP_MEMORY_SCOPE_AGENT); }
	v_pk_fma_f32 v[58:59], v[58:59], 0.5, v[158:159] op_sel_hi:[1,0,1]
	v_pk_fma_f32 v[56:57], v[56:57], 0.5, v[156:157] op_sel_hi:[1,0,1]
	global_store_dwordx4 v[218:219], v[56:59], off
	v_pk_mul_f32 v[224:225], v[64:65], v[56:57]
	v_pk_mul_f32 v[226:227], v[66:67], v[58:59]
	v_mul_f32_e32 v175, v56, v56
	v_fmac_f32_e32 v175, v57, v57
	v_fmac_f32_e32 v175, v58, v58
	v_fmac_f32_e32 v175, v59, v59
	v_cvt_pk_bf16_f32 v222, v224, v225
	v_cvt_pk_bf16_f32 v223, v226, v227
	global_store_dwordx2 v[202:203], v[222:223], off
	v_pk_fma_f32 v[50:51], v[50:51], 0.5, v[162:163] op_sel_hi:[1,0,1]
	v_pk_fma_f32 v[48:49], v[48:49], 0.5, v[160:161] op_sel_hi:[1,0,1]
	global_store_dwordx4 v[218:219], v[48:51], off offset:512
	v_pk_mul_f32 v[228:229], v[72:73], v[48:49]
	v_pk_mul_f32 v[230:231], v[74:75], v[50:51]
	v_fmac_f32_e32 v175, v48, v48
	v_fmac_f32_e32 v175, v49, v49
	v_fmac_f32_e32 v175, v50, v50
	v_fmac_f32_e32 v175, v51, v51
	v_cvt_pk_bf16_f32 v232, v228, v229
	v_cvt_pk_bf16_f32 v233, v230, v231
	global_store_dwordx2 v[202:203], v[232:233], off offset:256
	v_pk_fma_f32 v[62:63], v[62:63], 0.5, v[178:179] op_sel_hi:[1,0,1]
	v_pk_fma_f32 v[60:61], v[60:61], 0.5, v[176:177] op_sel_hi:[1,0,1]
	global_store_dwordx4 v[220:221], v[60:63], off
	v_pk_mul_f32 v[224:225], v[80:81], v[60:61]
	v_pk_mul_f32 v[226:227], v[82:83], v[62:63]
	v_mul_f32_e32 v234, v60, v60
	v_fmac_f32_e32 v234, v61, v61
	v_fmac_f32_e32 v234, v62, v62
	v_fmac_f32_e32 v234, v63, v63
	v_cvt_pk_bf16_f32 v222, v224, v225
	v_cvt_pk_bf16_f32 v223, v226, v227
	global_store_dwordx2 v[204:205], v[222:223], off
	v_pk_fma_f32 v[54:55], v[54:55], 0.5, v[182:183] op_sel_hi:[1,0,1]
	v_pk_fma_f32 v[52:53], v[52:53], 0.5, v[180:181] op_sel_hi:[1,0,1]
	global_store_dwordx4 v[220:221], v[52:55], off offset:512
	v_pk_mul_f32 v[228:229], v[84:85], v[52:53]
	v_pk_mul_f32 v[230:231], v[86:87], v[54:55]
	v_fmac_f32_e32 v234, v52, v52
	v_fmac_f32_e32 v234, v53, v53
	v_fmac_f32_e32 v234, v54, v54
	v_fmac_f32_e32 v234, v55, v55
	v_cvt_pk_bf16_f32 v232, v228, v229
	v_cvt_pk_bf16_f32 v233, v230, v231
	global_store_dwordx2 v[204:205], v[232:233], off offset:256
	s_nop 1
	v_mov_b32_dpp v241, v175 row_ror:8 row_mask:0xf bank_mask:0xf
	v_mov_b32_dpp v242, v234 row_ror:8 row_mask:0xf bank_mask:0xf
	v_add_f32_e32 v175, v175, v241
	v_add_f32_e32 v234, v234, v242
	v_cndmask_b32_e64 v175, v234, v175, s[34:35]
	s_nop 0
	ds_bpermute_b32 v241, v235, v175
	global_load_dwordx4 v[156:159], v[164:165], off
	global_load_dwordx4 v[160:163], v[164:165], off offset:512
	global_load_dwordx4 v[176:179], v[200:201], off
	global_load_dwordx4 v[180:183], v[200:201], off offset:512
	s_mov_b64 vcc, 0x20000
	v_lshl_add_u64 v[164:165], v[164:165], 0, vcc
	v_lshl_add_u64 v[200:201], v[200:201], 0, vcc
	s_mov_b64 vcc, 0x20000
	v_lshl_add_u64 v[218:219], v[218:219], 0, vcc
	v_lshl_add_u64 v[220:221], v[220:221], 0, vcc
	s_mov_b64 vcc, 0x10000
	v_lshl_add_u64 v[202:203], v[202:203], 0, vcc
	v_lshl_add_u64 v[204:205], v[204:205], 0, vcc
	s_waitcnt lgkmcnt(0)
	v_add_f32_e32 v175, v175, v241
	s_nop 0
	ds_bpermute_b32 v242, v240, v175
	s_waitcnt lgkmcnt(0)
	v_add_f32_e32 v175, v175, v242
	s_mov_b64 exec, s[0:1]
	global_atomic_add_f32 v[206:207], v175, off
	s_mov_b64 exec, -1
	s_mov_b64 vcc, 64
	v_lshl_add_u64 v[206:207], v[206:207], 0, vcc
	v_mov_b32_dpp v236, v40 row_ror:8 row_mask:0xf bank_mask:0xf
	v_mov_b32_dpp v237, v41 row_ror:8 row_mask:0xf bank_mask:0xf
	v_mov_b32_dpp v238, v42 row_ror:8 row_mask:0xf bank_mask:0xf
	v_mov_b32_dpp v239, v43 row_ror:8 row_mask:0xf bank_mask:0xf
	v_cndmask_b32_e64 v40, v236, v44, s[34:35]
	v_cndmask_b32_e64 v41, v237, v45, s[34:35]
	v_cndmask_b32_e64 v42, v238, v46, s[34:35]
	v_cndmask_b32_e64 v43, v239, v47, s[34:35]
	v_cndmask_b32_e64 v44, v44, v236, s[34:35]
	v_cndmask_b32_e64 v45, v45, v237, s[34:35]
	v_cndmask_b32_e64 v46, v46, v238, s[34:35]
	v_cndmask_b32_e64 v47, v47, v239, s[34:35]
	v_mov_b32_dpp v236, v32 row_ror:8 row_mask:0xf bank_mask:0xf
	v_mov_b32_dpp v237, v33 row_ror:8 row_mask:0xf bank_mask:0xf
	v_mov_b32_dpp v238, v34 row_ror:8 row_mask:0xf bank_mask:0xf
	v_mov_b32_dpp v239, v35 row_ror:8 row_mask:0xf bank_mask:0xf
	v_cndmask_b32_e64 v32, v236, v36, s[34:35]
	v_cndmask_b32_e64 v33, v237, v37, s[34:35]
	v_cndmask_b32_e64 v34, v238, v38, s[34:35]
	v_cndmask_b32_e64 v35, v239, v39, s[34:35]
	v_cndmask_b32_e64 v36, v36, v236, s[34:35]
	v_cndmask_b32_e64 v37, v37, v237, s[34:35]
	v_cndmask_b32_e64 v38, v38, v238, s[34:35]
	v_cndmask_b32_e64 v39, v39, v239, s[34:35]
	s_waitcnt vmcnt(14)
;     __device__ __forceinline__ void operator()(const f32x4 (&acc)[2][2][4][2], const Unit& u, int wr, int wc, int fr, int fq) const {
;     ...
; #pragma unroll
;         for (int ai = 0; ai < 2; ++ai)
; #pragma unroll
;             for (int m = 0; m < 4; ++m) {
;                 const int row = row0 + ai * HALF + m * 16;
;                 const size_t off = (size_t)row * ldc + col0;
;                 float q = 0.f;
; #pragma unroll
;                 for (int bj = 0; bj < 2; ++bj)
; #pragma unroll
;                     for (int n = 0; n < 2; ++n) {
;                         const f32x4 rv = *(const f32x4*)(rbase + off + bj * HALF + n * 16);
;                         const f32x4 v = rv + acc[ai][bj][m][n] * scale;
;                         if (out) *(f32x4*)(out + off + bj * HALF + n * 16) = v;
;                         if (xn) { q += (v.x * v.x + v.y * v.y) + (v.z * v.z + v.w * v.w); const f32x4 o = v * wv[bj][n];
;                             u32x2 p; p.x = pk2(o.x, o.y); p.y = pk2(o.z, o.w); *(u32x2*)(xn + off + bj * HALF + n * 16) = p; }
;                     }
;                 if (xn) { q += __shfl_xor(q, 16); q += __shfl_xor(q, 32); if (fq == 0) (void)__hip_atomic_fetch_add(ss + row, q, __ATOMIC_RELAXED, __HIP_MEMORY_SCOPE_AGENT); }
	v_pk_fma_f32 v[42:43], v[42:43], 0.5, v[186:187] op_sel_hi:[1,0,1]
	v_pk_fma_f32 v[40:41], v[40:41], 0.5, v[184:185] op_sel_hi:[1,0,1]
	global_store_dwordx4 v[218:219], v[40:43], off
	v_pk_mul_f32 v[224:225], v[64:65], v[40:41]
	v_pk_mul_f32 v[226:227], v[66:67], v[42:43]
	v_mul_f32_e32 v175, v40, v40
	v_fmac_f32_e32 v175, v41, v41
	v_fmac_f32_e32 v175, v42, v42
	v_fmac_f32_e32 v175, v43, v43
	v_cvt_pk_bf16_f32 v222, v224, v225
	v_cvt_pk_bf16_f32 v223, v226, v227
	global_store_dwordx2 v[202:203], v[222:223], off
	v_pk_fma_f32 v[34:35], v[34:35], 0.5, v[190:191] op_sel_hi:[1,0,1]
	v_pk_fma_f32 v[32:33], v[32:33], 0.5, v[188:189] op_sel_hi:[1,0,1]
	global_store_dwordx4 v[218:219], v[32:35], off offset:512
	v_pk_mul_f32 v[228:229], v[72:73], v[32:33]
	v_pk_mul_f32 v[230:231], v[74:75], v[34:35]
	v_fmac_f32_e32 v175, v32, v32
	v_fmac_f32_e32 v175, v33, v33
	v_fmac_f32_e32 v175, v34, v34
	v_fmac_f32_e32 v175, v35, v35
	v_cvt_pk_bf16_f32 v232, v228, v229
	v_cvt_pk_bf16_f32 v233, v230, v231
	global_store_dwordx2 v[202:203], v[232:233], off offset:256
	v_pk_fma_f32 v[46:47], v[46:47], 0.5, v[194:195] op_sel_hi:[1,0,1]
	v_pk_fma_f32 v[44:45], v[44:45], 0.5, v[192:193] op_sel_hi:[1,0,1]
	global_store_dwordx4 v[220:221], v[44:47], off
	v_pk_mul_f32 v[224:225], v[80:81], v[44:45]
	v_pk_mul_f32 v[226:227], v[82:83], v[46:47]
	v_mul_f32_e32 v234, v44, v44
	v_fmac_f32_e32 v234, v45, v45
	v_fmac_f32_e32 v234, v46, v46
	v_fmac_f32_e32 v234, v47, v47
	v_cvt_pk_bf16_f32 v222, v224, v225
	v_cvt_pk_bf16_f32 v223, v226, v227
	global_store_dwordx2 v[204:205], v[222:223], off
	v_pk_fma_f32 v[38:39], v[38:39], 0.5, v[198:199] op_sel_hi:[1,0,1]
	v_pk_fma_f32 v[36:37], v[36:37], 0.5, v[196:197] op_sel_hi:[1,0,1]
	global_store_dwordx4 v[220:221], v[36:39], off offset:512
	v_pk_mul_f32 v[228:229], v[84:85], v[36:37]
	v_pk_mul_f32 v[230:231], v[86:87], v[38:39]
	v_fmac_f32_e32 v234, v36, v36
	v_fmac_f32_e32 v234, v37, v37
	v_fmac_f32_e32 v234, v38, v38
	v_fmac_f32_e32 v234, v39, v39
	v_cvt_pk_bf16_f32 v232, v228, v229
	v_cvt_pk_bf16_f32 v233, v230, v231
	global_store_dwordx2 v[204:205], v[232:233], off offset:256
	s_nop 1
	v_mov_b32_dpp v241, v175 row_ror:8 row_mask:0xf bank_mask:0xf
	v_mov_b32_dpp v242, v234 row_ror:8 row_mask:0xf bank_mask:0xf
	v_add_f32_e32 v175, v175, v241
	v_add_f32_e32 v234, v234, v242
	v_cndmask_b32_e64 v175, v234, v175, s[34:35]
	s_nop 0
	ds_bpermute_b32 v241, v235, v175
	global_load_dwordx4 v[184:187], v[164:165], off
	global_load_dwordx4 v[188:191], v[164:165], off offset:512
	global_load_dwordx4 v[192:195], v[200:201], off
	global_load_dwordx4 v[196:199], v[200:201], off offset:512
	s_mov_b64 vcc, 0x20000
	v_lshl_add_u64 v[218:219], v[218:219], 0, vcc
	v_lshl_add_u64 v[220:221], v[220:221], 0, vcc
	s_mov_b64 vcc, 0x10000
	v_lshl_add_u64 v[202:203], v[202:203], 0, vcc
	v_lshl_add_u64 v[204:205], v[204:205], 0, vcc
	s_waitcnt lgkmcnt(0)
	v_add_f32_e32 v175, v175, v241
	s_nop 0
	ds_bpermute_b32 v242, v240, v175
	s_waitcnt lgkmcnt(0)
	v_add_f32_e32 v175, v175, v242
	s_mov_b64 exec, s[0:1]
	global_atomic_add_f32 v[206:207], v175, off
	s_mov_b64 exec, -1
	s_mov_b64 vcc, 64
	v_lshl_add_u64 v[206:207], v[206:207], 0, vcc
	v_mov_b32_dpp v236, v24 row_ror:8 row_mask:0xf bank_mask:0xf
	v_mov_b32_dpp v237, v25 row_ror:8 row_mask:0xf bank_mask:0xf
	v_mov_b32_dpp v238, v26 row_ror:8 row_mask:0xf bank_mask:0xf
	v_mov_b32_dpp v239, v27 row_ror:8 row_mask:0xf bank_mask:0xf
	v_cndmask_b32_e64 v24, v236, v28, s[34:35]
	v_cndmask_b32_e64 v25, v237, v29, s[34:35]
	v_cndmask_b32_e64 v26, v238, v30, s[34:35]
	v_cndmask_b32_e64 v27, v239, v31, s[34:35]
	v_cndmask_b32_e64 v28, v28, v236, s[34:35]
	v_cndmask_b32_e64 v29, v29, v237, s[34:35]
	v_cndmask_b32_e64 v30, v30, v238, s[34:35]
	v_cndmask_b32_e64 v31, v31, v239, s[34:35]
	v_mov_b32_dpp v236, v16 row_ror:8 row_mask:0xf bank_mask:0xf
	v_mov_b32_dpp v237, v17 row_ror:8 row_mask:0xf bank_mask:0xf
	v_mov_b32_dpp v238, v18 row_ror:8 row_mask:0xf bank_mask:0xf
	v_mov_b32_dpp v239, v19 row_ror:8 row_mask:0xf bank_mask:0xf
	v_cndmask_b32_e64 v16, v236, v20, s[34:35]
	v_cndmask_b32_e64 v17, v237, v21, s[34:35]
	v_cndmask_b32_e64 v18, v238, v22, s[34:35]
	v_cndmask_b32_e64 v19, v239, v23, s[34:35]
	v_cndmask_b32_e64 v20, v20, v236, s[34:35]
	v_cndmask_b32_e64 v21, v21, v237, s[34:35]
	v_cndmask_b32_e64 v22, v22, v238, s[34:35]
	v_cndmask_b32_e64 v23, v23, v239, s[34:35]
	s_waitcnt vmcnt(14)
; #define PG8_BAR __builtin_amdgcn_s_barrier()
;     __device__ __forceinline__ void operator()(const f32x4 (&acc)[2][2][4][2], const Unit& u, int wr, int wc, int fr, int fq) const {
;     ...
; #pragma unroll
;         for (int ai = 0; ai < 2; ++ai)
; #pragma unroll
;             for (int m = 0; m < 4; ++m) {
;                 const int row = row0 + ai * HALF + m * 16;
;                 const size_t off = (size_t)row * ldc + col0;
;                 float q = 0.f;
; #pragma unroll
;                 for (int bj = 0; bj < 2; ++bj)
; #pragma unroll
;                     for (int n = 0; n < 2; ++n) {
;                         const f32x4 rv = *(const f32x4*)(rbase + off + bj * HALF + n * 16);
;                         const f32x4 v = rv + acc[ai][bj][m][n] * scale;
;                         if (out) *(f32x4*)(out + off + bj * HALF + n * 16) = v;
;                         if (xn) { q += (v.x * v.x + v.y * v.y) + (v.z * v.z + v.w * v.w); const f32x4 o = v * wv[bj][n];
;                             u32x2 p; p.x = pk2(o.x, o.y); p.y = pk2(o.z, o.w); *(u32x2*)(xn + off + bj * HALF + n * 16) = p; }
;                     }
;                 if (xn) { q += __shfl_xor(q, 16); q += __shfl_xor(q, 32); if (fq == 0) (void)__hip_atomic_fetch_add(ss + row, q, __ATOMIC_RELAXED, __HIP_MEMORY_SCOPE_AGENT); }
; template <class Epi, bool ALIGN_EPI>
; __device__ __forceinline__ void gemm_phase(LAS unsigned char* lds, const Gemm g, const StaticOrder& S, const Epi& E) {
;     ...
;         if (!has_next) break;
; #pragma unroll
;         for (int a = 0; a < 2; ++a)
; #pragma unroll
;             for (int b = 0; b < 2; ++b)
; #pragma unroll
;                 for (int m = 0; m < 4; ++m)
; #pragma unroll
;                     for (int n = 0; n < 2; ++n) acc[a][b][m][n] = (f32x4){0.f, 0.f, 0.f, 0.f};
;         cur = nxt; cA = nA; cB = nB; ++ui;
;         if constexpr (ALIGN_EPI) { if (wr == 1) PG8_BAR; }
	v_pk_fma_f32 v[26:27], v[26:27], 0.5, v[158:159] op_sel_hi:[1,0,1]
	v_pk_fma_f32 v[24:25], v[24:25], 0.5, v[156:157] op_sel_hi:[1,0,1]
	global_store_dwordx4 v[218:219], v[24:27], off
	v_pk_mul_f32 v[224:225], v[64:65], v[24:25]
	v_pk_mul_f32 v[226:227], v[66:67], v[26:27]
	v_mul_f32_e32 v175, v24, v24
	v_fmac_f32_e32 v175, v25, v25
	v_fmac_f32_e32 v175, v26, v26
	v_fmac_f32_e32 v175, v27, v27
	v_cvt_pk_bf16_f32 v222, v224, v225
	v_cvt_pk_bf16_f32 v223, v226, v227
	global_store_dwordx2 v[202:203], v[222:223], off
	v_pk_fma_f32 v[18:19], v[18:19], 0.5, v[162:163] op_sel_hi:[1,0,1]
	v_pk_fma_f32 v[16:17], v[16:17], 0.5, v[160:161] op_sel_hi:[1,0,1]
	global_store_dwordx4 v[218:219], v[16:19], off offset:512
	v_pk_mul_f32 v[228:229], v[72:73], v[16:17]
	v_pk_mul_f32 v[230:231], v[74:75], v[18:19]
	v_fmac_f32_e32 v175, v16, v16
	v_fmac_f32_e32 v175, v17, v17
	v_fmac_f32_e32 v175, v18, v18
	v_fmac_f32_e32 v175, v19, v19
	v_cvt_pk_bf16_f32 v232, v228, v229
	v_cvt_pk_bf16_f32 v233, v230, v231
	global_store_dwordx2 v[202:203], v[232:233], off offset:256
	v_pk_fma_f32 v[30:31], v[30:31], 0.5, v[178:179] op_sel_hi:[1,0,1]
	v_pk_fma_f32 v[28:29], v[28:29], 0.5, v[176:177] op_sel_hi:[1,0,1]
	global_store_dwordx4 v[220:221], v[28:31], off
	v_pk_mul_f32 v[224:225], v[80:81], v[28:29]
	v_pk_mul_f32 v[226:227], v[82:83], v[30:31]
	v_mul_f32_e32 v234, v28, v28
	v_fmac_f32_e32 v234, v29, v29
	v_fmac_f32_e32 v234, v30, v30
	v_fmac_f32_e32 v234, v31, v31
	v_cvt_pk_bf16_f32 v222, v224, v225
	v_cvt_pk_bf16_f32 v223, v226, v227
	global_store_dwordx2 v[204:205], v[222:223], off
	v_pk_fma_f32 v[22:23], v[22:23], 0.5, v[182:183] op_sel_hi:[1,0,1]
	v_pk_fma_f32 v[20:21], v[20:21], 0.5, v[180:181] op_sel_hi:[1,0,1]
	global_store_dwordx4 v[220:221], v[20:23], off offset:512
	v_pk_mul_f32 v[228:229], v[84:85], v[20:21]
	v_pk_mul_f32 v[230:231], v[86:87], v[22:23]
	v_fmac_f32_e32 v234, v20, v20
	v_fmac_f32_e32 v234, v21, v21
	v_fmac_f32_e32 v234, v22, v22
	v_fmac_f32_e32 v234, v23, v23
	v_cvt_pk_bf16_f32 v232, v228, v229
	v_cvt_pk_bf16_f32 v233, v230, v231
	global_store_dwordx2 v[204:205], v[232:233], off offset:256
	s_nop 1
	v_mov_b32_dpp v241, v175 row_ror:8 row_mask:0xf bank_mask:0xf
	v_mov_b32_dpp v242, v234 row_ror:8 row_mask:0xf bank_mask:0xf
	v_add_f32_e32 v175, v175, v241
	v_add_f32_e32 v234, v234, v242
	v_cndmask_b32_e64 v175, v234, v175, s[34:35]
	s_nop 0
	ds_bpermute_b32 v241, v235, v175
	s_mov_b64 vcc, 0x20000
	v_lshl_add_u64 v[218:219], v[218:219], 0, vcc
	v_lshl_add_u64 v[220:221], v[220:221], 0, vcc
	s_mov_b64 vcc, 0x10000
	v_lshl_add_u64 v[202:203], v[202:203], 0, vcc
	v_lshl_add_u64 v[204:205], v[204:205], 0, vcc
	s_waitcnt lgkmcnt(0)
	v_add_f32_e32 v175, v175, v241
	s_nop 0
	ds_bpermute_b32 v242, v240, v175
	s_waitcnt lgkmcnt(0)
	v_add_f32_e32 v175, v175, v242
	s_mov_b64 exec, s[0:1]
	global_atomic_add_f32 v[206:207], v175, off
	s_mov_b64 exec, -1
	s_mov_b64 vcc, 64
	v_lshl_add_u64 v[206:207], v[206:207], 0, vcc
	v_mov_b32_dpp v236, v8 row_ror:8 row_mask:0xf bank_mask:0xf
	v_mov_b32_dpp v237, v9 row_ror:8 row_mask:0xf bank_mask:0xf
	v_mov_b32_dpp v238, v10 row_ror:8 row_mask:0xf bank_mask:0xf
	v_mov_b32_dpp v239, v11 row_ror:8 row_mask:0xf bank_mask:0xf
	v_cndmask_b32_e64 v8, v236, v12, s[34:35]
	v_cndmask_b32_e64 v9, v237, v13, s[34:35]
	v_cndmask_b32_e64 v10, v238, v14, s[34:35]
	v_cndmask_b32_e64 v11, v239, v15, s[34:35]
	v_cndmask_b32_e64 v12, v12, v236, s[34:35]
	v_cndmask_b32_e64 v13, v13, v237, s[34:35]
	v_cndmask_b32_e64 v14, v14, v238, s[34:35]
	v_cndmask_b32_e64 v15, v15, v239, s[34:35]
	v_mov_b32_dpp v236, v0 row_ror:8 row_mask:0xf bank_mask:0xf
	v_mov_b32_dpp v237, v1 row_ror:8 row_mask:0xf bank_mask:0xf
	v_mov_b32_dpp v238, v2 row_ror:8 row_mask:0xf bank_mask:0xf
	v_mov_b32_dpp v239, v3 row_ror:8 row_mask:0xf bank_mask:0xf
	v_cndmask_b32_e64 v0, v236, v4, s[34:35]
	v_cndmask_b32_e64 v1, v237, v5, s[34:35]
	v_cndmask_b32_e64 v2, v238, v6, s[34:35]
	v_cndmask_b32_e64 v3, v239, v7, s[34:35]
	v_cndmask_b32_e64 v4, v4, v236, s[34:35]
	v_cndmask_b32_e64 v5, v5, v237, s[34:35]
	v_cndmask_b32_e64 v6, v6, v238, s[34:35]
	v_cndmask_b32_e64 v7, v7, v239, s[34:35]
	s_waitcnt vmcnt(10)
	v_pk_fma_f32 v[10:11], v[10:11], 0.5, v[186:187] op_sel_hi:[1,0,1]
	v_pk_fma_f32 v[8:9], v[8:9], 0.5, v[184:185] op_sel_hi:[1,0,1]
	global_store_dwordx4 v[218:219], v[8:11], off
	v_pk_mul_f32 v[224:225], v[64:65], v[8:9]
	v_pk_mul_f32 v[226:227], v[66:67], v[10:11]
	v_mul_f32_e32 v175, v8, v8
	v_fmac_f32_e32 v175, v9, v9
	v_fmac_f32_e32 v175, v10, v10
	v_fmac_f32_e32 v175, v11, v11
	v_cvt_pk_bf16_f32 v222, v224, v225
	v_cvt_pk_bf16_f32 v223, v226, v227
	global_store_dwordx2 v[202:203], v[222:223], off
	v_pk_fma_f32 v[2:3], v[2:3], 0.5, v[190:191] op_sel_hi:[1,0,1]
	v_pk_fma_f32 v[0:1], v[0:1], 0.5, v[188:189] op_sel_hi:[1,0,1]
	global_store_dwordx4 v[218:219], v[0:3], off offset:512
	v_pk_mul_f32 v[228:229], v[72:73], v[0:1]
	v_pk_mul_f32 v[230:231], v[74:75], v[2:3]
	v_fmac_f32_e32 v175, v0, v0
	v_fmac_f32_e32 v175, v1, v1
	v_fmac_f32_e32 v175, v2, v2
	v_fmac_f32_e32 v175, v3, v3
	v_cvt_pk_bf16_f32 v232, v228, v229
	v_cvt_pk_bf16_f32 v233, v230, v231
	global_store_dwordx2 v[202:203], v[232:233], off offset:256
	v_pk_fma_f32 v[14:15], v[14:15], 0.5, v[194:195] op_sel_hi:[1,0,1]
	v_pk_fma_f32 v[12:13], v[12:13], 0.5, v[192:193] op_sel_hi:[1,0,1]
	global_store_dwordx4 v[220:221], v[12:15], off
	v_pk_mul_f32 v[224:225], v[80:81], v[12:13]
	v_pk_mul_f32 v[226:227], v[82:83], v[14:15]
	v_mul_f32_e32 v234, v12, v12
	v_fmac_f32_e32 v234, v13, v13
	v_fmac_f32_e32 v234, v14, v14
	v_fmac_f32_e32 v234, v15, v15
	v_cvt_pk_bf16_f32 v222, v224, v225
	v_cvt_pk_bf16_f32 v223, v226, v227
	global_store_dwordx2 v[204:205], v[222:223], off
	v_pk_fma_f32 v[6:7], v[6:7], 0.5, v[198:199] op_sel_hi:[1,0,1]
	v_pk_fma_f32 v[4:5], v[4:5], 0.5, v[196:197] op_sel_hi:[1,0,1]
	global_store_dwordx4 v[220:221], v[4:7], off offset:512
	v_pk_mul_f32 v[228:229], v[84:85], v[4:5]
	v_pk_mul_f32 v[230:231], v[86:87], v[6:7]
	v_fmac_f32_e32 v234, v4, v4
	v_fmac_f32_e32 v234, v5, v5
	v_fmac_f32_e32 v234, v6, v6
	v_fmac_f32_e32 v234, v7, v7
	v_cvt_pk_bf16_f32 v232, v228, v229
	v_cvt_pk_bf16_f32 v233, v230, v231
	global_store_dwordx2 v[204:205], v[232:233], off offset:256
	s_nop 1
	v_mov_b32_dpp v241, v175 row_ror:8 row_mask:0xf bank_mask:0xf
	v_mov_b32_dpp v242, v234 row_ror:8 row_mask:0xf bank_mask:0xf
	v_add_f32_e32 v175, v175, v241
	v_add_f32_e32 v234, v234, v242
	v_cndmask_b32_e64 v175, v234, v175, s[34:35]
	s_nop 0
	ds_bpermute_b32 v241, v235, v175
	s_waitcnt lgkmcnt(0)
	v_add_f32_e32 v175, v175, v241
	s_nop 0
	ds_bpermute_b32 v242, v240, v175
	s_waitcnt lgkmcnt(0)
	v_add_f32_e32 v175, v175, v242
	s_mov_b64 exec, s[0:1]
	global_atomic_add_f32 v[206:207], v175, off
	s_mov_b64 exec, -1
	s_and_b64 vcc, exec, s[6:7]
	s_mov_b64 s[4:5], -1
	s_cbranch_vccnz .LBB0_301
	s_andn2_b64 vcc, exec, s[12:13]
	s_cbranch_vccnz .LBB0_300
	s_barrier
	s_branch .LBB0_300

;     __device__ __forceinline__ void operator()(const f32x4 (&acc)[2][2][4][2], const Unit& u, int wr, int wc, int fr, int fq) const {
;         const int row0 = u.pm * BM + wr * 64 + fr, col0 = u.pn * BM + wc * 32 + 4 * fq;
;         const float* rbase = (u.pm * BM < SEQ_P) ? resA : (resB - (size_t)SEQ_P * ldc);
;         f32x4 wv[2][2];
;         if (xn) {
; #pragma unroll
;             for (int bj = 0; bj < 2; ++bj)
; #pragma unroll
;                 for (int n = 0; n < 2; ++n) wv[bj][n] = *(const f32x4*)(wn + col0 + bj * HALF + n * 16);
;         }
; #pragma unroll
;         for (int ai = 0; ai < 2; ++ai)
; #pragma unroll
;             for (int m = 0; m < 4; ++m) {
;                 const int row = row0 + ai * HALF + m * 16;
;                 const size_t off = (size_t)row * ldc + col0;
;                 float q = 0.f;
; #pragma unroll
;                 for (int bj = 0; bj < 2; ++bj)
; #pragma unroll
;                     for (int n = 0; n < 2; ++n) {
;                         const f32x4 rv = *(const f32x4*)(rbase + off + bj * HALF + n * 16);
;                         const f32x4 v = rv + acc[ai][bj][m][n] * scale;
;                         if (out) *(f32x4*)(out + off + bj * HALF + n * 16) = v;
;                         if (xn) { q += (v.x * v.x + v.y * v.y) + (v.z * v.z + v.w * v.w); const f32x4 o = v * wv[bj][n];
;                             u32x2 p; p.x = pk2(o.x, o.y); p.y = pk2(o.z, o.w); *(u32x2*)(xn + off + bj * HALF + n * 16) = p; }
.LBB0_1085:
	v_lshl_add_u32 v212, s34, 8, v164
	v_lshl_or_b32 v214, s4, 8, v168
	v_and_b32_e32 v243, 8, v172
	v_mov_b32_e32 v213, 0
	v_cmp_eq_u32_e64 s[34:35], 0, v243
	v_lshlrev_b32_e32 v173, 1, v243
	v_add_u32_e32 v216, v214, v173
	v_sub_u32_e32 v234, 16, v173
	v_add_u32_e32 v234, v214, v234
	v_mov_b32_e32 v214, v216
	v_mov_b32_e32 v216, v234
	v_mov_b32_e32 v215, 0
	v_mov_b32_e32 v217, 0
	v_sub_u32_e32 v210, v212, v243
	v_mov_b32_e32 v211, 0
	v_lshlrev_b64 v[208:209], 11, v[210:211]
	v_add_u32_e32 v210, 8, v210
	v_lshlrev_b64 v[210:211], 11, v[210:211]
	v_lshl_add_u64 v[208:209], v[208:209], 0, v[214:215]
	v_lshl_add_u64 v[210:211], v[210:211], 0, v[216:217]
	v_lshl_add_u64 v[174:175], v[208:209], 2, s[8:9]
	v_lshl_add_u64 v[200:201], v[210:211], 2, s[8:9]
	v_lshl_add_u64 v[202:203], v[214:215], 2, s[10:11]
	v_lshl_add_u64 v[204:205], v[216:217], 2, s[10:11]
	global_load_dwordx4 v[64:67], v[202:203], off
	global_load_dwordx4 v[72:75], v[202:203], off offset:512
	global_load_dwordx4 v[76:79], v[204:205], off
	global_load_dwordx4 v[84:87], v[204:205], off offset:512
	global_load_dwordx4 v[156:159], v[174:175], off
	global_load_dwordx4 v[160:163], v[174:175], off offset:512
	global_load_dwordx4 v[176:179], v[200:201], off
	global_load_dwordx4 v[180:183], v[200:201], off offset:512
	s_mov_b64 vcc, 0x20000
	v_lshl_add_u64 v[174:175], v[174:175], 0, vcc
	v_lshl_add_u64 v[200:201], v[200:201], 0, vcc
	global_load_dwordx4 v[184:187], v[174:175], off
	global_load_dwordx4 v[188:191], v[174:175], off offset:512
	global_load_dwordx4 v[192:195], v[200:201], off
	global_load_dwordx4 v[196:199], v[200:201], off offset:512
	s_mov_b64 vcc, 0x20000
	v_lshl_add_u64 v[174:175], v[174:175], 0, vcc
	v_lshl_add_u64 v[200:201], v[200:201], 0, vcc
	v_lshl_add_u64 v[218:219], v[208:209], 2, s[8:9]
	v_lshl_add_u64 v[220:221], v[210:211], 2, s[8:9]
	v_lshl_add_u64 v[202:203], v[208:209], 1, s[14:15]
	v_lshl_add_u64 v[204:205], v[210:211], 1, s[14:15]
	v_lshl_add_u64 v[206:207], v[212:213], 2, s[16:17]
	v_xor_b32_e32 v235, 16, v172
	v_xor_b32_e32 v240, 32, v172
	v_lshlrev_b32_e32 v235, 2, v235
	v_lshlrev_b32_e32 v240, 2, v240
	v_mov_b32_dpp v236, v136 row_ror:8 row_mask:0xf bank_mask:0xf
	v_mov_b32_dpp v237, v137 row_ror:8 row_mask:0xf bank_mask:0xf
	v_mov_b32_dpp v238, v138 row_ror:8 row_mask:0xf bank_mask:0xf
	v_mov_b32_dpp v239, v139 row_ror:8 row_mask:0xf bank_mask:0xf
	v_cndmask_b32_e64 v136, v236, v140, s[34:35]
	v_cndmask_b32_e64 v137, v237, v141, s[34:35]
	v_cndmask_b32_e64 v138, v238, v142, s[34:35]
	v_cndmask_b32_e64 v139, v239, v143, s[34:35]
	v_cndmask_b32_e64 v140, v140, v236, s[34:35]
	v_cndmask_b32_e64 v141, v141, v237, s[34:35]
	v_cndmask_b32_e64 v142, v142, v238, s[34:35]
	v_cndmask_b32_e64 v143, v143, v239, s[34:35]
	v_mov_b32_dpp v236, v128 row_ror:8 row_mask:0xf bank_mask:0xf
	v_mov_b32_dpp v237, v129 row_ror:8 row_mask:0xf bank_mask:0xf
	v_mov_b32_dpp v238, v130 row_ror:8 row_mask:0xf bank_mask:0xf
	v_mov_b32_dpp v239, v131 row_ror:8 row_mask:0xf bank_mask:0xf
	v_cndmask_b32_e64 v128, v236, v132, s[34:35]
	v_cndmask_b32_e64 v129, v237, v133, s[34:35]
	v_cndmask_b32_e64 v130, v238, v134, s[34:35]
	v_cndmask_b32_e64 v131, v239, v135, s[34:35]
	v_cndmask_b32_e64 v132, v132, v236, s[34:35]
	v_cndmask_b32_e64 v133, v133, v237, s[34:35]
	v_cndmask_b32_e64 v134, v134, v238, s[34:35]
	v_cndmask_b32_e64 v135, v135, v239, s[34:35]
	s_waitcnt vmcnt(4)
	v_pk_add_f32 v[138:139], v[138:139], v[158:159]
	v_pk_add_f32 v[136:137], v[136:137], v[156:157]
	global_store_dwordx4 v[218:219], v[136:139], off
	v_pk_mul_f32 v[224:225], v[64:65], v[136:137]
	v_pk_mul_f32 v[226:227], v[66:67], v[138:139]
	v_mul_f32_e32 v173, v136, v136
	v_fmac_f32_e32 v173, v137, v137
	v_fmac_f32_e32 v173, v138, v138
	v_fmac_f32_e32 v173, v139, v139
	v_cvt_pk_bf16_f32 v222, v224, v225
	v_cvt_pk_bf16_f32 v223, v226, v227
	global_store_dwordx2 v[202:203], v[222:223], off
	v_pk_add_f32 v[130:131], v[130:131], v[162:163]
	v_pk_add_f32 v[128:129], v[128:129], v[160:161]
	global_store_dwordx4 v[218:219], v[128:131], off offset:512
	v_pk_mul_f32 v[228:229], v[72:73], v[128:129]
	v_pk_mul_f32 v[230:231], v[74:75], v[130:131]
	v_fmac_f32_e32 v173, v128, v128
	v_fmac_f32_e32 v173, v129, v129
	v_fmac_f32_e32 v173, v130, v130
	v_fmac_f32_e32 v173, v131, v131
	v_cvt_pk_bf16_f32 v232, v228, v229
	v_cvt_pk_bf16_f32 v233, v230, v231
	global_store_dwordx2 v[202:203], v[232:233], off offset:256
	v_pk_add_f32 v[142:143], v[142:143], v[178:179]
	v_pk_add_f32 v[140:141], v[140:141], v[176:177]
	global_store_dwordx4 v[220:221], v[140:143], off
	v_pk_mul_f32 v[224:225], v[76:77], v[140:141]
	v_pk_mul_f32 v[226:227], v[78:79], v[142:143]
	v_mul_f32_e32 v234, v140, v140
	v_fmac_f32_e32 v234, v141, v141
	v_fmac_f32_e32 v234, v142, v142
	v_fmac_f32_e32 v234, v143, v143
	v_cvt_pk_bf16_f32 v222, v224, v225
	v_cvt_pk_bf16_f32 v223, v226, v227
	global_store_dwordx2 v[204:205], v[222:223], off
	v_pk_add_f32 v[134:135], v[134:135], v[182:183]
	v_pk_add_f32 v[132:133], v[132:133], v[180:181]
	global_store_dwordx4 v[220:221], v[132:135], off offset:512
	v_pk_mul_f32 v[228:229], v[84:85], v[132:133]
	v_pk_mul_f32 v[230:231], v[86:87], v[134:135]
	v_fmac_f32_e32 v234, v132, v132
	v_fmac_f32_e32 v234, v133, v133
	v_fmac_f32_e32 v234, v134, v134
	v_fmac_f32_e32 v234, v135, v135
	v_cvt_pk_bf16_f32 v232, v228, v229
	v_cvt_pk_bf16_f32 v233, v230, v231
	global_store_dwordx2 v[204:205], v[232:233], off offset:256
	s_nop 1
	v_mov_b32_dpp v241, v173 row_ror:8 row_mask:0xf bank_mask:0xf
	v_mov_b32_dpp v242, v234 row_ror:8 row_mask:0xf bank_mask:0xf
	v_add_f32_e32 v173, v173, v241
	v_add_f32_e32 v234, v234, v242
	v_cndmask_b32_e64 v173, v234, v173, s[34:35]
	s_nop 0
	ds_bpermute_b32 v241, v235, v173
	global_load_dwordx4 v[156:159], v[174:175], off
	global_load_dwordx4 v[160:163], v[174:175], off offset:512
	global_load_dwordx4 v[176:179], v[200:201], off
	global_load_dwordx4 v[180:183], v[200:201], off offset:512
	s_mov_b64 vcc, 0x20000
	v_lshl_add_u64 v[174:175], v[174:175], 0, vcc
	v_lshl_add_u64 v[200:201], v[200:201], 0, vcc
	s_mov_b64 vcc, 0x20000
	v_lshl_add_u64 v[218:219], v[218:219], 0, vcc
	v_lshl_add_u64 v[220:221], v[220:221], 0, vcc
	s_mov_b64 vcc, 0x10000
	v_lshl_add_u64 v[202:203], v[202:203], 0, vcc
	v_lshl_add_u64 v[204:205], v[204:205], 0, vcc
	s_waitcnt lgkmcnt(0)
;     __device__ __forceinline__ void operator()(const f32x4 (&acc)[2][2][4][2], const Unit& u, int wr, int wc, int fr, int fq) const {
;     ...
; #pragma unroll
;         for (int ai = 0; ai < 2; ++ai)
; #pragma unroll
;             for (int m = 0; m < 4; ++m) {
;                 const int row = row0 + ai * HALF + m * 16;
;                 const size_t off = (size_t)row * ldc + col0;
;                 float q = 0.f;
; #pragma unroll
;                 for (int bj = 0; bj < 2; ++bj)
; #pragma unroll
;                     for (int n = 0; n < 2; ++n) {
;                         const f32x4 rv = *(const f32x4*)(rbase + off + bj * HALF + n * 16);
;                         const f32x4 v = rv + acc[ai][bj][m][n] * scale;
;                         if (out) *(f32x4*)(out + off + bj * HALF + n * 16) = v;
;                         if (xn) { q += (v.x * v.x + v.y * v.y) + (v.z * v.z + v.w * v.w); const f32x4 o = v * wv[bj][n];
;                             u32x2 p; p.x = pk2(o.x, o.y); p.y = pk2(o.z, o.w); *(u32x2*)(xn + off + bj * HALF + n * 16) = p; }
;                     }
;                 if (xn) { q += __shfl_xor(q, 16); q += __shfl_xor(q, 32); if (fq == 0) (void)__hip_atomic_fetch_add(ss + row, q, __ATOMIC_RELAXED, __HIP_MEMORY_SCOPE_AGENT); }
	v_add_f32_e32 v173, v173, v241
	s_nop 0
	ds_bpermute_b32 v242, v240, v173
	s_waitcnt lgkmcnt(0)
	v_add_f32_e32 v173, v173, v242
	s_mov_b64 exec, s[0:1]
	global_atomic_add_f32 v[206:207], v173, off
	s_mov_b64 exec, -1
	s_mov_b64 vcc, 64
	v_lshl_add_u64 v[206:207], v[206:207], 0, vcc
	v_mov_b32_dpp v236, v120 row_ror:8 row_mask:0xf bank_mask:0xf
	v_mov_b32_dpp v237, v121 row_ror:8 row_mask:0xf bank_mask:0xf
	v_mov_b32_dpp v238, v122 row_ror:8 row_mask:0xf bank_mask:0xf
	v_mov_b32_dpp v239, v123 row_ror:8 row_mask:0xf bank_mask:0xf
	v_cndmask_b32_e64 v120, v236, v124, s[34:35]
	v_cndmask_b32_e64 v121, v237, v125, s[34:35]
	v_cndmask_b32_e64 v122, v238, v126, s[34:35]
	v_cndmask_b32_e64 v123, v239, v127, s[34:35]
	v_cndmask_b32_e64 v124, v124, v236, s[34:35]
	v_cndmask_b32_e64 v125, v125, v237, s[34:35]
	v_cndmask_b32_e64 v126, v126, v238, s[34:35]
	v_cndmask_b32_e64 v127, v127, v239, s[34:35]
	v_mov_b32_dpp v236, v112 row_ror:8 row_mask:0xf bank_mask:0xf
	v_mov_b32_dpp v237, v113 row_ror:8 row_mask:0xf bank_mask:0xf
	v_mov_b32_dpp v238, v114 row_ror:8 row_mask:0xf bank_mask:0xf
	v_mov_b32_dpp v239, v115 row_ror:8 row_mask:0xf bank_mask:0xf
	v_cndmask_b32_e64 v112, v236, v116, s[34:35]
	v_cndmask_b32_e64 v113, v237, v117, s[34:35]
	v_cndmask_b32_e64 v114, v238, v118, s[34:35]
	v_cndmask_b32_e64 v115, v239, v119, s[34:35]
	v_cndmask_b32_e64 v116, v116, v236, s[34:35]
	v_cndmask_b32_e64 v117, v117, v237, s[34:35]
	v_cndmask_b32_e64 v118, v118, v238, s[34:35]
	v_cndmask_b32_e64 v119, v119, v239, s[34:35]
	s_waitcnt vmcnt(13)
	v_pk_add_f32 v[122:123], v[122:123], v[186:187]
	v_pk_add_f32 v[120:121], v[120:121], v[184:185]
	global_store_dwordx4 v[218:219], v[120:123], off
	v_pk_mul_f32 v[224:225], v[64:65], v[120:121]
	v_pk_mul_f32 v[226:227], v[66:67], v[122:123]
	v_mul_f32_e32 v173, v120, v120
	v_fmac_f32_e32 v173, v121, v121
	v_fmac_f32_e32 v173, v122, v122
	v_fmac_f32_e32 v173, v123, v123
	v_cvt_pk_bf16_f32 v222, v224, v225
	v_cvt_pk_bf16_f32 v223, v226, v227
	global_store_dwordx2 v[202:203], v[222:223], off
	v_pk_add_f32 v[114:115], v[114:115], v[190:191]
	v_pk_add_f32 v[112:113], v[112:113], v[188:189]
	global_store_dwordx4 v[218:219], v[112:115], off offset:512
	v_pk_mul_f32 v[228:229], v[72:73], v[112:113]
	v_pk_mul_f32 v[230:231], v[74:75], v[114:115]
	v_fmac_f32_e32 v173, v112, v112
	v_fmac_f32_e32 v173, v113, v113
	v_fmac_f32_e32 v173, v114, v114
	v_fmac_f32_e32 v173, v115, v115
	v_cvt_pk_bf16_f32 v232, v228, v229
	v_cvt_pk_bf16_f32 v233, v230, v231
	global_store_dwordx2 v[202:203], v[232:233], off offset:256
	v_pk_add_f32 v[126:127], v[126:127], v[194:195]
	v_pk_add_f32 v[124:125], v[124:125], v[192:193]
	global_store_dwordx4 v[220:221], v[124:127], off
	v_pk_mul_f32 v[224:225], v[76:77], v[124:125]
	v_pk_mul_f32 v[226:227], v[78:79], v[126:127]
	v_mul_f32_e32 v234, v124, v124
	v_fmac_f32_e32 v234, v125, v125
	v_fmac_f32_e32 v234, v126, v126
	v_fmac_f32_e32 v234, v127, v127
	v_cvt_pk_bf16_f32 v222, v224, v225
	v_cvt_pk_bf16_f32 v223, v226, v227
	global_store_dwordx2 v[204:205], v[222:223], off
	v_pk_add_f32 v[118:119], v[118:119], v[198:199]
	v_pk_add_f32 v[116:117], v[116:117], v[196:197]
	global_store_dwordx4 v[220:221], v[116:119], off offset:512
	v_pk_mul_f32 v[228:229], v[84:85], v[116:117]
	v_pk_mul_f32 v[230:231], v[86:87], v[118:119]
	v_fmac_f32_e32 v234, v116, v116
	v_fmac_f32_e32 v234, v117, v117
	v_fmac_f32_e32 v234, v118, v118
	v_fmac_f32_e32 v234, v119, v119
	v_cvt_pk_bf16_f32 v232, v228, v229
	v_cvt_pk_bf16_f32 v233, v230, v231
	global_store_dwordx2 v[204:205], v[232:233], off offset:256
	s_nop 1
	v_mov_b32_dpp v241, v173 row_ror:8 row_mask:0xf bank_mask:0xf
	v_mov_b32_dpp v242, v234 row_ror:8 row_mask:0xf bank_mask:0xf
	v_add_f32_e32 v173, v173, v241
	v_add_f32_e32 v234, v234, v242
	v_cndmask_b32_e64 v173, v234, v173, s[34:35]
	s_nop 0
	ds_bpermute_b32 v241, v235, v173
	global_load_dwordx4 v[184:187], v[174:175], off
	global_load_dwordx4 v[188:191], v[174:175], off offset:512
	global_load_dwordx4 v[192:195], v[200:201], off
	global_load_dwordx4 v[196:199], v[200:201], off offset:512
	s_mov_b64 vcc, 0xa0000
	v_lshl_add_u64 v[174:175], v[174:175], 0, vcc
	v_lshl_add_u64 v[200:201], v[200:201], 0, vcc
	s_mov_b64 vcc, 0x20000
	v_lshl_add_u64 v[218:219], v[218:219], 0, vcc
	v_lshl_add_u64 v[220:221], v[220:221], 0, vcc
	s_mov_b64 vcc, 0x10000
	v_lshl_add_u64 v[202:203], v[202:203], 0, vcc
	v_lshl_add_u64 v[204:205], v[204:205], 0, vcc
	s_waitcnt lgkmcnt(0)
	v_add_f32_e32 v173, v173, v241
	s_nop 0
	ds_bpermute_b32 v242, v240, v173
	s_waitcnt lgkmcnt(0)
	v_add_f32_e32 v173, v173, v242
	s_mov_b64 exec, s[0:1]
	global_atomic_add_f32 v[206:207], v173, off
	s_mov_b64 exec, -1
	s_mov_b64 vcc, 64
	v_lshl_add_u64 v[206:207], v[206:207], 0, vcc
	v_mov_b32_dpp v236, v104 row_ror:8 row_mask:0xf bank_mask:0xf
	v_mov_b32_dpp v237, v105 row_ror:8 row_mask:0xf bank_mask:0xf
	v_mov_b32_dpp v238, v106 row_ror:8 row_mask:0xf bank_mask:0xf
	v_mov_b32_dpp v239, v107 row_ror:8 row_mask:0xf bank_mask:0xf
	v_cndmask_b32_e64 v104, v236, v108, s[34:35]
	v_cndmask_b32_e64 v105, v237, v109, s[34:35]
	v_cndmask_b32_e64 v106, v238, v110, s[34:35]
	v_cndmask_b32_e64 v107, v239, v111, s[34:35]
	v_cndmask_b32_e64 v108, v108, v236, s[34:35]
	v_cndmask_b32_e64 v109, v109, v237, s[34:35]
	v_cndmask_b32_e64 v110, v110, v238, s[34:35]
	v_cndmask_b32_e64 v111, v111, v239, s[34:35]
	v_mov_b32_dpp v236, v96 row_ror:8 row_mask:0xf bank_mask:0xf
	v_mov_b32_dpp v237, v97 row_ror:8 row_mask:0xf bank_mask:0xf
	v_mov_b32_dpp v238, v98 row_ror:8 row_mask:0xf bank_mask:0xf
	v_mov_b32_dpp v239, v99 row_ror:8 row_mask:0xf bank_mask:0xf
	v_cndmask_b32_e64 v96, v236, v100, s[34:35]
	v_cndmask_b32_e64 v97, v237, v101, s[34:35]
	v_cndmask_b32_e64 v98, v238, v102, s[34:35]
	v_cndmask_b32_e64 v99, v239, v103, s[34:35]
	v_cndmask_b32_e64 v100, v100, v236, s[34:35]
	v_cndmask_b32_e64 v101, v101, v237, s[34:35]
	v_cndmask_b32_e64 v102, v102, v238, s[34:35]
	v_cndmask_b32_e64 v103, v103, v239, s[34:35]
	s_waitcnt vmcnt(14)
;     __device__ __forceinline__ void operator()(const f32x4 (&acc)[2][2][4][2], const Unit& u, int wr, int wc, int fr, int fq) const {
;     ...
; #pragma unroll
;         for (int ai = 0; ai < 2; ++ai)
; #pragma unroll
;             for (int m = 0; m < 4; ++m) {
;                 const int row = row0 + ai * HALF + m * 16;
;                 const size_t off = (size_t)row * ldc + col0;
;                 float q = 0.f;
; #pragma unroll
;                 for (int bj = 0; bj < 2; ++bj)
; #pragma unroll
;                     for (int n = 0; n < 2; ++n) {
;                         const f32x4 rv = *(const f32x4*)(rbase + off + bj * HALF + n * 16);
;                         const f32x4 v = rv + acc[ai][bj][m][n] * scale;
;                         if (out) *(f32x4*)(out + off + bj * HALF + n * 16) = v;
;                         if (xn) { q += (v.x * v.x + v.y * v.y) + (v.z * v.z + v.w * v.w); const f32x4 o = v * wv[bj][n];
;                             u32x2 p; p.x = pk2(o.x, o.y); p.y = pk2(o.z, o.w); *(u32x2*)(xn + off + bj * HALF + n * 16) = p; }
;                     }
;                 if (xn) { q += __shfl_xor(q, 16); q += __shfl_xor(q, 32); if (fq == 0) (void)__hip_atomic_fetch_add(ss + row, q, __ATOMIC_RELAXED, __HIP_MEMORY_SCOPE_AGENT); }
	v_pk_add_f32 v[106:107], v[106:107], v[158:159]
	v_pk_add_f32 v[104:105], v[104:105], v[156:157]
	global_store_dwordx4 v[218:219], v[104:107], off
	v_pk_mul_f32 v[224:225], v[64:65], v[104:105]
	v_pk_mul_f32 v[226:227], v[66:67], v[106:107]
	v_mul_f32_e32 v173, v104, v104
	v_fmac_f32_e32 v173, v105, v105
	v_fmac_f32_e32 v173, v106, v106
	v_fmac_f32_e32 v173, v107, v107
	v_cvt_pk_bf16_f32 v222, v224, v225
	v_cvt_pk_bf16_f32 v223, v226, v227
	global_store_dwordx2 v[202:203], v[222:223], off
	v_pk_add_f32 v[98:99], v[98:99], v[162:163]
	v_pk_add_f32 v[96:97], v[96:97], v[160:161]
	global_store_dwordx4 v[218:219], v[96:99], off offset:512
	v_pk_mul_f32 v[228:229], v[72:73], v[96:97]
	v_pk_mul_f32 v[230:231], v[74:75], v[98:99]
	v_fmac_f32_e32 v173, v96, v96
	v_fmac_f32_e32 v173, v97, v97
	v_fmac_f32_e32 v173, v98, v98
	v_fmac_f32_e32 v173, v99, v99
	v_cvt_pk_bf16_f32 v232, v228, v229
	v_cvt_pk_bf16_f32 v233, v230, v231
	global_store_dwordx2 v[202:203], v[232:233], off offset:256
	v_pk_add_f32 v[110:111], v[110:111], v[178:179]
	v_pk_add_f32 v[108:109], v[108:109], v[176:177]
	global_store_dwordx4 v[220:221], v[108:111], off
	v_pk_mul_f32 v[224:225], v[76:77], v[108:109]
	v_pk_mul_f32 v[226:227], v[78:79], v[110:111]
	v_mul_f32_e32 v234, v108, v108
	v_fmac_f32_e32 v234, v109, v109
	v_fmac_f32_e32 v234, v110, v110
	v_fmac_f32_e32 v234, v111, v111
	v_cvt_pk_bf16_f32 v222, v224, v225
	v_cvt_pk_bf16_f32 v223, v226, v227
	global_store_dwordx2 v[204:205], v[222:223], off
	v_pk_add_f32 v[102:103], v[102:103], v[182:183]
	v_pk_add_f32 v[100:101], v[100:101], v[180:181]
	global_store_dwordx4 v[220:221], v[100:103], off offset:512
	v_pk_mul_f32 v[228:229], v[84:85], v[100:101]
	v_pk_mul_f32 v[230:231], v[86:87], v[102:103]
	v_fmac_f32_e32 v234, v100, v100
	v_fmac_f32_e32 v234, v101, v101
	v_fmac_f32_e32 v234, v102, v102
	v_fmac_f32_e32 v234, v103, v103
	v_cvt_pk_bf16_f32 v232, v228, v229
	v_cvt_pk_bf16_f32 v233, v230, v231
	global_store_dwordx2 v[204:205], v[232:233], off offset:256
	s_nop 1
	v_mov_b32_dpp v241, v173 row_ror:8 row_mask:0xf bank_mask:0xf
	v_mov_b32_dpp v242, v234 row_ror:8 row_mask:0xf bank_mask:0xf
	v_add_f32_e32 v173, v173, v241
	v_add_f32_e32 v234, v234, v242
	v_cndmask_b32_e64 v173, v234, v173, s[34:35]
	s_nop 0
	ds_bpermute_b32 v241, v235, v173
	global_load_dwordx4 v[156:159], v[174:175], off
	global_load_dwordx4 v[160:163], v[174:175], off offset:512
	global_load_dwordx4 v[176:179], v[200:201], off
	global_load_dwordx4 v[180:183], v[200:201], off offset:512
	s_mov_b64 vcc, 0x20000
	v_lshl_add_u64 v[174:175], v[174:175], 0, vcc
	v_lshl_add_u64 v[200:201], v[200:201], 0, vcc
	s_mov_b64 vcc, 0x20000
	v_lshl_add_u64 v[218:219], v[218:219], 0, vcc
	v_lshl_add_u64 v[220:221], v[220:221], 0, vcc
	s_mov_b64 vcc, 0x10000
	v_lshl_add_u64 v[202:203], v[202:203], 0, vcc
	v_lshl_add_u64 v[204:205], v[204:205], 0, vcc
	s_waitcnt lgkmcnt(0)
	v_add_f32_e32 v173, v173, v241
	s_nop 0
	ds_bpermute_b32 v242, v240, v173
	s_waitcnt lgkmcnt(0)
	v_add_f32_e32 v173, v173, v242
	s_mov_b64 exec, s[0:1]
	global_atomic_add_f32 v[206:207], v173, off
	s_mov_b64 exec, -1
	s_mov_b64 vcc, 64
	v_lshl_add_u64 v[206:207], v[206:207], 0, vcc
	v_mov_b32_dpp v236, v88 row_ror:8 row_mask:0xf bank_mask:0xf
	v_mov_b32_dpp v237, v89 row_ror:8 row_mask:0xf bank_mask:0xf
	v_mov_b32_dpp v238, v90 row_ror:8 row_mask:0xf bank_mask:0xf
	v_mov_b32_dpp v239, v91 row_ror:8 row_mask:0xf bank_mask:0xf
	v_cndmask_b32_e64 v88, v236, v92, s[34:35]
	v_cndmask_b32_e64 v89, v237, v93, s[34:35]
	v_cndmask_b32_e64 v90, v238, v94, s[34:35]
	v_cndmask_b32_e64 v91, v239, v95, s[34:35]
	v_cndmask_b32_e64 v92, v92, v236, s[34:35]
	v_cndmask_b32_e64 v93, v93, v237, s[34:35]
	v_cndmask_b32_e64 v94, v94, v238, s[34:35]
	v_cndmask_b32_e64 v95, v95, v239, s[34:35]
	v_mov_b32_dpp v236, v68 row_ror:8 row_mask:0xf bank_mask:0xf
	v_mov_b32_dpp v237, v69 row_ror:8 row_mask:0xf bank_mask:0xf
	v_mov_b32_dpp v238, v70 row_ror:8 row_mask:0xf bank_mask:0xf
	v_mov_b32_dpp v239, v71 row_ror:8 row_mask:0xf bank_mask:0xf
	v_cndmask_b32_e64 v68, v236, v80, s[34:35]
	v_cndmask_b32_e64 v69, v237, v81, s[34:35]
	v_cndmask_b32_e64 v70, v238, v82, s[34:35]
	v_cndmask_b32_e64 v71, v239, v83, s[34:35]
	v_cndmask_b32_e64 v80, v80, v236, s[34:35]
	v_cndmask_b32_e64 v81, v81, v237, s[34:35]
	v_cndmask_b32_e64 v82, v82, v238, s[34:35]
	v_cndmask_b32_e64 v83, v83, v239, s[34:35]
	s_waitcnt vmcnt(14)
;     __device__ __forceinline__ void operator()(const f32x4 (&acc)[2][2][4][2], const Unit& u, int wr, int wc, int fr, int fq) const {
;     ...
; #pragma unroll
;         for (int ai = 0; ai < 2; ++ai)
; #pragma unroll
;             for (int m = 0; m < 4; ++m) {
;                 const int row = row0 + ai * HALF + m * 16;
;                 const size_t off = (size_t)row * ldc + col0;
;                 float q = 0.f;
; #pragma unroll
;                 for (int bj = 0; bj < 2; ++bj)
; #pragma unroll
;                     for (int n = 0; n < 2; ++n) {
;                         const f32x4 rv = *(const f32x4*)(rbase + off + bj * HALF + n * 16);
;                         const f32x4 v = rv + acc[ai][bj][m][n] * scale;
;                         if (out) *(f32x4*)(out + off + bj * HALF + n * 16) = v;
;                         if (xn) { q += (v.x * v.x + v.y * v.y) + (v.z * v.z + v.w * v.w); const f32x4 o = v * wv[bj][n];
;                             u32x2 p; p.x = pk2(o.x, o.y); p.y = pk2(o.z, o.w); *(u32x2*)(xn + off + bj * HALF + n * 16) = p; }
;                     }
;                 if (xn) { q += __shfl_xor(q, 16); q += __shfl_xor(q, 32); if (fq == 0) (void)__hip_atomic_fetch_add(ss + row, q, __ATOMIC_RELAXED, __HIP_MEMORY_SCOPE_AGENT); }
;             }
	v_pk_add_f32 v[90:91], v[90:91], v[186:187]
	v_pk_add_f32 v[88:89], v[88:89], v[184:185]
	global_store_dwordx4 v[218:219], v[88:91], off
	v_pk_mul_f32 v[224:225], v[64:65], v[88:89]
	v_pk_mul_f32 v[226:227], v[66:67], v[90:91]
	v_mul_f32_e32 v173, v88, v88
	v_fmac_f32_e32 v173, v89, v89
	v_fmac_f32_e32 v173, v90, v90
	v_fmac_f32_e32 v173, v91, v91
	v_cvt_pk_bf16_f32 v222, v224, v225
	v_cvt_pk_bf16_f32 v223, v226, v227
	global_store_dwordx2 v[202:203], v[222:223], off
	v_pk_add_f32 v[70:71], v[70:71], v[190:191]
	v_pk_add_f32 v[68:69], v[68:69], v[188:189]
	global_store_dwordx4 v[218:219], v[68:71], off offset:512
	v_pk_mul_f32 v[228:229], v[72:73], v[68:69]
	v_pk_mul_f32 v[230:231], v[74:75], v[70:71]
	v_fmac_f32_e32 v173, v68, v68
	v_fmac_f32_e32 v173, v69, v69
	v_fmac_f32_e32 v173, v70, v70
	v_fmac_f32_e32 v173, v71, v71
	v_cvt_pk_bf16_f32 v232, v228, v229
	v_cvt_pk_bf16_f32 v233, v230, v231
	global_store_dwordx2 v[202:203], v[232:233], off offset:256
	v_pk_add_f32 v[94:95], v[94:95], v[194:195]
	v_pk_add_f32 v[92:93], v[92:93], v[192:193]
	global_store_dwordx4 v[220:221], v[92:95], off
	v_pk_mul_f32 v[224:225], v[76:77], v[92:93]
	v_pk_mul_f32 v[226:227], v[78:79], v[94:95]
	v_mul_f32_e32 v234, v92, v92
	v_fmac_f32_e32 v234, v93, v93
	v_fmac_f32_e32 v234, v94, v94
	v_fmac_f32_e32 v234, v95, v95
	v_cvt_pk_bf16_f32 v222, v224, v225
	v_cvt_pk_bf16_f32 v223, v226, v227
	global_store_dwordx2 v[204:205], v[222:223], off
	v_pk_add_f32 v[82:83], v[82:83], v[198:199]
	v_pk_add_f32 v[80:81], v[80:81], v[196:197]
	global_store_dwordx4 v[220:221], v[80:83], off offset:512
	v_pk_mul_f32 v[228:229], v[84:85], v[80:81]
	v_pk_mul_f32 v[230:231], v[86:87], v[82:83]
	v_fmac_f32_e32 v234, v80, v80
	v_fmac_f32_e32 v234, v81, v81
	v_fmac_f32_e32 v234, v82, v82
	v_fmac_f32_e32 v234, v83, v83
	v_cvt_pk_bf16_f32 v232, v228, v229
	v_cvt_pk_bf16_f32 v233, v230, v231
	global_store_dwordx2 v[204:205], v[232:233], off offset:256
	s_nop 1
	v_mov_b32_dpp v241, v173 row_ror:8 row_mask:0xf bank_mask:0xf
	v_mov_b32_dpp v242, v234 row_ror:8 row_mask:0xf bank_mask:0xf
	v_add_f32_e32 v173, v173, v241
	v_add_f32_e32 v234, v234, v242
	v_cndmask_b32_e64 v173, v234, v173, s[34:35]
	s_nop 0
	ds_bpermute_b32 v241, v235, v173
	global_load_dwordx4 v[184:187], v[174:175], off
	global_load_dwordx4 v[188:191], v[174:175], off offset:512
	global_load_dwordx4 v[192:195], v[200:201], off
	global_load_dwordx4 v[196:199], v[200:201], off offset:512
	s_mov_b64 vcc, 0x20000
	v_lshl_add_u64 v[174:175], v[174:175], 0, vcc
	v_lshl_add_u64 v[200:201], v[200:201], 0, vcc
	s_mov_b64 vcc, 0xa0000
	v_lshl_add_u64 v[218:219], v[218:219], 0, vcc
	v_lshl_add_u64 v[220:221], v[220:221], 0, vcc
	s_mov_b64 vcc, 0x50000
	v_lshl_add_u64 v[202:203], v[202:203], 0, vcc
	v_lshl_add_u64 v[204:205], v[204:205], 0, vcc
	s_waitcnt lgkmcnt(0)
	v_add_f32_e32 v173, v173, v241
	s_nop 0
	ds_bpermute_b32 v242, v240, v173
	s_waitcnt lgkmcnt(0)
	v_add_f32_e32 v173, v173, v242
	s_mov_b64 exec, s[0:1]
	global_atomic_add_f32 v[206:207], v173, off
	s_mov_b64 exec, -1
	s_mov_b64 vcc, 320
	v_lshl_add_u64 v[206:207], v[206:207], 0, vcc
	v_mov_b32_dpp v236, v56 row_ror:8 row_mask:0xf bank_mask:0xf
	v_mov_b32_dpp v237, v57 row_ror:8 row_mask:0xf bank_mask:0xf
	v_mov_b32_dpp v238, v58 row_ror:8 row_mask:0xf bank_mask:0xf
	v_mov_b32_dpp v239, v59 row_ror:8 row_mask:0xf bank_mask:0xf
	v_cndmask_b32_e64 v56, v236, v60, s[34:35]
	v_cndmask_b32_e64 v57, v237, v61, s[34:35]
	v_cndmask_b32_e64 v58, v238, v62, s[34:35]
	v_cndmask_b32_e64 v59, v239, v63, s[34:35]
	v_cndmask_b32_e64 v60, v60, v236, s[34:35]
	v_cndmask_b32_e64 v61, v61, v237, s[34:35]
	v_cndmask_b32_e64 v62, v62, v238, s[34:35]
	v_cndmask_b32_e64 v63, v63, v239, s[34:35]
	v_mov_b32_dpp v236, v48 row_ror:8 row_mask:0xf bank_mask:0xf
	v_mov_b32_dpp v237, v49 row_ror:8 row_mask:0xf bank_mask:0xf
	v_mov_b32_dpp v238, v50 row_ror:8 row_mask:0xf bank_mask:0xf
	v_mov_b32_dpp v239, v51 row_ror:8 row_mask:0xf bank_mask:0xf
	v_cndmask_b32_e64 v48, v236, v52, s[34:35]
	v_cndmask_b32_e64 v49, v237, v53, s[34:35]
	v_cndmask_b32_e64 v50, v238, v54, s[34:35]
	v_cndmask_b32_e64 v51, v239, v55, s[34:35]
	v_cndmask_b32_e64 v52, v52, v236, s[34:35]
	v_cndmask_b32_e64 v53, v53, v237, s[34:35]
	v_cndmask_b32_e64 v54, v54, v238, s[34:35]
	v_cndmask_b32_e64 v55, v55, v239, s[34:35]
	s_waitcnt vmcnt(14)
;     __device__ __forceinline__ void operator()(const f32x4 (&acc)[2][2][4][2], const Unit& u, int wr, int wc, int fr, int fq) const {
;     ...
; #pragma unroll
;         for (int ai = 0; ai < 2; ++ai)
; #pragma unroll
;             for (int m = 0; m < 4; ++m) {
;                 const int row = row0 + ai * HALF + m * 16;
;                 const size_t off = (size_t)row * ldc + col0;
;                 float q = 0.f;
; #pragma unroll
;                 for (int bj = 0; bj < 2; ++bj)
; #pragma unroll
;                     for (int n = 0; n < 2; ++n) {
;                         const f32x4 rv = *(const f32x4*)(rbase + off + bj * HALF + n * 16);
;                         const f32x4 v = rv + acc[ai][bj][m][n] * scale;
;                         if (out) *(f32x4*)(out + off + bj * HALF + n * 16) = v;
;                         if (xn) { q += (v.x * v.x + v.y * v.y) + (v.z * v.z + v.w * v.w); const f32x4 o = v * wv[bj][n];
;                             u32x2 p; p.x = pk2(o.x, o.y); p.y = pk2(o.z, o.w); *(u32x2*)(xn + off + bj * HALF + n * 16) = p; }
;                     }
;                 if (xn) { q += __shfl_xor(q, 16); q += __shfl_xor(q, 32); if (fq == 0) (void)__hip_atomic_fetch_add(ss + row, q, __ATOMIC_RELAXED, __HIP_MEMORY_SCOPE_AGENT); }
;             }
	v_pk_add_f32 v[58:59], v[58:59], v[158:159]
	v_pk_add_f32 v[56:57], v[56:57], v[156:157]
	global_store_dwordx4 v[218:219], v[56:59], off
	v_pk_mul_f32 v[224:225], v[64:65], v[56:57]
	v_pk_mul_f32 v[226:227], v[66:67], v[58:59]
	v_mul_f32_e32 v173, v56, v56
	v_fmac_f32_e32 v173, v57, v57
	v_fmac_f32_e32 v173, v58, v58
	v_fmac_f32_e32 v173, v59, v59
	v_cvt_pk_bf16_f32 v222, v224, v225
	v_cvt_pk_bf16_f32 v223, v226, v227
	global_store_dwordx2 v[202:203], v[222:223], off
	v_pk_add_f32 v[50:51], v[50:51], v[162:163]
	v_pk_add_f32 v[48:49], v[48:49], v[160:161]
	global_store_dwordx4 v[218:219], v[48:51], off offset:512
	v_pk_mul_f32 v[228:229], v[72:73], v[48:49]
	v_pk_mul_f32 v[230:231], v[74:75], v[50:51]
	v_fmac_f32_e32 v173, v48, v48
	v_fmac_f32_e32 v173, v49, v49
	v_fmac_f32_e32 v173, v50, v50
	v_fmac_f32_e32 v173, v51, v51
	v_cvt_pk_bf16_f32 v232, v228, v229
	v_cvt_pk_bf16_f32 v233, v230, v231
	global_store_dwordx2 v[202:203], v[232:233], off offset:256
	v_pk_add_f32 v[62:63], v[62:63], v[178:179]
	v_pk_add_f32 v[60:61], v[60:61], v[176:177]
	global_store_dwordx4 v[220:221], v[60:63], off
	v_pk_mul_f32 v[224:225], v[76:77], v[60:61]
	v_pk_mul_f32 v[226:227], v[78:79], v[62:63]
	v_mul_f32_e32 v234, v60, v60
	v_fmac_f32_e32 v234, v61, v61
	v_fmac_f32_e32 v234, v62, v62
	v_fmac_f32_e32 v234, v63, v63
	v_cvt_pk_bf16_f32 v222, v224, v225
	v_cvt_pk_bf16_f32 v223, v226, v227
	global_store_dwordx2 v[204:205], v[222:223], off
	v_pk_add_f32 v[54:55], v[54:55], v[182:183]
	v_pk_add_f32 v[52:53], v[52:53], v[180:181]
	global_store_dwordx4 v[220:221], v[52:55], off offset:512
	v_pk_mul_f32 v[228:229], v[84:85], v[52:53]
	v_pk_mul_f32 v[230:231], v[86:87], v[54:55]
	v_fmac_f32_e32 v234, v52, v52
	v_fmac_f32_e32 v234, v53, v53
	v_fmac_f32_e32 v234, v54, v54
	v_fmac_f32_e32 v234, v55, v55
	v_cvt_pk_bf16_f32 v232, v228, v229
	v_cvt_pk_bf16_f32 v233, v230, v231
	global_store_dwordx2 v[204:205], v[232:233], off offset:256
	s_nop 1
	v_mov_b32_dpp v241, v173 row_ror:8 row_mask:0xf bank_mask:0xf
	v_mov_b32_dpp v242, v234 row_ror:8 row_mask:0xf bank_mask:0xf
	v_add_f32_e32 v173, v173, v241
	v_add_f32_e32 v234, v234, v242
	v_cndmask_b32_e64 v173, v234, v173, s[34:35]
	s_nop 0
	ds_bpermute_b32 v241, v235, v173
	global_load_dwordx4 v[156:159], v[174:175], off
	global_load_dwordx4 v[160:163], v[174:175], off offset:512
	global_load_dwordx4 v[176:179], v[200:201], off
	global_load_dwordx4 v[180:183], v[200:201], off offset:512
	s_mov_b64 vcc, 0x20000
	v_lshl_add_u64 v[174:175], v[174:175], 0, vcc
	v_lshl_add_u64 v[200:201], v[200:201], 0, vcc
	s_mov_b64 vcc, 0x20000
	v_lshl_add_u64 v[218:219], v[218:219], 0, vcc
	v_lshl_add_u64 v[220:221], v[220:221], 0, vcc
	s_mov_b64 vcc, 0x10000
	v_lshl_add_u64 v[202:203], v[202:203], 0, vcc
	v_lshl_add_u64 v[204:205], v[204:205], 0, vcc
	s_waitcnt lgkmcnt(0)
	v_add_f32_e32 v173, v173, v241
	s_nop 0
	ds_bpermute_b32 v242, v240, v173
	s_waitcnt lgkmcnt(0)
	v_add_f32_e32 v173, v173, v242
	s_mov_b64 exec, s[0:1]
	global_atomic_add_f32 v[206:207], v173, off
	s_mov_b64 exec, -1
	s_mov_b64 vcc, 64
	v_lshl_add_u64 v[206:207], v[206:207], 0, vcc
	v_mov_b32_dpp v236, v40 row_ror:8 row_mask:0xf bank_mask:0xf
	v_mov_b32_dpp v237, v41 row_ror:8 row_mask:0xf bank_mask:0xf
	v_mov_b32_dpp v238, v42 row_ror:8 row_mask:0xf bank_mask:0xf
	v_mov_b32_dpp v239, v43 row_ror:8 row_mask:0xf bank_mask:0xf
	v_cndmask_b32_e64 v40, v236, v44, s[34:35]
	v_cndmask_b32_e64 v41, v237, v45, s[34:35]
	v_cndmask_b32_e64 v42, v238, v46, s[34:35]
	v_cndmask_b32_e64 v43, v239, v47, s[34:35]
	v_cndmask_b32_e64 v44, v44, v236, s[34:35]
	v_cndmask_b32_e64 v45, v45, v237, s[34:35]
	v_cndmask_b32_e64 v46, v46, v238, s[34:35]
	v_cndmask_b32_e64 v47, v47, v239, s[34:35]
	v_mov_b32_dpp v236, v32 row_ror:8 row_mask:0xf bank_mask:0xf
	v_mov_b32_dpp v237, v33 row_ror:8 row_mask:0xf bank_mask:0xf
	v_mov_b32_dpp v238, v34 row_ror:8 row_mask:0xf bank_mask:0xf
	v_mov_b32_dpp v239, v35 row_ror:8 row_mask:0xf bank_mask:0xf
	v_cndmask_b32_e64 v32, v236, v36, s[34:35]
	v_cndmask_b32_e64 v33, v237, v37, s[34:35]
	v_cndmask_b32_e64 v34, v238, v38, s[34:35]
	v_cndmask_b32_e64 v35, v239, v39, s[34:35]
	v_cndmask_b32_e64 v36, v36, v236, s[34:35]
	v_cndmask_b32_e64 v37, v37, v237, s[34:35]
	v_cndmask_b32_e64 v38, v38, v238, s[34:35]
	v_cndmask_b32_e64 v39, v39, v239, s[34:35]
	s_waitcnt vmcnt(14)
;     __device__ __forceinline__ void operator()(const f32x4 (&acc)[2][2][4][2], const Unit& u, int wr, int wc, int fr, int fq) const {
;     ...
; #pragma unroll
;         for (int ai = 0; ai < 2; ++ai)
; #pragma unroll
;             for (int m = 0; m < 4; ++m) {
;                 const int row = row0 + ai * HALF + m * 16;
;                 const size_t off = (size_t)row * ldc + col0;
;                 float q = 0.f;
; #pragma unroll
;                 for (int bj = 0; bj < 2; ++bj)
; #pragma unroll
;                     for (int n = 0; n < 2; ++n) {
;                         const f32x4 rv = *(const f32x4*)(rbase + off + bj * HALF + n * 16);
;                         const f32x4 v = rv + acc[ai][bj][m][n] * scale;
;                         if (out) *(f32x4*)(out + off + bj * HALF + n * 16) = v;
;                         if (xn) { q += (v.x * v.x + v.y * v.y) + (v.z * v.z + v.w * v.w); const f32x4 o = v * wv[bj][n];
;                             u32x2 p; p.x = pk2(o.x, o.y); p.y = pk2(o.z, o.w); *(u32x2*)(xn + off + bj * HALF + n * 16) = p; }
;                     }
;                 if (xn) { q += __shfl_xor(q, 16); q += __shfl_xor(q, 32); if (fq == 0) (void)__hip_atomic_fetch_add(ss + row, q, __ATOMIC_RELAXED, __HIP_MEMORY_SCOPE_AGENT); }
;             }
	v_pk_add_f32 v[42:43], v[42:43], v[186:187]
	v_pk_add_f32 v[40:41], v[40:41], v[184:185]
	global_store_dwordx4 v[218:219], v[40:43], off
	v_pk_mul_f32 v[224:225], v[64:65], v[40:41]
	v_pk_mul_f32 v[226:227], v[66:67], v[42:43]
	v_mul_f32_e32 v173, v40, v40
	v_fmac_f32_e32 v173, v41, v41
	v_fmac_f32_e32 v173, v42, v42
	v_fmac_f32_e32 v173, v43, v43
	v_cvt_pk_bf16_f32 v222, v224, v225
	v_cvt_pk_bf16_f32 v223, v226, v227
	global_store_dwordx2 v[202:203], v[222:223], off
	v_pk_add_f32 v[34:35], v[34:35], v[190:191]
	v_pk_add_f32 v[32:33], v[32:33], v[188:189]
	global_store_dwordx4 v[218:219], v[32:35], off offset:512
	v_pk_mul_f32 v[228:229], v[72:73], v[32:33]
	v_pk_mul_f32 v[230:231], v[74:75], v[34:35]
	v_fmac_f32_e32 v173, v32, v32
	v_fmac_f32_e32 v173, v33, v33
	v_fmac_f32_e32 v173, v34, v34
	v_fmac_f32_e32 v173, v35, v35
	v_cvt_pk_bf16_f32 v232, v228, v229
	v_cvt_pk_bf16_f32 v233, v230, v231
	global_store_dwordx2 v[202:203], v[232:233], off offset:256
	v_pk_add_f32 v[46:47], v[46:47], v[194:195]
	v_pk_add_f32 v[44:45], v[44:45], v[192:193]
	global_store_dwordx4 v[220:221], v[44:47], off
	v_pk_mul_f32 v[224:225], v[76:77], v[44:45]
	v_pk_mul_f32 v[226:227], v[78:79], v[46:47]
	v_mul_f32_e32 v234, v44, v44
	v_fmac_f32_e32 v234, v45, v45
	v_fmac_f32_e32 v234, v46, v46
	v_fmac_f32_e32 v234, v47, v47
	v_cvt_pk_bf16_f32 v222, v224, v225
	v_cvt_pk_bf16_f32 v223, v226, v227
	global_store_dwordx2 v[204:205], v[222:223], off
	v_pk_add_f32 v[38:39], v[38:39], v[198:199]
	v_pk_add_f32 v[36:37], v[36:37], v[196:197]
	global_store_dwordx4 v[220:221], v[36:39], off offset:512
	v_pk_mul_f32 v[228:229], v[84:85], v[36:37]
	v_pk_mul_f32 v[230:231], v[86:87], v[38:39]
	v_fmac_f32_e32 v234, v36, v36
	v_fmac_f32_e32 v234, v37, v37
	v_fmac_f32_e32 v234, v38, v38
	v_fmac_f32_e32 v234, v39, v39
	v_cvt_pk_bf16_f32 v232, v228, v229
	v_cvt_pk_bf16_f32 v233, v230, v231
	global_store_dwordx2 v[204:205], v[232:233], off offset:256
	s_nop 1
	v_mov_b32_dpp v241, v173 row_ror:8 row_mask:0xf bank_mask:0xf
	v_mov_b32_dpp v242, v234 row_ror:8 row_mask:0xf bank_mask:0xf
	v_add_f32_e32 v173, v173, v241
	v_add_f32_e32 v234, v234, v242
	v_cndmask_b32_e64 v173, v234, v173, s[34:35]
	s_nop 0
	ds_bpermute_b32 v241, v235, v173
	global_load_dwordx4 v[184:187], v[174:175], off
	global_load_dwordx4 v[188:191], v[174:175], off offset:512
	global_load_dwordx4 v[192:195], v[200:201], off
	global_load_dwordx4 v[196:199], v[200:201], off offset:512
	s_mov_b64 vcc, 0x20000
	v_lshl_add_u64 v[218:219], v[218:219], 0, vcc
	v_lshl_add_u64 v[220:221], v[220:221], 0, vcc
	s_mov_b64 vcc, 0x10000
	v_lshl_add_u64 v[202:203], v[202:203], 0, vcc
	v_lshl_add_u64 v[204:205], v[204:205], 0, vcc
	s_waitcnt lgkmcnt(0)
	v_add_f32_e32 v173, v173, v241
	s_nop 0
	ds_bpermute_b32 v242, v240, v173
	s_waitcnt lgkmcnt(0)
	v_add_f32_e32 v173, v173, v242
	s_mov_b64 exec, s[0:1]
	global_atomic_add_f32 v[206:207], v173, off
	s_mov_b64 exec, -1
	s_mov_b64 vcc, 64
	v_lshl_add_u64 v[206:207], v[206:207], 0, vcc
	v_mov_b32_dpp v236, v24 row_ror:8 row_mask:0xf bank_mask:0xf
	v_mov_b32_dpp v237, v25 row_ror:8 row_mask:0xf bank_mask:0xf
	v_mov_b32_dpp v238, v26 row_ror:8 row_mask:0xf bank_mask:0xf
	v_mov_b32_dpp v239, v27 row_ror:8 row_mask:0xf bank_mask:0xf
	v_cndmask_b32_e64 v24, v236, v28, s[34:35]
	v_cndmask_b32_e64 v25, v237, v29, s[34:35]
	v_cndmask_b32_e64 v26, v238, v30, s[34:35]
	v_cndmask_b32_e64 v27, v239, v31, s[34:35]
	v_cndmask_b32_e64 v28, v28, v236, s[34:35]
	v_cndmask_b32_e64 v29, v29, v237, s[34:35]
	v_cndmask_b32_e64 v30, v30, v238, s[34:35]
	v_cndmask_b32_e64 v31, v31, v239, s[34:35]
	v_mov_b32_dpp v236, v16 row_ror:8 row_mask:0xf bank_mask:0xf
	v_mov_b32_dpp v237, v17 row_ror:8 row_mask:0xf bank_mask:0xf
	v_mov_b32_dpp v238, v18 row_ror:8 row_mask:0xf bank_mask:0xf
	v_mov_b32_dpp v239, v19 row_ror:8 row_mask:0xf bank_mask:0xf
	v_cndmask_b32_e64 v16, v236, v20, s[34:35]
	v_cndmask_b32_e64 v17, v237, v21, s[34:35]
	v_cndmask_b32_e64 v18, v238, v22, s[34:35]
	v_cndmask_b32_e64 v19, v239, v23, s[34:35]
	v_cndmask_b32_e64 v20, v20, v236, s[34:35]
	v_cndmask_b32_e64 v21, v21, v237, s[34:35]
	v_cndmask_b32_e64 v22, v22, v238, s[34:35]
	v_cndmask_b32_e64 v23, v23, v239, s[34:35]
	s_waitcnt vmcnt(14)
; #define PG8_BAR __builtin_amdgcn_s_barrier()
;     __device__ __forceinline__ void operator()(const f32x4 (&acc)[2][2][4][2], const Unit& u, int wr, int wc, int fr, int fq) const {
;     ...
; #pragma unroll
;         for (int ai = 0; ai < 2; ++ai)
; #pragma unroll
;             for (int m = 0; m < 4; ++m) {
;                 const int row = row0 + ai * HALF + m * 16;
;                 const size_t off = (size_t)row * ldc + col0;
;                 float q = 0.f;
; #pragma unroll
;                 for (int bj = 0; bj < 2; ++bj)
; #pragma unroll
;                     for (int n = 0; n < 2; ++n) {
;                         const f32x4 rv = *(const f32x4*)(rbase + off + bj * HALF + n * 16);
;                         const f32x4 v = rv + acc[ai][bj][m][n] * scale;
;                         if (out) *(f32x4*)(out + off + bj * HALF + n * 16) = v;
;                         if (xn) { q += (v.x * v.x + v.y * v.y) + (v.z * v.z + v.w * v.w); const f32x4 o = v * wv[bj][n];
;                             u32x2 p; p.x = pk2(o.x, o.y); p.y = pk2(o.z, o.w); *(u32x2*)(xn + off + bj * HALF + n * 16) = p; }
;                     }
;                 if (xn) { q += __shfl_xor(q, 16); q += __shfl_xor(q, 32); if (fq == 0) (void)__hip_atomic_fetch_add(ss + row, q, __ATOMIC_RELAXED, __HIP_MEMORY_SCOPE_AGENT); }
;             }
; template <class Epi, bool ALIGN_EPI>
; __device__ __forceinline__ void gemm_phase(LAS unsigned char* lds, const Gemm g, const StaticOrder& S, const Epi& E) {
;     ...
;         if (!has_next) break;
; #pragma unroll
;         for (int a = 0; a < 2; ++a)
; #pragma unroll
;             for (int b = 0; b < 2; ++b)
; #pragma unroll
;                 for (int m = 0; m < 4; ++m)
; #pragma unroll
;                     for (int n = 0; n < 2; ++n) acc[a][b][m][n] = (f32x4){0.f, 0.f, 0.f, 0.f};
;         cur = nxt; cA = nA; cB = nB; ++ui;
;         if constexpr (ALIGN_EPI) { if (wr == 1) PG8_BAR; }
	v_pk_add_f32 v[26:27], v[26:27], v[158:159]
	v_pk_add_f32 v[24:25], v[24:25], v[156:157]
	global_store_dwordx4 v[218:219], v[24:27], off
	v_pk_mul_f32 v[224:225], v[64:65], v[24:25]
	v_pk_mul_f32 v[226:227], v[66:67], v[26:27]
	v_mul_f32_e32 v173, v24, v24
	v_fmac_f32_e32 v173, v25, v25
	v_fmac_f32_e32 v173, v26, v26
	v_fmac_f32_e32 v173, v27, v27
	v_cvt_pk_bf16_f32 v222, v224, v225
	v_cvt_pk_bf16_f32 v223, v226, v227
	global_store_dwordx2 v[202:203], v[222:223], off
	v_pk_add_f32 v[18:19], v[18:19], v[162:163]
	v_pk_add_f32 v[16:17], v[16:17], v[160:161]
	global_store_dwordx4 v[218:219], v[16:19], off offset:512
	v_pk_mul_f32 v[228:229], v[72:73], v[16:17]
	v_pk_mul_f32 v[230:231], v[74:75], v[18:19]
	v_fmac_f32_e32 v173, v16, v16
	v_fmac_f32_e32 v173, v17, v17
	v_fmac_f32_e32 v173, v18, v18
	v_fmac_f32_e32 v173, v19, v19
	v_cvt_pk_bf16_f32 v232, v228, v229
	v_cvt_pk_bf16_f32 v233, v230, v231
	global_store_dwordx2 v[202:203], v[232:233], off offset:256
	v_pk_add_f32 v[30:31], v[30:31], v[178:179]
	v_pk_add_f32 v[28:29], v[28:29], v[176:177]
	global_store_dwordx4 v[220:221], v[28:31], off
	v_pk_mul_f32 v[224:225], v[76:77], v[28:29]
	v_pk_mul_f32 v[226:227], v[78:79], v[30:31]
	v_mul_f32_e32 v234, v28, v28
	v_fmac_f32_e32 v234, v29, v29
	v_fmac_f32_e32 v234, v30, v30
	v_fmac_f32_e32 v234, v31, v31
	v_cvt_pk_bf16_f32 v222, v224, v225
	v_cvt_pk_bf16_f32 v223, v226, v227
	global_store_dwordx2 v[204:205], v[222:223], off
	v_pk_add_f32 v[22:23], v[22:23], v[182:183]
	v_pk_add_f32 v[20:21], v[20:21], v[180:181]
	global_store_dwordx4 v[220:221], v[20:23], off offset:512
	v_pk_mul_f32 v[228:229], v[84:85], v[20:21]
	v_pk_mul_f32 v[230:231], v[86:87], v[22:23]
	v_fmac_f32_e32 v234, v20, v20
	v_fmac_f32_e32 v234, v21, v21
	v_fmac_f32_e32 v234, v22, v22
	v_fmac_f32_e32 v234, v23, v23
	v_cvt_pk_bf16_f32 v232, v228, v229
	v_cvt_pk_bf16_f32 v233, v230, v231
	global_store_dwordx2 v[204:205], v[232:233], off offset:256
	s_nop 1
	v_mov_b32_dpp v241, v173 row_ror:8 row_mask:0xf bank_mask:0xf
	v_mov_b32_dpp v242, v234 row_ror:8 row_mask:0xf bank_mask:0xf
	v_add_f32_e32 v173, v173, v241
	v_add_f32_e32 v234, v234, v242
	v_cndmask_b32_e64 v173, v234, v173, s[34:35]
	s_nop 0
	ds_bpermute_b32 v241, v235, v173
	s_mov_b64 vcc, 0x20000
	v_lshl_add_u64 v[218:219], v[218:219], 0, vcc
	v_lshl_add_u64 v[220:221], v[220:221], 0, vcc
	s_mov_b64 vcc, 0x10000
	v_lshl_add_u64 v[202:203], v[202:203], 0, vcc
	v_lshl_add_u64 v[204:205], v[204:205], 0, vcc
	s_waitcnt lgkmcnt(0)
	v_add_f32_e32 v173, v173, v241
	s_nop 0
	ds_bpermute_b32 v242, v240, v173
	s_waitcnt lgkmcnt(0)
	v_add_f32_e32 v173, v173, v242
	s_mov_b64 exec, s[0:1]
	global_atomic_add_f32 v[206:207], v173, off
	s_mov_b64 exec, -1
	s_mov_b64 vcc, 64
	v_lshl_add_u64 v[206:207], v[206:207], 0, vcc
	v_mov_b32_dpp v236, v8 row_ror:8 row_mask:0xf bank_mask:0xf
	v_mov_b32_dpp v237, v9 row_ror:8 row_mask:0xf bank_mask:0xf
	v_mov_b32_dpp v238, v10 row_ror:8 row_mask:0xf bank_mask:0xf
	v_mov_b32_dpp v239, v11 row_ror:8 row_mask:0xf bank_mask:0xf
	v_cndmask_b32_e64 v8, v236, v12, s[34:35]
	v_cndmask_b32_e64 v9, v237, v13, s[34:35]
	v_cndmask_b32_e64 v10, v238, v14, s[34:35]
	v_cndmask_b32_e64 v11, v239, v15, s[34:35]
	v_cndmask_b32_e64 v12, v12, v236, s[34:35]
	v_cndmask_b32_e64 v13, v13, v237, s[34:35]
	v_cndmask_b32_e64 v14, v14, v238, s[34:35]
	v_cndmask_b32_e64 v15, v15, v239, s[34:35]
	v_mov_b32_dpp v236, v0 row_ror:8 row_mask:0xf bank_mask:0xf
	v_mov_b32_dpp v237, v1 row_ror:8 row_mask:0xf bank_mask:0xf
	v_mov_b32_dpp v238, v2 row_ror:8 row_mask:0xf bank_mask:0xf
	v_mov_b32_dpp v239, v3 row_ror:8 row_mask:0xf bank_mask:0xf
	v_cndmask_b32_e64 v0, v236, v4, s[34:35]
	v_cndmask_b32_e64 v1, v237, v5, s[34:35]
	v_cndmask_b32_e64 v2, v238, v6, s[34:35]
	v_cndmask_b32_e64 v3, v239, v7, s[34:35]
	v_cndmask_b32_e64 v4, v4, v236, s[34:35]
	v_cndmask_b32_e64 v5, v5, v237, s[34:35]
	v_cndmask_b32_e64 v6, v6, v238, s[34:35]
	v_cndmask_b32_e64 v7, v7, v239, s[34:35]
	s_waitcnt vmcnt(10)
	v_pk_add_f32 v[10:11], v[10:11], v[186:187]
	v_pk_add_f32 v[8:9], v[8:9], v[184:185]
	global_store_dwordx4 v[218:219], v[8:11], off
	v_pk_mul_f32 v[224:225], v[64:65], v[8:9]
	v_pk_mul_f32 v[226:227], v[66:67], v[10:11]
	v_mul_f32_e32 v173, v8, v8
	v_fmac_f32_e32 v173, v9, v9
	v_fmac_f32_e32 v173, v10, v10
	v_fmac_f32_e32 v173, v11, v11
	v_cvt_pk_bf16_f32 v222, v224, v225
	v_cvt_pk_bf16_f32 v223, v226, v227
	global_store_dwordx2 v[202:203], v[222:223], off
	v_pk_add_f32 v[2:3], v[2:3], v[190:191]
	v_pk_add_f32 v[0:1], v[0:1], v[188:189]
	global_store_dwordx4 v[218:219], v[0:3], off offset:512
	v_pk_mul_f32 v[228:229], v[72:73], v[0:1]
	v_pk_mul_f32 v[230:231], v[74:75], v[2:3]
	v_fmac_f32_e32 v173, v0, v0
	v_fmac_f32_e32 v173, v1, v1
	v_fmac_f32_e32 v173, v2, v2
	v_fmac_f32_e32 v173, v3, v3
	v_cvt_pk_bf16_f32 v232, v228, v229
	v_cvt_pk_bf16_f32 v233, v230, v231
	global_store_dwordx2 v[202:203], v[232:233], off offset:256
	v_pk_add_f32 v[14:15], v[14:15], v[194:195]
	v_pk_add_f32 v[12:13], v[12:13], v[192:193]
	global_store_dwordx4 v[220:221], v[12:15], off
	v_pk_mul_f32 v[224:225], v[76:77], v[12:13]
	v_pk_mul_f32 v[226:227], v[78:79], v[14:15]
	v_mul_f32_e32 v234, v12, v12
	v_fmac_f32_e32 v234, v13, v13
	v_fmac_f32_e32 v234, v14, v14
	v_fmac_f32_e32 v234, v15, v15
	v_cvt_pk_bf16_f32 v222, v224, v225
	v_cvt_pk_bf16_f32 v223, v226, v227
	global_store_dwordx2 v[204:205], v[222:223], off
	v_pk_add_f32 v[6:7], v[6:7], v[198:199]
	v_pk_add_f32 v[4:5], v[4:5], v[196:197]
	global_store_dwordx4 v[220:221], v[4:7], off offset:512
	v_pk_mul_f32 v[228:229], v[84:85], v[4:5]
	v_pk_mul_f32 v[230:231], v[86:87], v[6:7]
	v_fmac_f32_e32 v234, v4, v4
	v_fmac_f32_e32 v234, v5, v5
	v_fmac_f32_e32 v234, v6, v6
	v_fmac_f32_e32 v234, v7, v7
	v_cvt_pk_bf16_f32 v232, v228, v229
	v_cvt_pk_bf16_f32 v233, v230, v231
	global_store_dwordx2 v[204:205], v[232:233], off offset:256
	s_nop 1
	v_mov_b32_dpp v241, v173 row_ror:8 row_mask:0xf bank_mask:0xf
	v_mov_b32_dpp v242, v234 row_ror:8 row_mask:0xf bank_mask:0xf
	v_add_f32_e32 v173, v173, v241
	v_add_f32_e32 v234, v234, v242
	v_cndmask_b32_e64 v173, v234, v173, s[34:35]
	s_nop 0
	ds_bpermute_b32 v241, v235, v173
	s_waitcnt lgkmcnt(0)
	v_add_f32_e32 v173, v173, v241
	s_nop 0
	ds_bpermute_b32 v242, v240, v173
	s_waitcnt lgkmcnt(0)
	v_add_f32_e32 v173, v173, v242
	s_mov_b64 exec, s[0:1]
	global_atomic_add_f32 v[206:207], v173, off
	s_mov_b64 exec, -1
	s_andn2_b64 vcc, exec, s[6:7]
	s_mov_b64 s[4:5], -1
	s_cbranch_vccnz .LBB0_1078
	s_andn2_b64 vcc, exec, s[12:13]
	s_cbranch_vccnz .LBB0_1077
	s_barrier
	s_branch .LBB0_1077

;     __device__ __forceinline__ void operator()(const f32x4 (&acc)[2][2][4][2], const Unit& u, int wr, int wc, int fr, int fq) const {
;         const int row0 = u.pm * BM + wr * 64 + fr, col0 = u.pn * BM + wc * 32 + 4 * fq;
;         const float* rbase = (u.pm * BM < SEQ_P) ? resA : (resB - (size_t)SEQ_P * ldc);
;         f32x4 wv[2][2];
;         if (xn) {
; #pragma unroll
;             for (int bj = 0; bj < 2; ++bj)
; #pragma unroll
;                 for (int n = 0; n < 2; ++n) wv[bj][n] = *(const f32x4*)(wn + col0 + bj * HALF + n * 16);
;         }
; #pragma unroll
;         for (int ai = 0; ai < 2; ++ai)
; #pragma unroll
;             for (int m = 0; m < 4; ++m) {
;                 const int row = row0 + ai * HALF + m * 16;
;                 const size_t off = (size_t)row * ldc + col0;
;                 float q = 0.f;
; #pragma unroll
;                 for (int bj = 0; bj < 2; ++bj)
; #pragma unroll
;                     for (int n = 0; n < 2; ++n) {
;                         const f32x4 rv = *(const f32x4*)(rbase + off + bj * HALF + n * 16);
;                         const f32x4 v = rv + acc[ai][bj][m][n] * scale;
;                         if (out) *(f32x4*)(out + off + bj * HALF + n * 16) = v;
;                         if (xn) { q += (v.x * v.x + v.y * v.y) + (v.z * v.z + v.w * v.w); const f32x4 o = v * wv[bj][n];
;                             u32x2 p; p.x = pk2(o.x, o.y); p.y = pk2(o.z, o.w); *(u32x2*)(xn + off + bj * HALF + n * 16) = p; }
;                     }
;                 if (xn) { q += __shfl_xor(q, 16); q += __shfl_xor(q, 32); if (fq == 0) (void)__hip_atomic_fetch_add(ss + row, q, __ATOMIC_RELAXED, __HIP_MEMORY_SCOPE_AGENT); }
;             }
.LBB0_1382:
	v_lshl_add_u32 v210, s54, 8, v160
	v_lshl_or_b32 v212, s53, 8, v162
	v_and_b32_e32 v238, 8, v167
	v_mov_b32_e32 v211, 0
	v_cmp_eq_u32_e64 s[24:25], 0, v238
	v_lshlrev_b32_e32 v232, 1, v238
	v_add_u32_e32 v214, v212, v232
	v_sub_u32_e32 v233, 16, v232
	v_add_u32_e32 v233, v212, v233
	v_mov_b32_e32 v212, v214
	v_mov_b32_e32 v214, v233
	v_mov_b32_e32 v213, 0
	v_mov_b32_e32 v215, 0
	v_sub_u32_e32 v208, v210, v238
	v_mov_b32_e32 v209, 0
	v_lshlrev_b64 v[206:207], 11, v[208:209]
	v_add_u32_e32 v208, 8, v208
	v_lshlrev_b64 v[208:209], 11, v[208:209]
	v_lshl_add_u64 v[206:207], v[206:207], 0, v[212:213]
	v_lshl_add_u64 v[208:209], v[208:209], 0, v[214:215]
	v_lshl_add_u64 v[196:197], v[206:207], 2, s[8:9]
	v_lshl_add_u64 v[198:199], v[208:209], 2, s[8:9]
	v_lshl_add_u64 v[200:201], v[212:213], 2, s[10:11]
	v_lshl_add_u64 v[202:203], v[214:215], 2, s[10:11]
	global_load_dwordx4 v[72:75], v[200:201], off
	global_load_dwordx4 v[84:87], v[200:201], off offset:512
	global_load_dwordx4 v[88:91], v[202:203], off
	global_load_dwordx4 v[96:99], v[202:203], off offset:512
	global_load_dwordx4 v[156:159], v[196:197], off
	global_load_dwordx4 v[168:171], v[196:197], off offset:512
	global_load_dwordx4 v[172:175], v[198:199], off
	global_load_dwordx4 v[176:179], v[198:199], off offset:512
	s_mov_b64 vcc, 0x20000
	v_lshl_add_u64 v[196:197], v[196:197], 0, vcc
	v_lshl_add_u64 v[198:199], v[198:199], 0, vcc
	global_load_dwordx4 v[180:183], v[196:197], off
	global_load_dwordx4 v[184:187], v[196:197], off offset:512
	global_load_dwordx4 v[188:191], v[198:199], off
	global_load_dwordx4 v[192:195], v[198:199], off offset:512
	s_mov_b64 vcc, 0x20000
	v_lshl_add_u64 v[196:197], v[196:197], 0, vcc
	v_lshl_add_u64 v[198:199], v[198:199], 0, vcc
	v_lshl_add_u64 v[200:201], v[206:207], 1, s[14:15]
	v_lshl_add_u64 v[202:203], v[208:209], 1, s[14:15]
	v_lshl_add_u64 v[204:205], v[210:211], 2, s[16:17]
	v_xor_b32_e32 v234, 16, v167
	v_xor_b32_e32 v235, 32, v167
	v_lshlrev_b32_e32 v234, 2, v234
	v_lshlrev_b32_e32 v235, 2, v235
	v_mov_b32_dpp v228, v136 row_ror:8 row_mask:0xf bank_mask:0xf
	v_mov_b32_dpp v229, v137 row_ror:8 row_mask:0xf bank_mask:0xf
	v_mov_b32_dpp v230, v138 row_ror:8 row_mask:0xf bank_mask:0xf
	v_mov_b32_dpp v231, v139 row_ror:8 row_mask:0xf bank_mask:0xf
	v_cndmask_b32_e64 v136, v228, v140, s[24:25]
	v_cndmask_b32_e64 v137, v229, v141, s[24:25]
	v_cndmask_b32_e64 v138, v230, v142, s[24:25]
	v_cndmask_b32_e64 v139, v231, v143, s[24:25]
	v_cndmask_b32_e64 v140, v140, v228, s[24:25]
	v_cndmask_b32_e64 v141, v141, v229, s[24:25]
	v_cndmask_b32_e64 v142, v142, v230, s[24:25]
	v_cndmask_b32_e64 v143, v143, v231, s[24:25]
	v_mov_b32_dpp v228, v128 row_ror:8 row_mask:0xf bank_mask:0xf
	v_mov_b32_dpp v229, v129 row_ror:8 row_mask:0xf bank_mask:0xf
	v_mov_b32_dpp v230, v130 row_ror:8 row_mask:0xf bank_mask:0xf
	v_mov_b32_dpp v231, v131 row_ror:8 row_mask:0xf bank_mask:0xf
	v_cndmask_b32_e64 v128, v228, v132, s[24:25]
	v_cndmask_b32_e64 v129, v229, v133, s[24:25]
	v_cndmask_b32_e64 v130, v230, v134, s[24:25]
	v_cndmask_b32_e64 v131, v231, v135, s[24:25]
	v_cndmask_b32_e64 v132, v132, v228, s[24:25]
	v_cndmask_b32_e64 v133, v133, v229, s[24:25]
	v_cndmask_b32_e64 v134, v134, v230, s[24:25]
	v_cndmask_b32_e64 v135, v135, v231, s[24:25]
	s_waitcnt vmcnt(4)
	v_pk_fma_f32 v[138:139], v[138:139], 0.5, v[158:159] op_sel_hi:[1,0,1]
	v_pk_fma_f32 v[136:137], v[136:137], 0.5, v[156:157] op_sel_hi:[1,0,1]
	v_pk_mul_f32 v[216:217], v[72:73], v[136:137]
	v_pk_mul_f32 v[218:219], v[74:75], v[138:139]
	v_mul_f32_e32 v232, v136, v136
	v_fmac_f32_e32 v232, v137, v137
	v_fmac_f32_e32 v232, v138, v138
	v_fmac_f32_e32 v232, v139, v139
	v_cvt_pk_bf16_f32 v224, v216, v217
	v_cvt_pk_bf16_f32 v225, v218, v219
	global_store_dwordx2 v[200:201], v[224:225], off
	v_pk_fma_f32 v[130:131], v[130:131], 0.5, v[170:171] op_sel_hi:[1,0,1]
	v_pk_fma_f32 v[128:129], v[128:129], 0.5, v[168:169] op_sel_hi:[1,0,1]
	v_pk_mul_f32 v[220:221], v[84:85], v[128:129]
	v_pk_mul_f32 v[222:223], v[86:87], v[130:131]
	v_fmac_f32_e32 v232, v128, v128
	v_fmac_f32_e32 v232, v129, v129
	v_fmac_f32_e32 v232, v130, v130
	v_fmac_f32_e32 v232, v131, v131
	v_cvt_pk_bf16_f32 v226, v220, v221
	v_cvt_pk_bf16_f32 v227, v222, v223
	global_store_dwordx2 v[200:201], v[226:227], off offset:256
	v_pk_fma_f32 v[142:143], v[142:143], 0.5, v[174:175] op_sel_hi:[1,0,1]
	v_pk_fma_f32 v[140:141], v[140:141], 0.5, v[172:173] op_sel_hi:[1,0,1]
	v_pk_mul_f32 v[216:217], v[88:89], v[140:141]
	v_pk_mul_f32 v[218:219], v[90:91], v[142:143]
	v_mul_f32_e32 v233, v140, v140
	v_fmac_f32_e32 v233, v141, v141
	v_fmac_f32_e32 v233, v142, v142
	v_fmac_f32_e32 v233, v143, v143
	v_cvt_pk_bf16_f32 v224, v216, v217
	v_cvt_pk_bf16_f32 v225, v218, v219
	global_store_dwordx2 v[202:203], v[224:225], off
	v_pk_fma_f32 v[134:135], v[134:135], 0.5, v[178:179] op_sel_hi:[1,0,1]
	v_pk_fma_f32 v[132:133], v[132:133], 0.5, v[176:177] op_sel_hi:[1,0,1]
	v_pk_mul_f32 v[220:221], v[96:97], v[132:133]
	v_pk_mul_f32 v[222:223], v[98:99], v[134:135]
	v_fmac_f32_e32 v233, v132, v132
	v_fmac_f32_e32 v233, v133, v133
	v_fmac_f32_e32 v233, v134, v134
	v_fmac_f32_e32 v233, v135, v135
	v_cvt_pk_bf16_f32 v226, v220, v221
	v_cvt_pk_bf16_f32 v227, v222, v223
	global_store_dwordx2 v[202:203], v[226:227], off offset:256
	s_nop 1
	v_mov_b32_dpp v236, v232 row_ror:8 row_mask:0xf bank_mask:0xf
	v_mov_b32_dpp v237, v233 row_ror:8 row_mask:0xf bank_mask:0xf
	v_add_f32_e32 v232, v232, v236
	v_add_f32_e32 v233, v233, v237
	v_cndmask_b32_e64 v232, v233, v232, s[24:25]
	s_nop 0
	ds_bpermute_b32 v236, v234, v232
	global_load_dwordx4 v[156:159], v[196:197], off
	global_load_dwordx4 v[168:171], v[196:197], off offset:512
	global_load_dwordx4 v[172:175], v[198:199], off
	global_load_dwordx4 v[176:179], v[198:199], off offset:512
	s_mov_b64 vcc, 0x20000
	v_lshl_add_u64 v[196:197], v[196:197], 0, vcc
	v_lshl_add_u64 v[198:199], v[198:199], 0, vcc
	s_mov_b64 vcc, 0x20000
	s_mov_b64 vcc, 0x10000
	v_lshl_add_u64 v[200:201], v[200:201], 0, vcc
	v_lshl_add_u64 v[202:203], v[202:203], 0, vcc
	s_waitcnt lgkmcnt(0)
;     __device__ __forceinline__ void operator()(const f32x4 (&acc)[2][2][4][2], const Unit& u, int wr, int wc, int fr, int fq) const {
;     ...
; #pragma unroll
;         for (int ai = 0; ai < 2; ++ai)
; #pragma unroll
;             for (int m = 0; m < 4; ++m) {
;                 const int row = row0 + ai * HALF + m * 16;
;                 const size_t off = (size_t)row * ldc + col0;
;                 float q = 0.f;
; #pragma unroll
;                 for (int bj = 0; bj < 2; ++bj)
; #pragma unroll
;                     for (int n = 0; n < 2; ++n) {
;                         const f32x4 rv = *(const f32x4*)(rbase + off + bj * HALF + n * 16);
;                         const f32x4 v = rv + acc[ai][bj][m][n] * scale;
;                         if (out) *(f32x4*)(out + off + bj * HALF + n * 16) = v;
;                         if (xn) { q += (v.x * v.x + v.y * v.y) + (v.z * v.z + v.w * v.w); const f32x4 o = v * wv[bj][n];
;                             u32x2 p; p.x = pk2(o.x, o.y); p.y = pk2(o.z, o.w); *(u32x2*)(xn + off + bj * HALF + n * 16) = p; }
;                     }
;                 if (xn) { q += __shfl_xor(q, 16); q += __shfl_xor(q, 32); if (fq == 0) (void)__hip_atomic_fetch_add(ss + row, q, __ATOMIC_RELAXED, __HIP_MEMORY_SCOPE_AGENT); }
;             }
	v_add_f32_e32 v232, v232, v236
	s_nop 0
	ds_bpermute_b32 v237, v235, v232
	s_waitcnt lgkmcnt(0)
	v_add_f32_e32 v232, v232, v237
	s_mov_b64 exec, s[0:1]
	global_atomic_add_f32 v[204:205], v232, off
	s_mov_b64 exec, -1
	s_mov_b64 vcc, 64
	v_lshl_add_u64 v[204:205], v[204:205], 0, vcc
	v_mov_b32_dpp v228, v120 row_ror:8 row_mask:0xf bank_mask:0xf
	v_mov_b32_dpp v229, v121 row_ror:8 row_mask:0xf bank_mask:0xf
	v_mov_b32_dpp v230, v122 row_ror:8 row_mask:0xf bank_mask:0xf
	v_mov_b32_dpp v231, v123 row_ror:8 row_mask:0xf bank_mask:0xf
	v_cndmask_b32_e64 v120, v228, v124, s[24:25]
	v_cndmask_b32_e64 v121, v229, v125, s[24:25]
	v_cndmask_b32_e64 v122, v230, v126, s[24:25]
	v_cndmask_b32_e64 v123, v231, v127, s[24:25]
	v_cndmask_b32_e64 v124, v124, v228, s[24:25]
	v_cndmask_b32_e64 v125, v125, v229, s[24:25]
	v_cndmask_b32_e64 v126, v126, v230, s[24:25]
	v_cndmask_b32_e64 v127, v127, v231, s[24:25]
	v_mov_b32_dpp v228, v112 row_ror:8 row_mask:0xf bank_mask:0xf
	v_mov_b32_dpp v229, v113 row_ror:8 row_mask:0xf bank_mask:0xf
	v_mov_b32_dpp v230, v114 row_ror:8 row_mask:0xf bank_mask:0xf
	v_mov_b32_dpp v231, v115 row_ror:8 row_mask:0xf bank_mask:0xf
	v_cndmask_b32_e64 v112, v228, v116, s[24:25]
	v_cndmask_b32_e64 v113, v229, v117, s[24:25]
	v_cndmask_b32_e64 v114, v230, v118, s[24:25]
	v_cndmask_b32_e64 v115, v231, v119, s[24:25]
	v_cndmask_b32_e64 v116, v116, v228, s[24:25]
	v_cndmask_b32_e64 v117, v117, v229, s[24:25]
	v_cndmask_b32_e64 v118, v118, v230, s[24:25]
	v_cndmask_b32_e64 v119, v119, v231, s[24:25]
	s_waitcnt vmcnt(9)
	v_pk_fma_f32 v[122:123], v[122:123], 0.5, v[182:183] op_sel_hi:[1,0,1]
	v_pk_fma_f32 v[120:121], v[120:121], 0.5, v[180:181] op_sel_hi:[1,0,1]
	v_pk_mul_f32 v[216:217], v[72:73], v[120:121]
	v_pk_mul_f32 v[218:219], v[74:75], v[122:123]
	v_mul_f32_e32 v232, v120, v120
	v_fmac_f32_e32 v232, v121, v121
	v_fmac_f32_e32 v232, v122, v122
	v_fmac_f32_e32 v232, v123, v123
	v_cvt_pk_bf16_f32 v224, v216, v217
	v_cvt_pk_bf16_f32 v225, v218, v219
	global_store_dwordx2 v[200:201], v[224:225], off
	v_pk_fma_f32 v[114:115], v[114:115], 0.5, v[186:187] op_sel_hi:[1,0,1]
	v_pk_fma_f32 v[112:113], v[112:113], 0.5, v[184:185] op_sel_hi:[1,0,1]
	v_pk_mul_f32 v[220:221], v[84:85], v[112:113]
	v_pk_mul_f32 v[222:223], v[86:87], v[114:115]
	v_fmac_f32_e32 v232, v112, v112
	v_fmac_f32_e32 v232, v113, v113
	v_fmac_f32_e32 v232, v114, v114
	v_fmac_f32_e32 v232, v115, v115
	v_cvt_pk_bf16_f32 v226, v220, v221
	v_cvt_pk_bf16_f32 v227, v222, v223
	global_store_dwordx2 v[200:201], v[226:227], off offset:256
	v_pk_fma_f32 v[126:127], v[126:127], 0.5, v[190:191] op_sel_hi:[1,0,1]
	v_pk_fma_f32 v[124:125], v[124:125], 0.5, v[188:189] op_sel_hi:[1,0,1]
	v_pk_mul_f32 v[216:217], v[88:89], v[124:125]
	v_pk_mul_f32 v[218:219], v[90:91], v[126:127]
	v_mul_f32_e32 v233, v124, v124
	v_fmac_f32_e32 v233, v125, v125
	v_fmac_f32_e32 v233, v126, v126
	v_fmac_f32_e32 v233, v127, v127
	v_cvt_pk_bf16_f32 v224, v216, v217
	v_cvt_pk_bf16_f32 v225, v218, v219
	global_store_dwordx2 v[202:203], v[224:225], off
	v_pk_fma_f32 v[118:119], v[118:119], 0.5, v[194:195] op_sel_hi:[1,0,1]
	v_pk_fma_f32 v[116:117], v[116:117], 0.5, v[192:193] op_sel_hi:[1,0,1]
	v_pk_mul_f32 v[220:221], v[96:97], v[116:117]
	v_pk_mul_f32 v[222:223], v[98:99], v[118:119]
	v_fmac_f32_e32 v233, v116, v116
	v_fmac_f32_e32 v233, v117, v117
	v_fmac_f32_e32 v233, v118, v118
	v_fmac_f32_e32 v233, v119, v119
	v_cvt_pk_bf16_f32 v226, v220, v221
	v_cvt_pk_bf16_f32 v227, v222, v223
	global_store_dwordx2 v[202:203], v[226:227], off offset:256
	s_nop 1
	v_mov_b32_dpp v236, v232 row_ror:8 row_mask:0xf bank_mask:0xf
	v_mov_b32_dpp v237, v233 row_ror:8 row_mask:0xf bank_mask:0xf
	v_add_f32_e32 v232, v232, v236
	v_add_f32_e32 v233, v233, v237
	v_cndmask_b32_e64 v232, v233, v232, s[24:25]
	s_nop 0
	ds_bpermute_b32 v236, v234, v232
	global_load_dwordx4 v[180:183], v[196:197], off
	global_load_dwordx4 v[184:187], v[196:197], off offset:512
	global_load_dwordx4 v[188:191], v[198:199], off
	global_load_dwordx4 v[192:195], v[198:199], off offset:512
	s_mov_b64 vcc, 0xa0000
	v_lshl_add_u64 v[196:197], v[196:197], 0, vcc
	v_lshl_add_u64 v[198:199], v[198:199], 0, vcc
	s_mov_b64 vcc, 0x20000
	s_mov_b64 vcc, 0x10000
	v_lshl_add_u64 v[200:201], v[200:201], 0, vcc
	v_lshl_add_u64 v[202:203], v[202:203], 0, vcc
	s_waitcnt lgkmcnt(0)
	v_add_f32_e32 v232, v232, v236
	s_nop 0
	ds_bpermute_b32 v237, v235, v232
	s_waitcnt lgkmcnt(0)
	v_add_f32_e32 v232, v232, v237
	s_mov_b64 exec, s[0:1]
	global_atomic_add_f32 v[204:205], v232, off
	s_mov_b64 exec, -1
	s_mov_b64 vcc, 64
	v_lshl_add_u64 v[204:205], v[204:205], 0, vcc
	v_mov_b32_dpp v228, v104 row_ror:8 row_mask:0xf bank_mask:0xf
	v_mov_b32_dpp v229, v105 row_ror:8 row_mask:0xf bank_mask:0xf
	v_mov_b32_dpp v230, v106 row_ror:8 row_mask:0xf bank_mask:0xf
	v_mov_b32_dpp v231, v107 row_ror:8 row_mask:0xf bank_mask:0xf
	v_cndmask_b32_e64 v104, v228, v108, s[24:25]
	v_cndmask_b32_e64 v105, v229, v109, s[24:25]
	v_cndmask_b32_e64 v106, v230, v110, s[24:25]
	v_cndmask_b32_e64 v107, v231, v111, s[24:25]
	v_cndmask_b32_e64 v108, v108, v228, s[24:25]
	v_cndmask_b32_e64 v109, v109, v229, s[24:25]
	v_cndmask_b32_e64 v110, v110, v230, s[24:25]
	v_cndmask_b32_e64 v111, v111, v231, s[24:25]
	v_mov_b32_dpp v228, v92 row_ror:8 row_mask:0xf bank_mask:0xf
	v_mov_b32_dpp v229, v93 row_ror:8 row_mask:0xf bank_mask:0xf
	v_mov_b32_dpp v230, v94 row_ror:8 row_mask:0xf bank_mask:0xf
	v_mov_b32_dpp v231, v95 row_ror:8 row_mask:0xf bank_mask:0xf
	v_cndmask_b32_e64 v92, v228, v100, s[24:25]
	v_cndmask_b32_e64 v93, v229, v101, s[24:25]
	v_cndmask_b32_e64 v94, v230, v102, s[24:25]
	v_cndmask_b32_e64 v95, v231, v103, s[24:25]
	v_cndmask_b32_e64 v100, v100, v228, s[24:25]
	v_cndmask_b32_e64 v101, v101, v229, s[24:25]
	v_cndmask_b32_e64 v102, v102, v230, s[24:25]
	v_cndmask_b32_e64 v103, v103, v231, s[24:25]
	s_waitcnt vmcnt(10)
;     __device__ __forceinline__ void operator()(const f32x4 (&acc)[2][2][4][2], const Unit& u, int wr, int wc, int fr, int fq) const {
;     ...
; #pragma unroll
;         for (int ai = 0; ai < 2; ++ai)
; #pragma unroll
;             for (int m = 0; m < 4; ++m) {
;                 const int row = row0 + ai * HALF + m * 16;
;                 const size_t off = (size_t)row * ldc + col0;
;                 float q = 0.f;
; #pragma unroll
;                 for (int bj = 0; bj < 2; ++bj)
; #pragma unroll
;                     for (int n = 0; n < 2; ++n) {
;                         const f32x4 rv = *(const f32x4*)(rbase + off + bj * HALF + n * 16);
;                         const f32x4 v = rv + acc[ai][bj][m][n] * scale;
;                         if (out) *(f32x4*)(out + off + bj * HALF + n * 16) = v;
;                         if (xn) { q += (v.x * v.x + v.y * v.y) + (v.z * v.z + v.w * v.w); const f32x4 o = v * wv[bj][n];
;                             u32x2 p; p.x = pk2(o.x, o.y); p.y = pk2(o.z, o.w); *(u32x2*)(xn + off + bj * HALF + n * 16) = p; }
;                     }
;                 if (xn) { q += __shfl_xor(q, 16); q += __shfl_xor(q, 32); if (fq == 0) (void)__hip_atomic_fetch_add(ss + row, q, __ATOMIC_RELAXED, __HIP_MEMORY_SCOPE_AGENT); }
;             }
	v_pk_fma_f32 v[106:107], v[106:107], 0.5, v[158:159] op_sel_hi:[1,0,1]
	v_pk_fma_f32 v[104:105], v[104:105], 0.5, v[156:157] op_sel_hi:[1,0,1]
	v_pk_mul_f32 v[216:217], v[72:73], v[104:105]
	v_pk_mul_f32 v[218:219], v[74:75], v[106:107]
	v_mul_f32_e32 v232, v104, v104
	v_fmac_f32_e32 v232, v105, v105
	v_fmac_f32_e32 v232, v106, v106
	v_fmac_f32_e32 v232, v107, v107
	v_cvt_pk_bf16_f32 v224, v216, v217
	v_cvt_pk_bf16_f32 v225, v218, v219
	global_store_dwordx2 v[200:201], v[224:225], off
	v_pk_fma_f32 v[94:95], v[94:95], 0.5, v[170:171] op_sel_hi:[1,0,1]
	v_pk_fma_f32 v[92:93], v[92:93], 0.5, v[168:169] op_sel_hi:[1,0,1]
	v_pk_mul_f32 v[220:221], v[84:85], v[92:93]
	v_pk_mul_f32 v[222:223], v[86:87], v[94:95]
	v_fmac_f32_e32 v232, v92, v92
	v_fmac_f32_e32 v232, v93, v93
	v_fmac_f32_e32 v232, v94, v94
	v_fmac_f32_e32 v232, v95, v95
	v_cvt_pk_bf16_f32 v226, v220, v221
	v_cvt_pk_bf16_f32 v227, v222, v223
	global_store_dwordx2 v[200:201], v[226:227], off offset:256
	v_pk_fma_f32 v[110:111], v[110:111], 0.5, v[174:175] op_sel_hi:[1,0,1]
	v_pk_fma_f32 v[108:109], v[108:109], 0.5, v[172:173] op_sel_hi:[1,0,1]
	v_pk_mul_f32 v[216:217], v[88:89], v[108:109]
	v_pk_mul_f32 v[218:219], v[90:91], v[110:111]
	v_mul_f32_e32 v233, v108, v108
	v_fmac_f32_e32 v233, v109, v109
	v_fmac_f32_e32 v233, v110, v110
	v_fmac_f32_e32 v233, v111, v111
	v_cvt_pk_bf16_f32 v224, v216, v217
	v_cvt_pk_bf16_f32 v225, v218, v219
	global_store_dwordx2 v[202:203], v[224:225], off
	v_pk_fma_f32 v[102:103], v[102:103], 0.5, v[178:179] op_sel_hi:[1,0,1]
	v_pk_fma_f32 v[100:101], v[100:101], 0.5, v[176:177] op_sel_hi:[1,0,1]
	v_pk_mul_f32 v[220:221], v[96:97], v[100:101]
	v_pk_mul_f32 v[222:223], v[98:99], v[102:103]
	v_fmac_f32_e32 v233, v100, v100
	v_fmac_f32_e32 v233, v101, v101
	v_fmac_f32_e32 v233, v102, v102
	v_fmac_f32_e32 v233, v103, v103
	v_cvt_pk_bf16_f32 v226, v220, v221
	v_cvt_pk_bf16_f32 v227, v222, v223
	global_store_dwordx2 v[202:203], v[226:227], off offset:256
	s_nop 1
	v_mov_b32_dpp v236, v232 row_ror:8 row_mask:0xf bank_mask:0xf
	v_mov_b32_dpp v237, v233 row_ror:8 row_mask:0xf bank_mask:0xf
	v_add_f32_e32 v232, v232, v236
	v_add_f32_e32 v233, v233, v237
	v_cndmask_b32_e64 v232, v233, v232, s[24:25]
	s_nop 0
	ds_bpermute_b32 v236, v234, v232
	global_load_dwordx4 v[156:159], v[196:197], off
	global_load_dwordx4 v[168:171], v[196:197], off offset:512
	global_load_dwordx4 v[172:175], v[198:199], off
	global_load_dwordx4 v[176:179], v[198:199], off offset:512
	s_mov_b64 vcc, 0x20000
	v_lshl_add_u64 v[196:197], v[196:197], 0, vcc
	v_lshl_add_u64 v[198:199], v[198:199], 0, vcc
	s_mov_b64 vcc, 0x20000
	s_mov_b64 vcc, 0x10000
	v_lshl_add_u64 v[200:201], v[200:201], 0, vcc
	v_lshl_add_u64 v[202:203], v[202:203], 0, vcc
	s_waitcnt lgkmcnt(0)
	v_add_f32_e32 v232, v232, v236
	s_nop 0
	ds_bpermute_b32 v237, v235, v232
	s_waitcnt lgkmcnt(0)
	v_add_f32_e32 v232, v232, v237
	s_mov_b64 exec, s[0:1]
	global_atomic_add_f32 v[204:205], v232, off
	s_mov_b64 exec, -1
	s_mov_b64 vcc, 64
	v_lshl_add_u64 v[204:205], v[204:205], 0, vcc
	v_mov_b32_dpp v228, v76 row_ror:8 row_mask:0xf bank_mask:0xf
	v_mov_b32_dpp v229, v77 row_ror:8 row_mask:0xf bank_mask:0xf
	v_mov_b32_dpp v230, v78 row_ror:8 row_mask:0xf bank_mask:0xf
	v_mov_b32_dpp v231, v79 row_ror:8 row_mask:0xf bank_mask:0xf
	v_cndmask_b32_e64 v76, v228, v80, s[24:25]
	v_cndmask_b32_e64 v77, v229, v81, s[24:25]
	v_cndmask_b32_e64 v78, v230, v82, s[24:25]
	v_cndmask_b32_e64 v79, v231, v83, s[24:25]
	v_cndmask_b32_e64 v80, v80, v228, s[24:25]
	v_cndmask_b32_e64 v81, v81, v229, s[24:25]
	v_cndmask_b32_e64 v82, v82, v230, s[24:25]
	v_cndmask_b32_e64 v83, v83, v231, s[24:25]
	v_mov_b32_dpp v228, v64 row_ror:8 row_mask:0xf bank_mask:0xf
	v_mov_b32_dpp v229, v65 row_ror:8 row_mask:0xf bank_mask:0xf
	v_mov_b32_dpp v230, v66 row_ror:8 row_mask:0xf bank_mask:0xf
	v_mov_b32_dpp v231, v67 row_ror:8 row_mask:0xf bank_mask:0xf
	v_cndmask_b32_e64 v64, v228, v68, s[24:25]
	v_cndmask_b32_e64 v65, v229, v69, s[24:25]
	v_cndmask_b32_e64 v66, v230, v70, s[24:25]
	v_cndmask_b32_e64 v67, v231, v71, s[24:25]
	v_cndmask_b32_e64 v68, v68, v228, s[24:25]
	v_cndmask_b32_e64 v69, v69, v229, s[24:25]
	v_cndmask_b32_e64 v70, v70, v230, s[24:25]
	v_cndmask_b32_e64 v71, v71, v231, s[24:25]
	s_waitcnt vmcnt(10)
	v_pk_fma_f32 v[78:79], v[78:79], 0.5, v[182:183] op_sel_hi:[1,0,1]
	v_pk_fma_f32 v[76:77], v[76:77], 0.5, v[180:181] op_sel_hi:[1,0,1]
	v_pk_mul_f32 v[216:217], v[72:73], v[76:77]
	v_pk_mul_f32 v[218:219], v[74:75], v[78:79]
	v_mul_f32_e32 v232, v76, v76
	v_fmac_f32_e32 v232, v77, v77
	v_fmac_f32_e32 v232, v78, v78
	v_fmac_f32_e32 v232, v79, v79
	v_cvt_pk_bf16_f32 v224, v216, v217
	v_cvt_pk_bf16_f32 v225, v218, v219
	global_store_dwordx2 v[200:201], v[224:225], off
	v_pk_fma_f32 v[66:67], v[66:67], 0.5, v[186:187] op_sel_hi:[1,0,1]
	v_pk_fma_f32 v[64:65], v[64:65], 0.5, v[184:185] op_sel_hi:[1,0,1]
	v_pk_mul_f32 v[220:221], v[84:85], v[64:65]
	v_pk_mul_f32 v[222:223], v[86:87], v[66:67]
	v_fmac_f32_e32 v232, v64, v64
	v_fmac_f32_e32 v232, v65, v65
	v_fmac_f32_e32 v232, v66, v66
	v_fmac_f32_e32 v232, v67, v67
	v_cvt_pk_bf16_f32 v226, v220, v221
	v_cvt_pk_bf16_f32 v227, v222, v223
	global_store_dwordx2 v[200:201], v[226:227], off offset:256
	v_pk_fma_f32 v[82:83], v[82:83], 0.5, v[190:191] op_sel_hi:[1,0,1]
	v_pk_fma_f32 v[80:81], v[80:81], 0.5, v[188:189] op_sel_hi:[1,0,1]
	v_pk_mul_f32 v[216:217], v[88:89], v[80:81]
	v_pk_mul_f32 v[218:219], v[90:91], v[82:83]
	v_mul_f32_e32 v233, v80, v80
	v_fmac_f32_e32 v233, v81, v81
	v_fmac_f32_e32 v233, v82, v82
	v_fmac_f32_e32 v233, v83, v83
	v_cvt_pk_bf16_f32 v224, v216, v217
	v_cvt_pk_bf16_f32 v225, v218, v219
	global_store_dwordx2 v[202:203], v[224:225], off
	v_pk_fma_f32 v[70:71], v[70:71], 0.5, v[194:195] op_sel_hi:[1,0,1]
	v_pk_fma_f32 v[68:69], v[68:69], 0.5, v[192:193] op_sel_hi:[1,0,1]
	v_pk_mul_f32 v[220:221], v[96:97], v[68:69]
	v_pk_mul_f32 v[222:223], v[98:99], v[70:71]
	v_fmac_f32_e32 v233, v68, v68
	v_fmac_f32_e32 v233, v69, v69
	v_fmac_f32_e32 v233, v70, v70
	v_fmac_f32_e32 v233, v71, v71
	v_cvt_pk_bf16_f32 v226, v220, v221
	v_cvt_pk_bf16_f32 v227, v222, v223
	global_store_dwordx2 v[202:203], v[226:227], off offset:256
	s_nop 1
	v_mov_b32_dpp v236, v232 row_ror:8 row_mask:0xf bank_mask:0xf
	v_mov_b32_dpp v237, v233 row_ror:8 row_mask:0xf bank_mask:0xf
	v_add_f32_e32 v232, v232, v236
	v_add_f32_e32 v233, v233, v237
	v_cndmask_b32_e64 v232, v233, v232, s[24:25]
	s_nop 0
	ds_bpermute_b32 v236, v234, v232
	global_load_dwordx4 v[180:183], v[196:197], off
	global_load_dwordx4 v[184:187], v[196:197], off offset:512
	global_load_dwordx4 v[188:191], v[198:199], off
	global_load_dwordx4 v[192:195], v[198:199], off offset:512
	s_mov_b64 vcc, 0x20000
	v_lshl_add_u64 v[196:197], v[196:197], 0, vcc
	v_lshl_add_u64 v[198:199], v[198:199], 0, vcc
	s_mov_b64 vcc, 0xa0000
	s_mov_b64 vcc, 0x50000
	v_lshl_add_u64 v[200:201], v[200:201], 0, vcc
	v_lshl_add_u64 v[202:203], v[202:203], 0, vcc
	s_waitcnt lgkmcnt(0)
;     __device__ __forceinline__ void operator()(const f32x4 (&acc)[2][2][4][2], const Unit& u, int wr, int wc, int fr, int fq) const {
;     ...
; #pragma unroll
;         for (int ai = 0; ai < 2; ++ai)
; #pragma unroll
;             for (int m = 0; m < 4; ++m) {
;                 const int row = row0 + ai * HALF + m * 16;
;                 const size_t off = (size_t)row * ldc + col0;
;                 float q = 0.f;
; #pragma unroll
;                 for (int bj = 0; bj < 2; ++bj)
; #pragma unroll
;                     for (int n = 0; n < 2; ++n) {
;                         const f32x4 rv = *(const f32x4*)(rbase + off + bj * HALF + n * 16);
;                         const f32x4 v = rv + acc[ai][bj][m][n] * scale;
;                         if (out) *(f32x4*)(out + off + bj * HALF + n * 16) = v;
;                         if (xn) { q += (v.x * v.x + v.y * v.y) + (v.z * v.z + v.w * v.w); const f32x4 o = v * wv[bj][n];
;                             u32x2 p; p.x = pk2(o.x, o.y); p.y = pk2(o.z, o.w); *(u32x2*)(xn + off + bj * HALF + n * 16) = p; }
;                     }
;                 if (xn) { q += __shfl_xor(q, 16); q += __shfl_xor(q, 32); if (fq == 0) (void)__hip_atomic_fetch_add(ss + row, q, __ATOMIC_RELAXED, __HIP_MEMORY_SCOPE_AGENT); }
;             }
	v_add_f32_e32 v232, v232, v236
	s_nop 0
	ds_bpermute_b32 v237, v235, v232
	s_waitcnt lgkmcnt(0)
	v_add_f32_e32 v232, v232, v237
	s_mov_b64 exec, s[0:1]
	global_atomic_add_f32 v[204:205], v232, off
	s_mov_b64 exec, -1
	s_mov_b64 vcc, 320
	v_lshl_add_u64 v[204:205], v[204:205], 0, vcc
	v_mov_b32_dpp v228, v56 row_ror:8 row_mask:0xf bank_mask:0xf
	v_mov_b32_dpp v229, v57 row_ror:8 row_mask:0xf bank_mask:0xf
	v_mov_b32_dpp v230, v58 row_ror:8 row_mask:0xf bank_mask:0xf
	v_mov_b32_dpp v231, v59 row_ror:8 row_mask:0xf bank_mask:0xf
	v_cndmask_b32_e64 v56, v228, v60, s[24:25]
	v_cndmask_b32_e64 v57, v229, v61, s[24:25]
	v_cndmask_b32_e64 v58, v230, v62, s[24:25]
	v_cndmask_b32_e64 v59, v231, v63, s[24:25]
	v_cndmask_b32_e64 v60, v60, v228, s[24:25]
	v_cndmask_b32_e64 v61, v61, v229, s[24:25]
	v_cndmask_b32_e64 v62, v62, v230, s[24:25]
	v_cndmask_b32_e64 v63, v63, v231, s[24:25]
	v_mov_b32_dpp v228, v48 row_ror:8 row_mask:0xf bank_mask:0xf
	v_mov_b32_dpp v229, v49 row_ror:8 row_mask:0xf bank_mask:0xf
	v_mov_b32_dpp v230, v50 row_ror:8 row_mask:0xf bank_mask:0xf
	v_mov_b32_dpp v231, v51 row_ror:8 row_mask:0xf bank_mask:0xf
	v_cndmask_b32_e64 v48, v228, v52, s[24:25]
	v_cndmask_b32_e64 v49, v229, v53, s[24:25]
	v_cndmask_b32_e64 v50, v230, v54, s[24:25]
	v_cndmask_b32_e64 v51, v231, v55, s[24:25]
	v_cndmask_b32_e64 v52, v52, v228, s[24:25]
	v_cndmask_b32_e64 v53, v53, v229, s[24:25]
	v_cndmask_b32_e64 v54, v54, v230, s[24:25]
	v_cndmask_b32_e64 v55, v55, v231, s[24:25]
	s_waitcnt vmcnt(10)
	v_pk_fma_f32 v[58:59], v[58:59], 0.5, v[158:159] op_sel_hi:[1,0,1]
	v_pk_fma_f32 v[56:57], v[56:57], 0.5, v[156:157] op_sel_hi:[1,0,1]
	v_pk_mul_f32 v[216:217], v[72:73], v[56:57]
	v_pk_mul_f32 v[218:219], v[74:75], v[58:59]
	v_mul_f32_e32 v232, v56, v56
	v_fmac_f32_e32 v232, v57, v57
	v_fmac_f32_e32 v232, v58, v58
	v_fmac_f32_e32 v232, v59, v59
	v_cvt_pk_bf16_f32 v224, v216, v217
	v_cvt_pk_bf16_f32 v225, v218, v219
	global_store_dwordx2 v[200:201], v[224:225], off
	v_pk_fma_f32 v[50:51], v[50:51], 0.5, v[170:171] op_sel_hi:[1,0,1]
	v_pk_fma_f32 v[48:49], v[48:49], 0.5, v[168:169] op_sel_hi:[1,0,1]
	v_pk_mul_f32 v[220:221], v[84:85], v[48:49]
	v_pk_mul_f32 v[222:223], v[86:87], v[50:51]
	v_fmac_f32_e32 v232, v48, v48
	v_fmac_f32_e32 v232, v49, v49
	v_fmac_f32_e32 v232, v50, v50
	v_fmac_f32_e32 v232, v51, v51
	v_cvt_pk_bf16_f32 v226, v220, v221
	v_cvt_pk_bf16_f32 v227, v222, v223
	global_store_dwordx2 v[200:201], v[226:227], off offset:256
	v_pk_fma_f32 v[62:63], v[62:63], 0.5, v[174:175] op_sel_hi:[1,0,1]
	v_pk_fma_f32 v[60:61], v[60:61], 0.5, v[172:173] op_sel_hi:[1,0,1]
	v_pk_mul_f32 v[216:217], v[88:89], v[60:61]
	v_pk_mul_f32 v[218:219], v[90:91], v[62:63]
	v_mul_f32_e32 v233, v60, v60
	v_fmac_f32_e32 v233, v61, v61
	v_fmac_f32_e32 v233, v62, v62
	v_fmac_f32_e32 v233, v63, v63
	v_cvt_pk_bf16_f32 v224, v216, v217
	v_cvt_pk_bf16_f32 v225, v218, v219
	global_store_dwordx2 v[202:203], v[224:225], off
	v_pk_fma_f32 v[54:55], v[54:55], 0.5, v[178:179] op_sel_hi:[1,0,1]
	v_pk_fma_f32 v[52:53], v[52:53], 0.5, v[176:177] op_sel_hi:[1,0,1]
	v_pk_mul_f32 v[220:221], v[96:97], v[52:53]
	v_pk_mul_f32 v[222:223], v[98:99], v[54:55]
	v_fmac_f32_e32 v233, v52, v52
	v_fmac_f32_e32 v233, v53, v53
	v_fmac_f32_e32 v233, v54, v54
	v_fmac_f32_e32 v233, v55, v55
	v_cvt_pk_bf16_f32 v226, v220, v221
	v_cvt_pk_bf16_f32 v227, v222, v223
	global_store_dwordx2 v[202:203], v[226:227], off offset:256
	s_nop 1
	v_mov_b32_dpp v236, v232 row_ror:8 row_mask:0xf bank_mask:0xf
	v_mov_b32_dpp v237, v233 row_ror:8 row_mask:0xf bank_mask:0xf
	v_add_f32_e32 v232, v232, v236
	v_add_f32_e32 v233, v233, v237
	v_cndmask_b32_e64 v232, v233, v232, s[24:25]
	s_nop 0
	ds_bpermute_b32 v236, v234, v232
	global_load_dwordx4 v[156:159], v[196:197], off
	global_load_dwordx4 v[168:171], v[196:197], off offset:512
	global_load_dwordx4 v[172:175], v[198:199], off
	global_load_dwordx4 v[176:179], v[198:199], off offset:512
	s_mov_b64 vcc, 0x20000
	v_lshl_add_u64 v[196:197], v[196:197], 0, vcc
	v_lshl_add_u64 v[198:199], v[198:199], 0, vcc
	s_mov_b64 vcc, 0x20000
	s_mov_b64 vcc, 0x10000
	v_lshl_add_u64 v[200:201], v[200:201], 0, vcc
	v_lshl_add_u64 v[202:203], v[202:203], 0, vcc
	s_waitcnt lgkmcnt(0)
	v_add_f32_e32 v232, v232, v236
	s_nop 0
	ds_bpermute_b32 v237, v235, v232
	s_waitcnt lgkmcnt(0)
	v_add_f32_e32 v232, v232, v237
	s_mov_b64 exec, s[0:1]
	global_atomic_add_f32 v[204:205], v232, off
	s_mov_b64 exec, -1
	s_mov_b64 vcc, 64
	v_lshl_add_u64 v[204:205], v[204:205], 0, vcc
	v_mov_b32_dpp v228, v40 row_ror:8 row_mask:0xf bank_mask:0xf
	v_mov_b32_dpp v229, v41 row_ror:8 row_mask:0xf bank_mask:0xf
	v_mov_b32_dpp v230, v42 row_ror:8 row_mask:0xf bank_mask:0xf
	v_mov_b32_dpp v231, v43 row_ror:8 row_mask:0xf bank_mask:0xf
	v_cndmask_b32_e64 v40, v228, v44, s[24:25]
	v_cndmask_b32_e64 v41, v229, v45, s[24:25]
	v_cndmask_b32_e64 v42, v230, v46, s[24:25]
	v_cndmask_b32_e64 v43, v231, v47, s[24:25]
	v_cndmask_b32_e64 v44, v44, v228, s[24:25]
	v_cndmask_b32_e64 v45, v45, v229, s[24:25]
	v_cndmask_b32_e64 v46, v46, v230, s[24:25]
	v_cndmask_b32_e64 v47, v47, v231, s[24:25]
	v_mov_b32_dpp v228, v32 row_ror:8 row_mask:0xf bank_mask:0xf
	v_mov_b32_dpp v229, v33 row_ror:8 row_mask:0xf bank_mask:0xf
	v_mov_b32_dpp v230, v34 row_ror:8 row_mask:0xf bank_mask:0xf
	v_mov_b32_dpp v231, v35 row_ror:8 row_mask:0xf bank_mask:0xf
	v_cndmask_b32_e64 v32, v228, v36, s[24:25]
	v_cndmask_b32_e64 v33, v229, v37, s[24:25]
	v_cndmask_b32_e64 v34, v230, v38, s[24:25]
	v_cndmask_b32_e64 v35, v231, v39, s[24:25]
	v_cndmask_b32_e64 v36, v36, v228, s[24:25]
	v_cndmask_b32_e64 v37, v37, v229, s[24:25]
	v_cndmask_b32_e64 v38, v38, v230, s[24:25]
	v_cndmask_b32_e64 v39, v39, v231, s[24:25]
	s_waitcnt vmcnt(10)
;     __device__ __forceinline__ void operator()(const f32x4 (&acc)[2][2][4][2], const Unit& u, int wr, int wc, int fr, int fq) const {
;     ...
; #pragma unroll
;         for (int ai = 0; ai < 2; ++ai)
; #pragma unroll
;             for (int m = 0; m < 4; ++m) {
;                 const int row = row0 + ai * HALF + m * 16;
;                 const size_t off = (size_t)row * ldc + col0;
;                 float q = 0.f;
; #pragma unroll
;                 for (int bj = 0; bj < 2; ++bj)
; #pragma unroll
;                     for (int n = 0; n < 2; ++n) {
;                         const f32x4 rv = *(const f32x4*)(rbase + off + bj * HALF + n * 16);
;                         const f32x4 v = rv + acc[ai][bj][m][n] * scale;
;                         if (out) *(f32x4*)(out + off + bj * HALF + n * 16) = v;
;                         if (xn) { q += (v.x * v.x + v.y * v.y) + (v.z * v.z + v.w * v.w); const f32x4 o = v * wv[bj][n];
;                             u32x2 p; p.x = pk2(o.x, o.y); p.y = pk2(o.z, o.w); *(u32x2*)(xn + off + bj * HALF + n * 16) = p; }
;                     }
;                 if (xn) { q += __shfl_xor(q, 16); q += __shfl_xor(q, 32); if (fq == 0) (void)__hip_atomic_fetch_add(ss + row, q, __ATOMIC_RELAXED, __HIP_MEMORY_SCOPE_AGENT); }
;             }
	v_pk_fma_f32 v[42:43], v[42:43], 0.5, v[182:183] op_sel_hi:[1,0,1]
	v_pk_fma_f32 v[40:41], v[40:41], 0.5, v[180:181] op_sel_hi:[1,0,1]
	v_pk_mul_f32 v[216:217], v[72:73], v[40:41]
	v_pk_mul_f32 v[218:219], v[74:75], v[42:43]
	v_mul_f32_e32 v232, v40, v40
	v_fmac_f32_e32 v232, v41, v41
	v_fmac_f32_e32 v232, v42, v42
	v_fmac_f32_e32 v232, v43, v43
	v_cvt_pk_bf16_f32 v224, v216, v217
	v_cvt_pk_bf16_f32 v225, v218, v219
	global_store_dwordx2 v[200:201], v[224:225], off
	v_pk_fma_f32 v[34:35], v[34:35], 0.5, v[186:187] op_sel_hi:[1,0,1]
	v_pk_fma_f32 v[32:33], v[32:33], 0.5, v[184:185] op_sel_hi:[1,0,1]
	v_pk_mul_f32 v[220:221], v[84:85], v[32:33]
	v_pk_mul_f32 v[222:223], v[86:87], v[34:35]
	v_fmac_f32_e32 v232, v32, v32
	v_fmac_f32_e32 v232, v33, v33
	v_fmac_f32_e32 v232, v34, v34
	v_fmac_f32_e32 v232, v35, v35
	v_cvt_pk_bf16_f32 v226, v220, v221
	v_cvt_pk_bf16_f32 v227, v222, v223
	global_store_dwordx2 v[200:201], v[226:227], off offset:256
	v_pk_fma_f32 v[46:47], v[46:47], 0.5, v[190:191] op_sel_hi:[1,0,1]
	v_pk_fma_f32 v[44:45], v[44:45], 0.5, v[188:189] op_sel_hi:[1,0,1]
	v_pk_mul_f32 v[216:217], v[88:89], v[44:45]
	v_pk_mul_f32 v[218:219], v[90:91], v[46:47]
	v_mul_f32_e32 v233, v44, v44
	v_fmac_f32_e32 v233, v45, v45
	v_fmac_f32_e32 v233, v46, v46
	v_fmac_f32_e32 v233, v47, v47
	v_cvt_pk_bf16_f32 v224, v216, v217
	v_cvt_pk_bf16_f32 v225, v218, v219
	global_store_dwordx2 v[202:203], v[224:225], off
	v_pk_fma_f32 v[38:39], v[38:39], 0.5, v[194:195] op_sel_hi:[1,0,1]
	v_pk_fma_f32 v[36:37], v[36:37], 0.5, v[192:193] op_sel_hi:[1,0,1]
	v_pk_mul_f32 v[220:221], v[96:97], v[36:37]
	v_pk_mul_f32 v[222:223], v[98:99], v[38:39]
	v_fmac_f32_e32 v233, v36, v36
	v_fmac_f32_e32 v233, v37, v37
	v_fmac_f32_e32 v233, v38, v38
	v_fmac_f32_e32 v233, v39, v39
	v_cvt_pk_bf16_f32 v226, v220, v221
	v_cvt_pk_bf16_f32 v227, v222, v223
	global_store_dwordx2 v[202:203], v[226:227], off offset:256
	s_nop 1
	v_mov_b32_dpp v236, v232 row_ror:8 row_mask:0xf bank_mask:0xf
	v_mov_b32_dpp v237, v233 row_ror:8 row_mask:0xf bank_mask:0xf
	v_add_f32_e32 v232, v232, v236
	v_add_f32_e32 v233, v233, v237
	v_cndmask_b32_e64 v232, v233, v232, s[24:25]
	s_nop 0
	ds_bpermute_b32 v236, v234, v232
	global_load_dwordx4 v[180:183], v[196:197], off
	global_load_dwordx4 v[184:187], v[196:197], off offset:512
	global_load_dwordx4 v[188:191], v[198:199], off
	global_load_dwordx4 v[192:195], v[198:199], off offset:512
	s_mov_b64 vcc, 0x20000
	s_mov_b64 vcc, 0x10000
	v_lshl_add_u64 v[200:201], v[200:201], 0, vcc
	v_lshl_add_u64 v[202:203], v[202:203], 0, vcc
	s_waitcnt lgkmcnt(0)
	v_add_f32_e32 v232, v232, v236
	s_nop 0
	ds_bpermute_b32 v237, v235, v232
	s_waitcnt lgkmcnt(0)
	v_add_f32_e32 v232, v232, v237
	s_mov_b64 exec, s[0:1]
	global_atomic_add_f32 v[204:205], v232, off
	s_mov_b64 exec, -1
	s_mov_b64 vcc, 64
	v_lshl_add_u64 v[204:205], v[204:205], 0, vcc
	v_mov_b32_dpp v228, v24 row_ror:8 row_mask:0xf bank_mask:0xf
	v_mov_b32_dpp v229, v25 row_ror:8 row_mask:0xf bank_mask:0xf
	v_mov_b32_dpp v230, v26 row_ror:8 row_mask:0xf bank_mask:0xf
	v_mov_b32_dpp v231, v27 row_ror:8 row_mask:0xf bank_mask:0xf
	v_cndmask_b32_e64 v24, v228, v28, s[24:25]
	v_cndmask_b32_e64 v25, v229, v29, s[24:25]
	v_cndmask_b32_e64 v26, v230, v30, s[24:25]
	v_cndmask_b32_e64 v27, v231, v31, s[24:25]
	v_cndmask_b32_e64 v28, v28, v228, s[24:25]
	v_cndmask_b32_e64 v29, v29, v229, s[24:25]
	v_cndmask_b32_e64 v30, v30, v230, s[24:25]
	v_cndmask_b32_e64 v31, v31, v231, s[24:25]
	v_mov_b32_dpp v228, v16 row_ror:8 row_mask:0xf bank_mask:0xf
	v_mov_b32_dpp v229, v17 row_ror:8 row_mask:0xf bank_mask:0xf
	v_mov_b32_dpp v230, v18 row_ror:8 row_mask:0xf bank_mask:0xf
	v_mov_b32_dpp v231, v19 row_ror:8 row_mask:0xf bank_mask:0xf
	v_cndmask_b32_e64 v16, v228, v20, s[24:25]
	v_cndmask_b32_e64 v17, v229, v21, s[24:25]
	v_cndmask_b32_e64 v18, v230, v22, s[24:25]
	v_cndmask_b32_e64 v19, v231, v23, s[24:25]
	v_cndmask_b32_e64 v20, v20, v228, s[24:25]
	v_cndmask_b32_e64 v21, v21, v229, s[24:25]
	v_cndmask_b32_e64 v22, v22, v230, s[24:25]
	v_cndmask_b32_e64 v23, v23, v231, s[24:25]
	s_waitcnt vmcnt(10)
; #define PG8_BAR __builtin_amdgcn_s_barrier()
;     __device__ __forceinline__ void operator()(const f32x4 (&acc)[2][2][4][2], const Unit& u, int wr, int wc, int fr, int fq) const {
;     ...
; #pragma unroll
;         for (int ai = 0; ai < 2; ++ai)
; #pragma unroll
;             for (int m = 0; m < 4; ++m) {
;                 const int row = row0 + ai * HALF + m * 16;
;                 const size_t off = (size_t)row * ldc + col0;
;                 float q = 0.f;
; #pragma unroll
;                 for (int bj = 0; bj < 2; ++bj)
; #pragma unroll
;                     for (int n = 0; n < 2; ++n) {
;                         const f32x4 rv = *(const f32x4*)(rbase + off + bj * HALF + n * 16);
;                         const f32x4 v = rv + acc[ai][bj][m][n] * scale;
;                         if (out) *(f32x4*)(out + off + bj * HALF + n * 16) = v;
;                         if (xn) { q += (v.x * v.x + v.y * v.y) + (v.z * v.z + v.w * v.w); const f32x4 o = v * wv[bj][n];
;                             u32x2 p; p.x = pk2(o.x, o.y); p.y = pk2(o.z, o.w); *(u32x2*)(xn + off + bj * HALF + n * 16) = p; }
;                     }
;                 if (xn) { q += __shfl_xor(q, 16); q += __shfl_xor(q, 32); if (fq == 0) (void)__hip_atomic_fetch_add(ss + row, q, __ATOMIC_RELAXED, __HIP_MEMORY_SCOPE_AGENT); }
;             }
; template <class Epi, bool ALIGN_EPI>
; __device__ __forceinline__ void gemm_phase(LAS unsigned char* lds, const Gemm g, const StaticOrder& S, const Epi& E) {
;     ...
;         if (!has_next) break;
; #pragma unroll
;         for (int a = 0; a < 2; ++a)
; #pragma unroll
;             for (int b = 0; b < 2; ++b)
; #pragma unroll
;                 for (int m = 0; m < 4; ++m)
; #pragma unroll
;                     for (int n = 0; n < 2; ++n) acc[a][b][m][n] = (f32x4){0.f, 0.f, 0.f, 0.f};
;         cur = nxt; cA = nA; cB = nB; ++ui;
;         if constexpr (ALIGN_EPI) { if (wr == 1) PG8_BAR; }
	v_pk_fma_f32 v[26:27], v[26:27], 0.5, v[158:159] op_sel_hi:[1,0,1]
	v_pk_fma_f32 v[24:25], v[24:25], 0.5, v[156:157] op_sel_hi:[1,0,1]
	v_pk_mul_f32 v[216:217], v[72:73], v[24:25]
	v_pk_mul_f32 v[218:219], v[74:75], v[26:27]
	v_mul_f32_e32 v232, v24, v24
	v_fmac_f32_e32 v232, v25, v25
	v_fmac_f32_e32 v232, v26, v26
	v_fmac_f32_e32 v232, v27, v27
	v_cvt_pk_bf16_f32 v224, v216, v217
	v_cvt_pk_bf16_f32 v225, v218, v219
	global_store_dwordx2 v[200:201], v[224:225], off
	v_pk_fma_f32 v[18:19], v[18:19], 0.5, v[170:171] op_sel_hi:[1,0,1]
	v_pk_fma_f32 v[16:17], v[16:17], 0.5, v[168:169] op_sel_hi:[1,0,1]
	v_pk_mul_f32 v[220:221], v[84:85], v[16:17]
	v_pk_mul_f32 v[222:223], v[86:87], v[18:19]
	v_fmac_f32_e32 v232, v16, v16
	v_fmac_f32_e32 v232, v17, v17
	v_fmac_f32_e32 v232, v18, v18
	v_fmac_f32_e32 v232, v19, v19
	v_cvt_pk_bf16_f32 v226, v220, v221
	v_cvt_pk_bf16_f32 v227, v222, v223
	global_store_dwordx2 v[200:201], v[226:227], off offset:256
	v_pk_fma_f32 v[30:31], v[30:31], 0.5, v[174:175] op_sel_hi:[1,0,1]
	v_pk_fma_f32 v[28:29], v[28:29], 0.5, v[172:173] op_sel_hi:[1,0,1]
	v_pk_mul_f32 v[216:217], v[88:89], v[28:29]
	v_pk_mul_f32 v[218:219], v[90:91], v[30:31]
	v_mul_f32_e32 v233, v28, v28
	v_fmac_f32_e32 v233, v29, v29
	v_fmac_f32_e32 v233, v30, v30
	v_fmac_f32_e32 v233, v31, v31
	v_cvt_pk_bf16_f32 v224, v216, v217
	v_cvt_pk_bf16_f32 v225, v218, v219
	global_store_dwordx2 v[202:203], v[224:225], off
	v_pk_fma_f32 v[22:23], v[22:23], 0.5, v[178:179] op_sel_hi:[1,0,1]
	v_pk_fma_f32 v[20:21], v[20:21], 0.5, v[176:177] op_sel_hi:[1,0,1]
	v_pk_mul_f32 v[220:221], v[96:97], v[20:21]
	v_pk_mul_f32 v[222:223], v[98:99], v[22:23]
	v_fmac_f32_e32 v233, v20, v20
	v_fmac_f32_e32 v233, v21, v21
	v_fmac_f32_e32 v233, v22, v22
	v_fmac_f32_e32 v233, v23, v23
	v_cvt_pk_bf16_f32 v226, v220, v221
	v_cvt_pk_bf16_f32 v227, v222, v223
	global_store_dwordx2 v[202:203], v[226:227], off offset:256
	s_nop 1
	v_mov_b32_dpp v236, v232 row_ror:8 row_mask:0xf bank_mask:0xf
	v_mov_b32_dpp v237, v233 row_ror:8 row_mask:0xf bank_mask:0xf
	v_add_f32_e32 v232, v232, v236
	v_add_f32_e32 v233, v233, v237
	v_cndmask_b32_e64 v232, v233, v232, s[24:25]
	s_nop 0
	ds_bpermute_b32 v236, v234, v232
	s_mov_b64 vcc, 0x20000
	s_mov_b64 vcc, 0x10000
	v_lshl_add_u64 v[200:201], v[200:201], 0, vcc
	v_lshl_add_u64 v[202:203], v[202:203], 0, vcc
	s_waitcnt lgkmcnt(0)
	v_add_f32_e32 v232, v232, v236
	s_nop 0
	ds_bpermute_b32 v237, v235, v232
	s_waitcnt lgkmcnt(0)
	v_add_f32_e32 v232, v232, v237
	s_mov_b64 exec, s[0:1]
	global_atomic_add_f32 v[204:205], v232, off
	s_mov_b64 exec, -1
	s_mov_b64 vcc, 64
	v_lshl_add_u64 v[204:205], v[204:205], 0, vcc
	v_mov_b32_dpp v228, v8 row_ror:8 row_mask:0xf bank_mask:0xf
	v_mov_b32_dpp v229, v9 row_ror:8 row_mask:0xf bank_mask:0xf
	v_mov_b32_dpp v230, v10 row_ror:8 row_mask:0xf bank_mask:0xf
	v_mov_b32_dpp v231, v11 row_ror:8 row_mask:0xf bank_mask:0xf
	v_cndmask_b32_e64 v8, v228, v12, s[24:25]
	v_cndmask_b32_e64 v9, v229, v13, s[24:25]
	v_cndmask_b32_e64 v10, v230, v14, s[24:25]
	v_cndmask_b32_e64 v11, v231, v15, s[24:25]
	v_cndmask_b32_e64 v12, v12, v228, s[24:25]
	v_cndmask_b32_e64 v13, v13, v229, s[24:25]
	v_cndmask_b32_e64 v14, v14, v230, s[24:25]
	v_cndmask_b32_e64 v15, v15, v231, s[24:25]
	v_mov_b32_dpp v228, v0 row_ror:8 row_mask:0xf bank_mask:0xf
	v_mov_b32_dpp v229, v1 row_ror:8 row_mask:0xf bank_mask:0xf
	v_mov_b32_dpp v230, v2 row_ror:8 row_mask:0xf bank_mask:0xf
	v_mov_b32_dpp v231, v3 row_ror:8 row_mask:0xf bank_mask:0xf
	v_cndmask_b32_e64 v0, v228, v4, s[24:25]
	v_cndmask_b32_e64 v1, v229, v5, s[24:25]
	v_cndmask_b32_e64 v2, v230, v6, s[24:25]
	v_cndmask_b32_e64 v3, v231, v7, s[24:25]
	v_cndmask_b32_e64 v4, v4, v228, s[24:25]
	v_cndmask_b32_e64 v5, v5, v229, s[24:25]
	v_cndmask_b32_e64 v6, v6, v230, s[24:25]
	v_cndmask_b32_e64 v7, v7, v231, s[24:25]
	s_waitcnt vmcnt(6)
	v_pk_fma_f32 v[10:11], v[10:11], 0.5, v[182:183] op_sel_hi:[1,0,1]
	v_pk_fma_f32 v[8:9], v[8:9], 0.5, v[180:181] op_sel_hi:[1,0,1]
	v_pk_mul_f32 v[216:217], v[72:73], v[8:9]
	v_pk_mul_f32 v[218:219], v[74:75], v[10:11]
	v_mul_f32_e32 v232, v8, v8
	v_fmac_f32_e32 v232, v9, v9
	v_fmac_f32_e32 v232, v10, v10
	v_fmac_f32_e32 v232, v11, v11
	v_cvt_pk_bf16_f32 v224, v216, v217
	v_cvt_pk_bf16_f32 v225, v218, v219
	global_store_dwordx2 v[200:201], v[224:225], off
	v_pk_fma_f32 v[2:3], v[2:3], 0.5, v[186:187] op_sel_hi:[1,0,1]
	v_pk_fma_f32 v[0:1], v[0:1], 0.5, v[184:185] op_sel_hi:[1,0,1]
	v_pk_mul_f32 v[220:221], v[84:85], v[0:1]
	v_pk_mul_f32 v[222:223], v[86:87], v[2:3]
	v_fmac_f32_e32 v232, v0, v0
	v_fmac_f32_e32 v232, v1, v1
	v_fmac_f32_e32 v232, v2, v2
	v_fmac_f32_e32 v232, v3, v3
	v_cvt_pk_bf16_f32 v226, v220, v221
	v_cvt_pk_bf16_f32 v227, v222, v223
	global_store_dwordx2 v[200:201], v[226:227], off offset:256
	v_pk_fma_f32 v[14:15], v[14:15], 0.5, v[190:191] op_sel_hi:[1,0,1]
	v_pk_fma_f32 v[12:13], v[12:13], 0.5, v[188:189] op_sel_hi:[1,0,1]
	v_pk_mul_f32 v[216:217], v[88:89], v[12:13]
	v_pk_mul_f32 v[218:219], v[90:91], v[14:15]
	v_mul_f32_e32 v233, v12, v12
	v_fmac_f32_e32 v233, v13, v13
	v_fmac_f32_e32 v233, v14, v14
	v_fmac_f32_e32 v233, v15, v15
	v_cvt_pk_bf16_f32 v224, v216, v217
	v_cvt_pk_bf16_f32 v225, v218, v219
	global_store_dwordx2 v[202:203], v[224:225], off
	v_pk_fma_f32 v[6:7], v[6:7], 0.5, v[194:195] op_sel_hi:[1,0,1]
	v_pk_fma_f32 v[4:5], v[4:5], 0.5, v[192:193] op_sel_hi:[1,0,1]
	v_pk_mul_f32 v[220:221], v[96:97], v[4:5]
	v_pk_mul_f32 v[222:223], v[98:99], v[6:7]
	v_fmac_f32_e32 v233, v4, v4
	v_fmac_f32_e32 v233, v5, v5
	v_fmac_f32_e32 v233, v6, v6
	v_fmac_f32_e32 v233, v7, v7
	v_cvt_pk_bf16_f32 v226, v220, v221
	v_cvt_pk_bf16_f32 v227, v222, v223
	global_store_dwordx2 v[202:203], v[226:227], off offset:256
	s_nop 1
	v_mov_b32_dpp v236, v232 row_ror:8 row_mask:0xf bank_mask:0xf
	v_mov_b32_dpp v237, v233 row_ror:8 row_mask:0xf bank_mask:0xf
	v_add_f32_e32 v232, v232, v236
	v_add_f32_e32 v233, v233, v237
	v_cndmask_b32_e64 v232, v233, v232, s[24:25]
	s_nop 0
	ds_bpermute_b32 v236, v234, v232
	s_waitcnt lgkmcnt(0)
	v_add_f32_e32 v232, v232, v236
	s_nop 0
	ds_bpermute_b32 v237, v235, v232
	s_waitcnt lgkmcnt(0)
	v_add_f32_e32 v232, v232, v237
	s_mov_b64 exec, s[0:1]
	global_atomic_add_f32 v[204:205], v232, off
	s_mov_b64 exec, -1
	s_and_b64 vcc, exec, s[6:7]
	s_mov_b64 s[6:7], -1
	s_cbranch_vccnz .LBB0_1371
	s_andn2_b64 vcc, exec, s[12:13]
	s_cbranch_vccnz .LBB0_1370
	s_barrier
	s_branch .LBB0_1370
